# merged 4 super-phase GEMM loops, per-phase s_setprio flips replaced by s_nop 0 (equal priority for MMA and load halves)
# speedup vs baseline: 1.0335x; 1.0162x over previous
; #define PG8_STAGE(bufoff, gbase, voff) do { _Pragma("unroll") for (int _i = 0; _i < 2; ++_i) \
;         __builtin_amdgcn_global_load_lds((const unsigned*)((const char*)(gbase) + (voff)[_i]), (LAS unsigned*)(lds + (bufoff) + ldsw + _i * 8192), 16, 0, 0); } while (0)
; #define PG8_LDA(dst, b, h) do { _Pragma("unroll") for (int m = 0; m < 4; ++m) _Pragma("unroll") for (int k = 0; k < 2; ++k) dst[m][k] = *(const LAS bf16x8*)(lds + PG8_SA(b, h) + aoff + m * 2048 + k * 1024); } while (0)
; #define PG8_LDB(dst, b, h) do { _Pragma("unroll") for (int n = 0; n < 2; ++n) _Pragma("unroll") for (int k = 0; k < 2; ++k) dst[n][k] = *(const LAS bf16x8*)(lds + PG8_SB(b, h) + boff + n * 2048 + k * 1024); } while (0)
; #define PG8_MMA(ai, bj, At, Bt) do { __builtin_amdgcn_s_setprio(1); _Pragma("unroll") for (int m = 0; m < 4; ++m) _Pragma("unroll") for (int n = 0; n < 2; ++n) _Pragma("unroll") for (int k = 0; k < 2; ++k) \
;         acc[ai][bj][m][n] = __builtin_amdgcn_mfma_f32_16x16x32_bf16(Bt[n][k], At[m][k], acc[ai][bj][m][n], 0, 0, 0); __builtin_amdgcn_s_setprio(0); } while (0)
; #define PG8_WAIT_V(n) asm volatile("s_waitcnt vmcnt(" #n ")" ::: "memory")
; #define PG8_WAIT_L(n) asm volatile("s_waitcnt lgkmcnt(" #n ")" ::: "memory")
; template <class Epi>
; __device__ __forceinline__ void gemm_phase(LAS unsigned char* lds, const Gemm g, const StaticOrder& S, const Epi& E) {
;     ...
;         for (int t = 0; t < nt; t += 2) {
;             const bool last = (t == nt - 2);
;             const char* a1 = cA + (size_t)(t + 1) * kstepA;
;             const char* a2 = last ? nA : cA + (size_t)(t + 2) * kstepA; const char* b2 = last ? nB : cB + (size_t)(t + 2) * kstepB;
;             const char* a3 = a2 + kstepA; const char* b3 = b2 + kstepB;
;             PG8_LDB(B0, 0, 0); PG8_SCHED; PG8_LDA(At, 0, 0); PG8_STAGE(PG8_SA(1, 1), a1 + hstep, voffA);
;             PG8_WAIT_L(8); PG8_BAR; PG8_WAIT_L(0); PG8_MMA(0, 0, At, B0); PG8_BAR; PG8_SCHED;
;             PG8_LDB(B1, 0, 1); PG8_STAGE(PG8_SB(0, 0), b2, voffB);
;             PG8_BAR; PG8_WAIT_L(0); PG8_MMA(0, 1, At, B1); PG8_BAR;
;             PG8_LDA(At, 0, 1); PG8_STAGE(PG8_SA(0, 0), a2, voffA);
;             PG8_BAR; PG8_WAIT_L(0); PG8_MMA(1, 0, At, B0); PG8_BAR; PG8_SCHED;
;             PG8_STAGE(PG8_SB(0, 1), b2 + hstep, voffB);
;             PG8_WAIT_V(6); PG8_BAR; PG8_MMA(1, 1, At, B1); PG8_BAR;
.LBB0_210:
	ds_read_b128 v[156:159], v152
	ds_read_b128 v[160:163], v152 offset:1024
	ds_read_b128 v[164:167], v152 offset:2048
	ds_read_b128 v[168:171], v152 offset:3072
	s_add_u32 s30, s28, 0x3fc000
	s_addc_u32 s31, s29, 0
	s_cmp_eq_u32 s60, 28
	s_cselect_b32 s36, s56, s30
	s_cselect_b32 s37, s7, s31
	s_cselect_b32 s30, s57, s58
	s_cselect_b32 s31, s5, s59
	s_add_u32 s34, s36, 0x400000
	s_addc_u32 s35, s37, 0
	v_lshl_add_u64 v[142:143], s[28:29], 0, v[134:135]
	s_add_i32 m0, s42, 0xc000
	ds_read_b128 v[172:175], v153
	ds_read_b128 v[176:179], v153 offset:1024
	ds_read_b128 v[184:187], v153 offset:2048
	ds_read_b128 v[188:191], v153 offset:3072
	ds_read_b128 v[192:195], v153 offset:4096
	ds_read_b128 v[196:199], v153 offset:5120
	ds_read_b128 v[200:203], v153 offset:6144
	ds_read_b128 v[204:207], v153 offset:7168
	global_load_lds_dwordx4 v[142:143], off
	v_lshl_add_u64 v[142:143], s[28:29], 0, v[136:137]
	s_add_i32 m0, s42, 0xe000
	s_nop 0
	global_load_lds_dwordx4 v[142:143], off
	ds_read_b128 v[208:211], v154
	ds_read_b128 v[212:215], v154 offset:1024
	ds_read_b128 v[216:219], v154 offset:2048
	ds_read_b128 v[220:223], v154 offset:3072
	s_waitcnt lgkmcnt(0)
	s_waitcnt vmcnt(8)
	s_barrier
	s_nop 0
	v_mfma_f32_16x16x32_bf16 v[124:127], v[156:159], v[172:175], v[124:127]
	v_mfma_f32_16x16x32_bf16 v[120:123], v[164:167], v[172:175], v[120:123]
	v_mfma_f32_16x16x32_bf16 v[108:111], v[156:159], v[184:187], v[108:111]
	v_mfma_f32_16x16x32_bf16 v[104:107], v[164:167], v[184:187], v[104:107]
	v_mfma_f32_16x16x32_bf16 v[92:95], v[156:159], v[192:195], v[92:95]
	v_mfma_f32_16x16x32_bf16 v[88:91], v[164:167], v[192:195], v[88:91]
	v_mfma_f32_16x16x32_bf16 v[76:79], v[156:159], v[200:203], v[76:79]
	v_mfma_f32_16x16x32_bf16 v[72:75], v[164:167], v[200:203], v[72:75]
	v_mfma_f32_16x16x32_bf16 v[124:127], v[160:163], v[176:179], v[124:127]
	v_mfma_f32_16x16x32_bf16 v[120:123], v[168:171], v[176:179], v[120:123]
	v_mfma_f32_16x16x32_bf16 v[108:111], v[160:163], v[188:191], v[108:111]
	v_mfma_f32_16x16x32_bf16 v[104:107], v[168:171], v[188:191], v[104:107]
	v_mfma_f32_16x16x32_bf16 v[92:95], v[160:163], v[196:199], v[92:95]
	v_mfma_f32_16x16x32_bf16 v[88:91], v[168:171], v[196:199], v[88:91]
	v_mfma_f32_16x16x32_bf16 v[76:79], v[160:163], v[204:207], v[76:79]
	v_mfma_f32_16x16x32_bf16 v[72:75], v[168:171], v[204:207], v[72:75]
	v_mfma_f32_16x16x32_bf16 v[116:119], v[208:211], v[172:175], v[116:119]
	v_mfma_f32_16x16x32_bf16 v[112:115], v[216:219], v[172:175], v[112:115]
	v_mfma_f32_16x16x32_bf16 v[100:103], v[208:211], v[184:187], v[100:103]
	v_mfma_f32_16x16x32_bf16 v[96:99], v[216:219], v[184:187], v[96:99]
	v_mfma_f32_16x16x32_bf16 v[84:87], v[208:211], v[192:195], v[84:87]
	v_mfma_f32_16x16x32_bf16 v[80:83], v[216:219], v[192:195], v[80:83]
	v_mfma_f32_16x16x32_bf16 v[68:71], v[208:211], v[200:203], v[68:71]
	v_mfma_f32_16x16x32_bf16 v[64:67], v[216:219], v[200:203], v[64:67]
	v_mfma_f32_16x16x32_bf16 v[116:119], v[212:215], v[176:179], v[116:119]
	v_mfma_f32_16x16x32_bf16 v[112:115], v[220:223], v[176:179], v[112:115]
	v_mfma_f32_16x16x32_bf16 v[100:103], v[212:215], v[188:191], v[100:103]
	v_mfma_f32_16x16x32_bf16 v[96:99], v[220:223], v[188:191], v[96:99]
	v_mfma_f32_16x16x32_bf16 v[84:87], v[212:215], v[196:199], v[84:87]
	v_mfma_f32_16x16x32_bf16 v[80:83], v[220:223], v[196:199], v[80:83]
	v_mfma_f32_16x16x32_bf16 v[68:71], v[212:215], v[204:207], v[68:71]
	v_mfma_f32_16x16x32_bf16 v[64:67], v[220:223], v[204:207], v[64:67]
	s_nop 0
	s_barrier
	s_add_i32 s61, s54, s39
	v_lshl_add_u64 v[142:143], s[30:31], 0, v[130:131]
	s_mov_b32 m0, s61
	s_nop 0
	global_load_lds_dwordx4 v[142:143], off
	v_lshl_add_u64 v[142:143], s[30:31], 0, v[128:129]
	s_add_i32 m0, s61, 0x2000
	s_nop 0
	global_load_lds_dwordx4 v[142:143], off
	s_mov_b32 m0, s42
	v_lshl_add_u64 v[142:143], s[36:37], 0, v[130:131]
	ds_read_b128 v[172:175], v153 offset:16384
	ds_read_b128 v[176:179], v153 offset:17408
	ds_read_b128 v[184:187], v153 offset:18432
	ds_read_b128 v[188:191], v153 offset:19456
	ds_read_b128 v[192:195], v153 offset:20480
	ds_read_b128 v[196:199], v153 offset:21504
	ds_read_b128 v[200:203], v153 offset:22528
	ds_read_b128 v[204:207], v153 offset:23552
	global_load_lds_dwordx4 v[142:143], off
	v_lshl_add_u64 v[142:143], s[36:37], 0, v[128:129]
	s_mov_b32 m0, s43
	s_nop 0
	global_load_lds_dwordx4 v[142:143], off
	s_add_u32 s94, s30, 0x4000
	s_addc_u32 s95, s31, 0
	s_add_i32 s61, s55, s39
	v_lshl_add_u64 v[142:143], s[94:95], 0, v[130:131]
	s_mov_b32 m0, s61
	s_nop 0
	global_load_lds_dwordx4 v[142:143], off
	v_lshl_add_u64 v[142:143], s[94:95], 0, v[128:129]
	s_add_i32 m0, s61, 0x2000
	s_nop 0
	global_load_lds_dwordx4 v[142:143], off
	s_waitcnt lgkmcnt(0)
	s_waitcnt vmcnt(8)
	s_barrier
; #define PG8_STAGE(bufoff, gbase, voff) do { _Pragma("unroll") for (int _i = 0; _i < 2; ++_i) \
;         __builtin_amdgcn_global_load_lds((const unsigned*)((const char*)(gbase) + (voff)[_i]), (LAS unsigned*)(lds + (bufoff) + ldsw + _i * 8192), 16, 0, 0); } while (0)
; #define PG8_LDA(dst, b, h) do { _Pragma("unroll") for (int m = 0; m < 4; ++m) _Pragma("unroll") for (int k = 0; k < 2; ++k) dst[m][k] = *(const LAS bf16x8*)(lds + PG8_SA(b, h) + aoff + m * 2048 + k * 1024); } while (0)
; #define PG8_LDB(dst, b, h) do { _Pragma("unroll") for (int n = 0; n < 2; ++n) _Pragma("unroll") for (int k = 0; k < 2; ++k) dst[n][k] = *(const LAS bf16x8*)(lds + PG8_SB(b, h) + boff + n * 2048 + k * 1024); } while (0)
; #define PG8_MMA(ai, bj, At, Bt) do { __builtin_amdgcn_s_setprio(1); _Pragma("unroll") for (int m = 0; m < 4; ++m) _Pragma("unroll") for (int n = 0; n < 2; ++n) _Pragma("unroll") for (int k = 0; k < 2; ++k) \
;         acc[ai][bj][m][n] = __builtin_amdgcn_mfma_f32_16x16x32_bf16(Bt[n][k], At[m][k], acc[ai][bj][m][n], 0, 0, 0); __builtin_amdgcn_s_setprio(0); } while (0)
; #define PG8_WAIT_V(n) asm volatile("s_waitcnt vmcnt(" #n ")" ::: "memory")
; #define PG8_WAIT_L(n) asm volatile("s_waitcnt lgkmcnt(" #n ")" ::: "memory")
; #define PG8_BAR __builtin_amdgcn_s_barrier()
; #define PG8_SCHED __builtin_amdgcn_sched_barrier(0)
; template <class Epi>
; __device__ __forceinline__ void gemm_phase(LAS unsigned char* lds, const Gemm g, const StaticOrder& S, const Epi& E) {
;     ...
;             PG8_BAR; PG8_WAIT_L(0); PG8_MMA(1, 0, At, B0); PG8_BAR; PG8_SCHED;
;             PG8_STAGE(PG8_SB(0, 1), b2 + hstep, voffB);
;             PG8_WAIT_V(6); PG8_BAR; PG8_MMA(1, 1, At, B1); PG8_BAR;
;             PG8_LDB(B0, 1, 0); PG8_SCHED; PG8_LDA(At, 1, 0); PG8_STAGE(PG8_SA(0, 1), a2 + hstep, voffA);
;             PG8_WAIT_L(8); PG8_BAR; PG8_WAIT_L(0); PG8_MMA(0, 0, At, B0); PG8_BAR; PG8_SCHED;
;             PG8_LDB(B1, 1, 1); PG8_STAGE(PG8_SB(1, 0), b3, voffB);
;             PG8_BAR; PG8_WAIT_L(0); PG8_MMA(0, 1, At, B1); PG8_BAR;
;             PG8_LDA(At, 1, 1); PG8_STAGE(PG8_SA(1, 0), a3, voffA);
;             PG8_BAR; PG8_WAIT_L(0); PG8_MMA(1, 0, At, B0); PG8_BAR; PG8_SCHED;
	s_nop 0
	v_mfma_f32_16x16x32_bf16 v[60:63], v[156:159], v[172:175], v[60:63]
	v_mfma_f32_16x16x32_bf16 v[56:59], v[164:167], v[172:175], v[56:59]
	v_mfma_f32_16x16x32_bf16 v[44:47], v[156:159], v[184:187], v[44:47]
	v_mfma_f32_16x16x32_bf16 v[40:43], v[164:167], v[184:187], v[40:43]
	v_mfma_f32_16x16x32_bf16 v[28:31], v[156:159], v[192:195], v[28:31]
	v_mfma_f32_16x16x32_bf16 v[24:27], v[164:167], v[192:195], v[24:27]
	v_mfma_f32_16x16x32_bf16 v[12:15], v[156:159], v[200:203], v[12:15]
	v_mfma_f32_16x16x32_bf16 v[8:11], v[164:167], v[200:203], v[8:11]
	v_mfma_f32_16x16x32_bf16 v[60:63], v[160:163], v[176:179], v[60:63]
	v_mfma_f32_16x16x32_bf16 v[56:59], v[168:171], v[176:179], v[56:59]
	v_mfma_f32_16x16x32_bf16 v[44:47], v[160:163], v[188:191], v[44:47]
	v_mfma_f32_16x16x32_bf16 v[40:43], v[168:171], v[188:191], v[40:43]
	v_mfma_f32_16x16x32_bf16 v[28:31], v[160:163], v[196:199], v[28:31]
	v_mfma_f32_16x16x32_bf16 v[24:27], v[168:171], v[196:199], v[24:27]
	v_mfma_f32_16x16x32_bf16 v[12:15], v[160:163], v[204:207], v[12:15]
	v_mfma_f32_16x16x32_bf16 v[8:11], v[168:171], v[204:207], v[8:11]
	v_mfma_f32_16x16x32_bf16 v[52:55], v[208:211], v[172:175], v[52:55]
	v_mfma_f32_16x16x32_bf16 v[48:51], v[216:219], v[172:175], v[48:51]
	v_mfma_f32_16x16x32_bf16 v[36:39], v[208:211], v[184:187], v[36:39]
	v_mfma_f32_16x16x32_bf16 v[32:35], v[216:219], v[184:187], v[32:35]
	v_mfma_f32_16x16x32_bf16 v[20:23], v[208:211], v[192:195], v[20:23]
	v_mfma_f32_16x16x32_bf16 v[16:19], v[216:219], v[192:195], v[16:19]
	v_mfma_f32_16x16x32_bf16 v[4:7], v[208:211], v[200:203], v[4:7]
	v_mfma_f32_16x16x32_bf16 v[0:3], v[216:219], v[200:203], v[0:3]
	v_mfma_f32_16x16x32_bf16 v[52:55], v[212:215], v[176:179], v[52:55]
	v_mfma_f32_16x16x32_bf16 v[48:51], v[220:223], v[176:179], v[48:51]
	v_mfma_f32_16x16x32_bf16 v[36:39], v[212:215], v[188:191], v[36:39]
	v_mfma_f32_16x16x32_bf16 v[32:35], v[220:223], v[188:191], v[32:35]
	v_mfma_f32_16x16x32_bf16 v[20:23], v[212:215], v[196:199], v[20:23]
	v_mfma_f32_16x16x32_bf16 v[16:19], v[220:223], v[196:199], v[16:19]
	v_mfma_f32_16x16x32_bf16 v[4:7], v[212:215], v[204:207], v[4:7]
	v_mfma_f32_16x16x32_bf16 v[0:3], v[220:223], v[204:207], v[0:3]
	s_nop 0
	s_add_i32 s61, 0, 0x18000
	v_add_u32_e32 v142, s61, v151
	s_barrier
	ds_read_b128 v[156:159], v142
	ds_read_b128 v[160:163], v142 offset:1024
	ds_read_b128 v[164:167], v142 offset:2048
	ds_read_b128 v[168:171], v142 offset:3072
	s_add_u32 s36, s36, 0x4000
	s_addc_u32 s37, s37, 0
	s_mov_b32 m0, s44
	v_lshl_add_u64 v[142:143], s[36:37], 0, v[130:131]
	ds_read_b128 v[172:175], v153 offset:32768
	ds_read_b128 v[176:179], v153 offset:33792
	ds_read_b128 v[184:187], v153 offset:34816
	ds_read_b128 v[188:191], v153 offset:35840
	ds_read_b128 v[192:195], v153 offset:36864
	ds_read_b128 v[196:199], v153 offset:37888
	ds_read_b128 v[200:203], v153 offset:38912
	ds_read_b128 v[204:207], v153 offset:39936
	global_load_lds_dwordx4 v[142:143], off
	v_lshl_add_u64 v[142:143], s[36:37], 0, v[128:129]
	s_mov_b32 m0, s45
	s_nop 0
	global_load_lds_dwordx4 v[142:143], off
	v_add_u32_e32 v253, 0x1c000, v151
	ds_read_b128 v[208:211], v253
	ds_read_b128 v[212:215], v253 offset:1024
	ds_read_b128 v[216:219], v253 offset:2048
	ds_read_b128 v[220:223], v253 offset:3072
	s_waitcnt lgkmcnt(0)
	s_waitcnt vmcnt(8)
	s_barrier
	s_nop 0
	v_mfma_f32_16x16x32_bf16 v[124:127], v[156:159], v[172:175], v[124:127]
	v_mfma_f32_16x16x32_bf16 v[120:123], v[164:167], v[172:175], v[120:123]
	v_mfma_f32_16x16x32_bf16 v[108:111], v[156:159], v[184:187], v[108:111]
	v_mfma_f32_16x16x32_bf16 v[104:107], v[164:167], v[184:187], v[104:107]
	v_mfma_f32_16x16x32_bf16 v[92:95], v[156:159], v[192:195], v[92:95]
	v_mfma_f32_16x16x32_bf16 v[88:91], v[164:167], v[192:195], v[88:91]
	v_mfma_f32_16x16x32_bf16 v[76:79], v[156:159], v[200:203], v[76:79]
	v_mfma_f32_16x16x32_bf16 v[72:75], v[164:167], v[200:203], v[72:75]
	v_mfma_f32_16x16x32_bf16 v[124:127], v[160:163], v[176:179], v[124:127]
	v_mfma_f32_16x16x32_bf16 v[120:123], v[168:171], v[176:179], v[120:123]
	v_mfma_f32_16x16x32_bf16 v[108:111], v[160:163], v[188:191], v[108:111]
	v_mfma_f32_16x16x32_bf16 v[104:107], v[168:171], v[188:191], v[104:107]
	v_mfma_f32_16x16x32_bf16 v[92:95], v[160:163], v[196:199], v[92:95]
	v_mfma_f32_16x16x32_bf16 v[88:91], v[168:171], v[196:199], v[88:91]
	v_mfma_f32_16x16x32_bf16 v[76:79], v[160:163], v[204:207], v[76:79]
	v_mfma_f32_16x16x32_bf16 v[72:75], v[168:171], v[204:207], v[72:75]
	v_mfma_f32_16x16x32_bf16 v[116:119], v[208:211], v[172:175], v[116:119]
	v_mfma_f32_16x16x32_bf16 v[112:115], v[216:219], v[172:175], v[112:115]
	v_mfma_f32_16x16x32_bf16 v[100:103], v[208:211], v[184:187], v[100:103]
	v_mfma_f32_16x16x32_bf16 v[96:99], v[216:219], v[184:187], v[96:99]
	v_mfma_f32_16x16x32_bf16 v[84:87], v[208:211], v[192:195], v[84:87]
	v_mfma_f32_16x16x32_bf16 v[80:83], v[216:219], v[192:195], v[80:83]
	v_mfma_f32_16x16x32_bf16 v[68:71], v[208:211], v[200:203], v[68:71]
	v_mfma_f32_16x16x32_bf16 v[64:67], v[216:219], v[200:203], v[64:67]
	v_mfma_f32_16x16x32_bf16 v[116:119], v[212:215], v[176:179], v[116:119]
	v_mfma_f32_16x16x32_bf16 v[112:115], v[220:223], v[176:179], v[112:115]
	v_mfma_f32_16x16x32_bf16 v[100:103], v[212:215], v[188:191], v[100:103]
	v_mfma_f32_16x16x32_bf16 v[96:99], v[220:223], v[188:191], v[96:99]
	v_mfma_f32_16x16x32_bf16 v[84:87], v[212:215], v[196:199], v[84:87]
	v_mfma_f32_16x16x32_bf16 v[80:83], v[220:223], v[196:199], v[80:83]
	v_mfma_f32_16x16x32_bf16 v[68:71], v[212:215], v[204:207], v[68:71]
	v_mfma_f32_16x16x32_bf16 v[64:67], v[220:223], v[204:207], v[64:67]
	s_nop 0
	s_barrier
; __device__ __forceinline__ unsigned pk_bf16(float lo, float hi) { unsigned r; asm("v_cvt_pk_bf16_f32 %0, %1, %2" : "=v"(r) : "v"(lo), "v"(hi)); return r; }
; __device__ __forceinline__ size_t blk_off(int row, int col, int nrows) { return ((size_t)(col >> 6) * nrows + row) * 64 + (col & 63); }
; __device__ __forceinline__ float sigmoidf_fast(float v) { return __builtin_amdgcn_rcpf(1.0f + __expf(-v)); }
; #define PG8_STAGE(bufoff, gbase, voff) do { _Pragma("unroll") for (int _i = 0; _i < 2; ++_i) \
;         __builtin_amdgcn_global_load_lds((const unsigned*)((const char*)(gbase) + (voff)[_i]), (LAS unsigned*)(lds + (bufoff) + ldsw + _i * 8192), 16, 0, 0); } while (0)
; #define PG8_LDA(dst, b, h) do { _Pragma("unroll") for (int m = 0; m < 4; ++m) _Pragma("unroll") for (int k = 0; k < 2; ++k) dst[m][k] = *(const LAS bf16x8*)(lds + PG8_SA(b, h) + aoff + m * 2048 + k * 1024); } while (0)
; #define PG8_WAIT_V(n) asm volatile("s_waitcnt vmcnt(" #n ")" ::: "memory")
;     __device__ __forceinline__ void operator()(const f32x4 (&acc)[2][2][4][2], const Unit& u, int wr, int wc, int fr, int fq) const {
;         const int row0 = u.pm * BM + wr * 64 + fr; const int col0 = u.pn * HALF + wc * 32 + 8 * fq;
; #pragma unroll
;         for (int ai = 0; ai < 2; ++ai)
; #pragma unroll
;             for (int m = 0; m < 4; ++m) { bf16_t* rowp = O + blk_off(row0 + ai * HALF + m * 16, col0, nrows);
;                 float v[8];
; #pragma unroll
;                 for (int bj = 0; bj < 2; ++bj)
; #pragma unroll
;                     for (int j = 0; j < 4; ++j) { const float g = acc[ai][bj][m][0][j], up = acc[ai][bj][m][1][j]; v[bj * 4 + j] = g * sigmoidf_fast(g) * up; }
;                 u32x4 w; w.x = pk_bf16(v[0], v[1]); w.y = pk_bf16(v[2], v[3]); w.z = pk_bf16(v[4], v[5]); w.w = pk_bf16(v[6], v[7]);
; template <class Epi>
; __device__ __forceinline__ void gemm_phase(LAS unsigned char* lds, const Gemm g, const StaticOrder& S, const Epi& E) {
;     ...
;             PG8_LDB(B1, 1, 1); PG8_STAGE(PG8_SB(1, 0), b3, voffB);
;             PG8_BAR; PG8_WAIT_L(0); PG8_MMA(0, 1, At, B1); PG8_BAR;
;             PG8_LDA(At, 1, 1); PG8_STAGE(PG8_SA(1, 0), a3, voffA);
;             PG8_BAR; PG8_WAIT_L(0); PG8_MMA(1, 0, At, B0); PG8_BAR; PG8_SCHED;
;             PG8_STAGE(PG8_SB(1, 1), b3 + hstep, voffB);
;             PG8_WAIT_V(6); PG8_BAR; PG8_MMA(1, 1, At, B1); PG8_BAR;
;         }
	s_add_i32 s63, 0, 0x1c000
	s_add_u32 s36, s30, 0x160000
	v_add_u32_e32 v142, s63, v151
	s_addc_u32 s37, s31, 0
	s_add_i32 s61, s61, s39
	s_nop 0
	v_lshl_add_u64 v[142:143], s[36:37], 0, v[130:131]
	s_mov_b32 m0, s61
	s_nop 0
	global_load_lds_dwordx4 v[142:143], off
	v_lshl_add_u64 v[142:143], s[36:37], 0, v[128:129]
	s_add_i32 m0, s61, 0x2000
	s_nop 0
	global_load_lds_dwordx4 v[142:143], off
	s_mov_b32 m0, s50
	v_lshl_add_u64 v[142:143], s[34:35], 0, v[130:131]
	ds_read_b128 v[172:175], v153 offset:49152
	ds_read_b128 v[176:179], v153 offset:50176
	ds_read_b128 v[184:187], v153 offset:51200
	ds_read_b128 v[188:191], v153 offset:52224
	ds_read_b128 v[192:195], v153 offset:53248
	ds_read_b128 v[196:199], v153 offset:54272
	ds_read_b128 v[200:203], v153 offset:55296
	ds_read_b128 v[204:207], v153 offset:56320
	global_load_lds_dwordx4 v[142:143], off
	v_lshl_add_u64 v[142:143], s[34:35], 0, v[128:129]
	s_mov_b32 m0, s51
	s_nop 0
	global_load_lds_dwordx4 v[142:143], off
	s_add_u32 s30, s30, 0x164000
	s_addc_u32 s31, s31, 0
	s_add_i32 s34, s63, s39
	v_lshl_add_u64 v[142:143], s[30:31], 0, v[130:131]
	s_mov_b32 m0, s34
	s_nop 0
	global_load_lds_dwordx4 v[142:143], off
	v_lshl_add_u64 v[142:143], s[30:31], 0, v[128:129]
	s_add_i32 m0, s34, 0x2000
	s_nop 0
	global_load_lds_dwordx4 v[142:143], off
	s_waitcnt lgkmcnt(0)
	s_waitcnt vmcnt(8)
	s_barrier
	s_nop 0
	v_mfma_f32_16x16x32_bf16 v[60:63], v[156:159], v[172:175], v[60:63]
	v_mfma_f32_16x16x32_bf16 v[56:59], v[164:167], v[172:175], v[56:59]
	v_mfma_f32_16x16x32_bf16 v[44:47], v[156:159], v[184:187], v[44:47]
	v_mfma_f32_16x16x32_bf16 v[40:43], v[164:167], v[184:187], v[40:43]
	v_mfma_f32_16x16x32_bf16 v[28:31], v[156:159], v[192:195], v[28:31]
	v_mfma_f32_16x16x32_bf16 v[24:27], v[164:167], v[192:195], v[24:27]
	v_mfma_f32_16x16x32_bf16 v[12:15], v[156:159], v[200:203], v[12:15]
	v_mfma_f32_16x16x32_bf16 v[8:11], v[164:167], v[200:203], v[8:11]
	v_mfma_f32_16x16x32_bf16 v[60:63], v[160:163], v[176:179], v[60:63]
	v_mfma_f32_16x16x32_bf16 v[56:59], v[168:171], v[176:179], v[56:59]
	v_mfma_f32_16x16x32_bf16 v[44:47], v[160:163], v[188:191], v[44:47]
	v_mfma_f32_16x16x32_bf16 v[40:43], v[168:171], v[188:191], v[40:43]
	v_mfma_f32_16x16x32_bf16 v[28:31], v[160:163], v[196:199], v[28:31]
	v_mfma_f32_16x16x32_bf16 v[24:27], v[168:171], v[196:199], v[24:27]
	v_mfma_f32_16x16x32_bf16 v[12:15], v[160:163], v[204:207], v[12:15]
	v_mfma_f32_16x16x32_bf16 v[8:11], v[168:171], v[204:207], v[8:11]
	v_mfma_f32_16x16x32_bf16 v[52:55], v[208:211], v[172:175], v[52:55]
	v_mfma_f32_16x16x32_bf16 v[48:51], v[216:219], v[172:175], v[48:51]
	v_mfma_f32_16x16x32_bf16 v[36:39], v[208:211], v[184:187], v[36:39]
	v_mfma_f32_16x16x32_bf16 v[32:35], v[216:219], v[184:187], v[32:35]
	v_mfma_f32_16x16x32_bf16 v[20:23], v[208:211], v[192:195], v[20:23]
	v_mfma_f32_16x16x32_bf16 v[16:19], v[216:219], v[192:195], v[16:19]
	v_mfma_f32_16x16x32_bf16 v[4:7], v[208:211], v[200:203], v[4:7]
	v_mfma_f32_16x16x32_bf16 v[0:3], v[216:219], v[200:203], v[0:3]
	v_mfma_f32_16x16x32_bf16 v[52:55], v[212:215], v[176:179], v[52:55]
	v_mfma_f32_16x16x32_bf16 v[48:51], v[220:223], v[176:179], v[48:51]
	v_mfma_f32_16x16x32_bf16 v[36:39], v[212:215], v[188:191], v[36:39]
	v_mfma_f32_16x16x32_bf16 v[32:35], v[220:223], v[188:191], v[32:35]
	v_mfma_f32_16x16x32_bf16 v[20:23], v[212:215], v[196:199], v[20:23]
	v_mfma_f32_16x16x32_bf16 v[16:19], v[220:223], v[196:199], v[16:19]
	v_mfma_f32_16x16x32_bf16 v[4:7], v[212:215], v[204:207], v[4:7]
	v_mfma_f32_16x16x32_bf16 v[0:3], v[220:223], v[204:207], v[0:3]
	s_nop 0
	s_add_i32 s60, s60, 2
	s_add_u32 s58, s58, 0x2c0000
	s_addc_u32 s59, s59, 0
	s_add_u32 s28, s28, 0x800000
	s_addc_u32 s29, s29, 0
	s_cmp_gt_u32 s60, 29
	s_barrier
	s_cbranch_scc0 .LBB0_210
	s_lshl_b32 s5, s13, 7
	v_mul_f32_e32 v155, 0xbfb8aa3b, v124
	s_or_b32 s5, s5, s49
	v_exp_f32_e32 v155, v155
	v_mul_f32_e32 v156, 0xbfb8aa3b, v125
	v_lshl_add_u32 v142, s12, 8, v150
	s_ashr_i32 s12, s5, 6
	v_exp_f32_e32 v158, v156
	s_ashr_i32 s13, s12, 31
	s_lshl_b64 s[12:13], s[12:13], 15
	v_ashrrev_i32_e32 v143, 31, v142
	v_lshl_add_u64 v[156:157], s[12:13], 0, v[142:143]
	v_add_f32_e32 v143, 1.0, v155
	v_rcp_f32_e32 v143, v143
	v_add_f32_e32 v155, 1.0, v158
	v_rcp_f32_e32 v155, v155
	v_lshlrev_b64 v[156:157], 7, v[156:157]
	v_mul_f32_e32 v124, v124, v143
	v_mul_f32_e32 v120, v120, v124
	v_mul_f32_e32 v124, v125, v155
	v_mul_f32_e32 v125, 0xbfb8aa3b, v126
	v_exp_f32_e32 v125, v125
	v_mul_f32_e32 v143, 0xbfb8aa3b, v127
	v_exp_f32_e32 v143, v143
	v_mul_f32_e32 v121, v121, v124
	v_add_f32_e32 v124, 1.0, v125
	v_rcp_f32_e32 v124, v124
	v_add_f32_e32 v125, 1.0, v143
	v_mul_f32_e32 v143, 0xbfb8aa3b, v116
	v_rcp_f32_e32 v125, v125
	v_exp_f32_e32 v143, v143
	v_mul_f32_e32 v124, v126, v124
	v_mul_f32_e32 v122, v122, v124
	v_mul_f32_e32 v124, v127, v125
	v_add_f32_e32 v125, 1.0, v143
	v_rcp_f32_e32 v125, v125
	v_mul_f32_e32 v126, 0xbfb8aa3b, v117
	v_exp_f32_e32 v126, v126
	v_mul_f32_e32 v123, v123, v124
	v_mul_f32_e32 v116, v116, v125
	v_mul_f32_e32 v124, v112, v116
	v_mul_f32_e32 v116, 0xbfb8aa3b, v118
	v_add_f32_e32 v112, 1.0, v126
	v_exp_f32_e32 v116, v116
	v_mul_f32_e32 v125, 0xbfb8aa3b, v119
	v_rcp_f32_e32 v112, v112
	v_exp_f32_e32 v125, v125
	v_add_f32_e32 v116, 1.0, v116
	v_rcp_f32_e32 v116, v116
	v_mul_f32_e32 v112, v117, v112
	v_add_f32_e32 v117, 1.0, v125
	v_rcp_f32_e32 v117, v117
	v_mul_f32_e32 v125, v113, v112
	v_mul_f32_e32 v112, v118, v116
	v_mul_f32_e32 v118, v114, v112
	v_mul_f32_e32 v112, v119, v117
	v_mul_f32_e32 v115, v115, v112
	v_lshl_add_u64 v[116:117], v[132:133], 0, v[156:157]
	v_cvt_pk_bf16_f32 v114, v124, v125
	v_cvt_pk_bf16_f32 v112, v120, v121
; __device__ __forceinline__ unsigned pk_bf16(float lo, float hi) { unsigned r; asm("v_cvt_pk_bf16_f32 %0, %1, %2" : "=v"(r) : "v"(lo), "v"(hi)); return r; }
; __device__ __forceinline__ size_t blk_off(int row, int col, int nrows) { return ((size_t)(col >> 6) * nrows + row) * 64 + (col & 63); }
; __device__ __forceinline__ float sigmoidf_fast(float v) { return __builtin_amdgcn_rcpf(1.0f + __expf(-v)); }
;     __device__ __forceinline__ void operator()(const f32x4 (&acc)[2][2][4][2], const Unit& u, int wr, int wc, int fr, int fq) const {
;         const int row0 = u.pm * BM + wr * 64 + fr; const int col0 = u.pn * HALF + wc * 32 + 8 * fq;
; #pragma unroll
;         for (int ai = 0; ai < 2; ++ai)
; #pragma unroll
;             for (int m = 0; m < 4; ++m) { bf16_t* rowp = O + blk_off(row0 + ai * HALF + m * 16, col0, nrows);
;                 float v[8];
; #pragma unroll
;                 for (int bj = 0; bj < 2; ++bj)
; #pragma unroll
;                     for (int j = 0; j < 4; ++j) { const float g = acc[ai][bj][m][0][j], up = acc[ai][bj][m][1][j]; v[bj * 4 + j] = g * sigmoidf_fast(g) * up; }
;                 u32x4 w; w.x = pk_bf16(v[0], v[1]); w.y = pk_bf16(v[2], v[3]); w.z = pk_bf16(v[4], v[5]); w.w = pk_bf16(v[6], v[7]);
;                 *(u32x4*)rowp = w; }
	v_cvt_pk_bf16_f32 v113, v122, v123
	v_cvt_pk_bf16_f32 v115, v118, v115
	global_store_dwordx4 v[116:117], v[112:115], off
	s_and_b64 vcc, exec, s[0:1]
	s_mov_b64 s[28:29], s[10:11]
	v_mul_f32_e32 v114, 0xbfb8aa3b, v108
	v_exp_f32_e32 v114, v114
	v_mul_f32_e32 v115, 0xbfb8aa3b, v109
	v_exp_f32_e32 v115, v115
	v_or_b32_e32 v112, 16, v142
	v_add_f32_e32 v114, 1.0, v114
	v_rcp_f32_e32 v114, v114
	v_add_f32_e32 v115, 1.0, v115
	v_rcp_f32_e32 v115, v115
	v_ashrrev_i32_e32 v113, 31, v112
	v_mul_f32_e32 v108, v108, v114
	v_mul_f32_e32 v104, v104, v108
	v_mul_f32_e32 v108, v109, v115
	v_mul_f32_e32 v109, 0xbfb8aa3b, v110
	v_exp_f32_e32 v109, v109
	v_mul_f32_e32 v114, 0xbfb8aa3b, v111
	v_exp_f32_e32 v114, v114
	v_mul_f32_e32 v105, v105, v108
	v_add_f32_e32 v108, 1.0, v109
	v_rcp_f32_e32 v108, v108
	v_add_f32_e32 v109, 1.0, v114
	v_mul_f32_e32 v114, 0xbfb8aa3b, v100
	v_rcp_f32_e32 v109, v109
	v_exp_f32_e32 v114, v114
	v_mul_f32_e32 v108, v110, v108
	v_mul_f32_e32 v106, v106, v108
	v_mul_f32_e32 v108, v111, v109
	v_add_f32_e32 v109, 1.0, v114
	v_rcp_f32_e32 v109, v109
	v_mul_f32_e32 v110, 0xbfb8aa3b, v101
	v_exp_f32_e32 v110, v110
	v_mul_f32_e32 v107, v107, v108
	v_mul_f32_e32 v100, v100, v109
	v_mul_f32_e32 v108, v96, v100
	v_mul_f32_e32 v100, 0xbfb8aa3b, v102
	v_add_f32_e32 v96, 1.0, v110
	v_exp_f32_e32 v100, v100
	v_mul_f32_e32 v109, 0xbfb8aa3b, v103
	v_rcp_f32_e32 v96, v96
	v_exp_f32_e32 v109, v109
	v_add_f32_e32 v100, 1.0, v100
	v_rcp_f32_e32 v100, v100
	v_mul_f32_e32 v96, v101, v96
	v_add_f32_e32 v101, 1.0, v109
	v_rcp_f32_e32 v101, v101
	v_lshl_add_u64 v[112:113], s[12:13], 0, v[112:113]
	v_mul_f32_e32 v109, v97, v96
	v_mul_f32_e32 v96, v102, v100
	v_lshlrev_b64 v[112:113], 7, v[112:113]
	v_mul_f32_e32 v102, v98, v96
	v_mul_f32_e32 v96, v103, v101
	v_mul_f32_e32 v99, v99, v96
	v_lshl_add_u64 v[100:101], v[132:133], 0, v[112:113]
	v_cvt_pk_bf16_f32 v98, v108, v109
	v_cvt_pk_bf16_f32 v96, v104, v105
	v_cvt_pk_bf16_f32 v97, v106, v107
	v_cvt_pk_bf16_f32 v99, v102, v99
	global_store_dwordx4 v[100:101], v[96:99], off
	s_mov_b64 s[30:31], s[8:9]
	s_nop 0
	v_mul_f32_e32 v98, 0xbfb8aa3b, v92
	v_exp_f32_e32 v98, v98
	v_mul_f32_e32 v99, 0xbfb8aa3b, v93
	v_exp_f32_e32 v99, v99
	v_or_b32_e32 v96, 32, v142
	v_add_f32_e32 v98, 1.0, v98
	v_rcp_f32_e32 v98, v98
	v_add_f32_e32 v99, 1.0, v99
	v_rcp_f32_e32 v99, v99
	v_ashrrev_i32_e32 v97, 31, v96
	v_mul_f32_e32 v92, v92, v98
	v_mul_f32_e32 v88, v88, v92
	v_mul_f32_e32 v92, v93, v99
	v_mul_f32_e32 v93, 0xbfb8aa3b, v94
	v_exp_f32_e32 v93, v93
	v_mul_f32_e32 v98, 0xbfb8aa3b, v95
	v_exp_f32_e32 v98, v98
	v_mul_f32_e32 v89, v89, v92
	v_add_f32_e32 v92, 1.0, v93
	v_rcp_f32_e32 v92, v92
	v_add_f32_e32 v93, 1.0, v98
	v_mul_f32_e32 v98, 0xbfb8aa3b, v84
	v_rcp_f32_e32 v93, v93
	v_exp_f32_e32 v98, v98
	v_mul_f32_e32 v92, v94, v92
	v_mul_f32_e32 v90, v90, v92
	v_mul_f32_e32 v92, v95, v93
	v_add_f32_e32 v93, 1.0, v98
	v_rcp_f32_e32 v93, v93
	v_mul_f32_e32 v94, 0xbfb8aa3b, v85
	v_exp_f32_e32 v94, v94
	v_mul_f32_e32 v91, v91, v92
	v_mul_f32_e32 v84, v84, v93
	v_mul_f32_e32 v92, v80, v84
	v_mul_f32_e32 v84, 0xbfb8aa3b, v86
	v_add_f32_e32 v80, 1.0, v94
	v_exp_f32_e32 v84, v84
	v_mul_f32_e32 v93, 0xbfb8aa3b, v87
	v_rcp_f32_e32 v80, v80
	v_exp_f32_e32 v93, v93
	v_add_f32_e32 v84, 1.0, v84
	v_rcp_f32_e32 v84, v84
	v_mul_f32_e32 v80, v85, v80
	v_add_f32_e32 v85, 1.0, v93
	v_rcp_f32_e32 v85, v85
	v_lshl_add_u64 v[96:97], s[12:13], 0, v[96:97]
	v_mul_f32_e32 v93, v81, v80
	v_mul_f32_e32 v80, v86, v84
	v_lshlrev_b64 v[96:97], 7, v[96:97]
	v_mul_f32_e32 v86, v82, v80
	v_mul_f32_e32 v80, v87, v85
	v_mul_f32_e32 v83, v83, v80
	v_lshl_add_u64 v[84:85], v[132:133], 0, v[96:97]
	v_cvt_pk_bf16_f32 v82, v92, v93
	v_cvt_pk_bf16_f32 v80, v88, v89
	v_cvt_pk_bf16_f32 v81, v90, v91
	v_cvt_pk_bf16_f32 v83, v86, v83
	global_store_dwordx4 v[84:85], v[80:83], off
	s_nop 1
	v_mul_f32_e32 v82, 0xbfb8aa3b, v76
	v_exp_f32_e32 v82, v82
	v_mul_f32_e32 v83, 0xbfb8aa3b, v77
	v_exp_f32_e32 v83, v83
	v_or_b32_e32 v80, 48, v142
	v_add_f32_e32 v82, 1.0, v82
	v_rcp_f32_e32 v82, v82
	v_add_f32_e32 v83, 1.0, v83
	v_rcp_f32_e32 v83, v83
	v_ashrrev_i32_e32 v81, 31, v80
	v_mul_f32_e32 v76, v76, v82
	v_mul_f32_e32 v72, v72, v76
	v_mul_f32_e32 v76, v77, v83
	v_mul_f32_e32 v77, 0xbfb8aa3b, v78
	v_exp_f32_e32 v77, v77
	v_mul_f32_e32 v82, 0xbfb8aa3b, v79
	v_exp_f32_e32 v82, v82
	v_mul_f32_e32 v73, v73, v76
	v_add_f32_e32 v76, 1.0, v77
	v_rcp_f32_e32 v76, v76
	v_add_f32_e32 v77, 1.0, v82
	v_mul_f32_e32 v82, 0xbfb8aa3b, v68
	v_rcp_f32_e32 v77, v77
	v_exp_f32_e32 v82, v82
	v_mul_f32_e32 v76, v78, v76
	v_mul_f32_e32 v74, v74, v76
	v_mul_f32_e32 v76, v79, v77
	v_add_f32_e32 v77, 1.0, v82
	v_rcp_f32_e32 v77, v77
	v_mul_f32_e32 v78, 0xbfb8aa3b, v69
	v_exp_f32_e32 v78, v78
	v_mul_f32_e32 v75, v75, v76
	v_mul_f32_e32 v68, v68, v77
	v_mul_f32_e32 v76, v64, v68
	v_mul_f32_e32 v68, 0xbfb8aa3b, v70
	v_add_f32_e32 v64, 1.0, v78
	v_exp_f32_e32 v68, v68
	v_mul_f32_e32 v77, 0xbfb8aa3b, v71
	v_rcp_f32_e32 v64, v64
	v_exp_f32_e32 v77, v77
	v_add_f32_e32 v68, 1.0, v68
	v_rcp_f32_e32 v68, v68
	v_mul_f32_e32 v64, v69, v64
	v_add_f32_e32 v69, 1.0, v77
	v_rcp_f32_e32 v69, v69
	v_lshl_add_u64 v[80:81], s[12:13], 0, v[80:81]
	v_mul_f32_e32 v77, v65, v64
	v_mul_f32_e32 v64, v70, v68
	v_lshlrev_b64 v[80:81], 7, v[80:81]
	v_mul_f32_e32 v70, v66, v64
	v_mul_f32_e32 v64, v71, v69
	v_mul_f32_e32 v67, v67, v64
	v_lshl_add_u64 v[68:69], v[132:133], 0, v[80:81]
	v_cvt_pk_bf16_f32 v66, v76, v77
	v_cvt_pk_bf16_f32 v64, v72, v73
	v_cvt_pk_bf16_f32 v65, v74, v75
	v_cvt_pk_bf16_f32 v67, v70, v67
	global_store_dwordx4 v[68:69], v[64:67], off
	s_nop 1
	v_mul_f32_e32 v66, 0xbfb8aa3b, v60
	v_exp_f32_e32 v66, v66
; __device__ __forceinline__ unsigned pk_bf16(float lo, float hi) { unsigned r; asm("v_cvt_pk_bf16_f32 %0, %1, %2" : "=v"(r) : "v"(lo), "v"(hi)); return r; }
; __device__ __forceinline__ size_t blk_off(int row, int col, int nrows) { return ((size_t)(col >> 6) * nrows + row) * 64 + (col & 63); }
; __device__ __forceinline__ float sigmoidf_fast(float v) { return __builtin_amdgcn_rcpf(1.0f + __expf(-v)); }
;     __device__ __forceinline__ void operator()(const f32x4 (&acc)[2][2][4][2], const Unit& u, int wr, int wc, int fr, int fq) const {
;         const int row0 = u.pm * BM + wr * 64 + fr; const int col0 = u.pn * HALF + wc * 32 + 8 * fq;
; #pragma unroll
;         for (int ai = 0; ai < 2; ++ai)
; #pragma unroll
;             for (int m = 0; m < 4; ++m) { bf16_t* rowp = O + blk_off(row0 + ai * HALF + m * 16, col0, nrows);
;                 float v[8];
; #pragma unroll
;                 for (int bj = 0; bj < 2; ++bj)
; #pragma unroll
;                     for (int j = 0; j < 4; ++j) { const float g = acc[ai][bj][m][0][j], up = acc[ai][bj][m][1][j]; v[bj * 4 + j] = g * sigmoidf_fast(g) * up; }
;                 u32x4 w; w.x = pk_bf16(v[0], v[1]); w.y = pk_bf16(v[2], v[3]); w.z = pk_bf16(v[4], v[5]); w.w = pk_bf16(v[6], v[7]);
;                 *(u32x4*)rowp = w; }
;     }
	v_mul_f32_e32 v67, 0xbfb8aa3b, v61
	v_exp_f32_e32 v67, v67
	v_add_u32_e32 v64, 0x80, v142
	v_add_f32_e32 v66, 1.0, v66
	v_rcp_f32_e32 v66, v66
	v_add_f32_e32 v67, 1.0, v67
	v_rcp_f32_e32 v67, v67
	v_ashrrev_i32_e32 v65, 31, v64
	v_mul_f32_e32 v60, v60, v66
	v_mul_f32_e32 v56, v56, v60
	v_mul_f32_e32 v60, v61, v67
	v_mul_f32_e32 v61, 0xbfb8aa3b, v62
	v_exp_f32_e32 v61, v61
	v_mul_f32_e32 v66, 0xbfb8aa3b, v63
	v_exp_f32_e32 v66, v66
	v_mul_f32_e32 v57, v57, v60
	v_add_f32_e32 v60, 1.0, v61
	v_rcp_f32_e32 v60, v60
	v_add_f32_e32 v61, 1.0, v66
	v_mul_f32_e32 v66, 0xbfb8aa3b, v52
	v_rcp_f32_e32 v61, v61
	v_exp_f32_e32 v66, v66
	v_mul_f32_e32 v60, v62, v60
	v_mul_f32_e32 v58, v58, v60
	v_mul_f32_e32 v60, v63, v61
	v_add_f32_e32 v61, 1.0, v66
	v_rcp_f32_e32 v61, v61
	v_mul_f32_e32 v62, 0xbfb8aa3b, v53
	v_exp_f32_e32 v62, v62
	v_mul_f32_e32 v59, v59, v60
	v_mul_f32_e32 v52, v52, v61
	v_mul_f32_e32 v60, v48, v52
	v_mul_f32_e32 v52, 0xbfb8aa3b, v54
	v_add_f32_e32 v48, 1.0, v62
	v_exp_f32_e32 v52, v52
	v_mul_f32_e32 v61, 0xbfb8aa3b, v55
	v_rcp_f32_e32 v48, v48
	v_exp_f32_e32 v61, v61
	v_add_f32_e32 v52, 1.0, v52
	v_rcp_f32_e32 v52, v52
	v_mul_f32_e32 v48, v53, v48
	v_add_f32_e32 v53, 1.0, v61
	v_rcp_f32_e32 v53, v53
	v_lshl_add_u64 v[64:65], s[12:13], 0, v[64:65]
	v_mul_f32_e32 v61, v49, v48
	v_mul_f32_e32 v48, v54, v52
	v_lshlrev_b64 v[64:65], 7, v[64:65]
	v_mul_f32_e32 v54, v50, v48
	v_mul_f32_e32 v48, v55, v53
	v_mul_f32_e32 v51, v51, v48
	v_lshl_add_u64 v[52:53], v[132:133], 0, v[64:65]
	v_cvt_pk_bf16_f32 v50, v60, v61
	v_cvt_pk_bf16_f32 v48, v56, v57
	v_cvt_pk_bf16_f32 v49, v58, v59
	v_cvt_pk_bf16_f32 v51, v54, v51
	global_store_dwordx4 v[52:53], v[48:51], off
	s_nop 1
	v_mul_f32_e32 v50, 0xbfb8aa3b, v44
	v_exp_f32_e32 v50, v50
	v_mul_f32_e32 v51, 0xbfb8aa3b, v45
	v_exp_f32_e32 v51, v51
	v_add_u32_e32 v48, 0x90, v142
	v_add_f32_e32 v50, 1.0, v50
	v_rcp_f32_e32 v50, v50
	v_add_f32_e32 v51, 1.0, v51
	v_rcp_f32_e32 v51, v51
	v_ashrrev_i32_e32 v49, 31, v48
	v_mul_f32_e32 v44, v44, v50
	v_mul_f32_e32 v40, v40, v44
	v_mul_f32_e32 v44, v45, v51
	v_mul_f32_e32 v45, 0xbfb8aa3b, v46
	v_exp_f32_e32 v45, v45
	v_mul_f32_e32 v50, 0xbfb8aa3b, v47
	v_exp_f32_e32 v50, v50
	v_mul_f32_e32 v41, v41, v44
	v_add_f32_e32 v44, 1.0, v45
	v_rcp_f32_e32 v44, v44
	v_add_f32_e32 v45, 1.0, v50
	v_mul_f32_e32 v50, 0xbfb8aa3b, v36
	v_rcp_f32_e32 v45, v45
	v_exp_f32_e32 v50, v50
	v_mul_f32_e32 v44, v46, v44
	v_mul_f32_e32 v42, v42, v44
	v_mul_f32_e32 v44, v47, v45
	v_add_f32_e32 v45, 1.0, v50
	v_rcp_f32_e32 v45, v45
	v_mul_f32_e32 v46, 0xbfb8aa3b, v37
	v_exp_f32_e32 v46, v46
	v_mul_f32_e32 v43, v43, v44
	v_mul_f32_e32 v36, v36, v45
	v_mul_f32_e32 v44, v32, v36
	v_mul_f32_e32 v36, 0xbfb8aa3b, v38
	v_add_f32_e32 v32, 1.0, v46
	v_exp_f32_e32 v36, v36
	v_mul_f32_e32 v45, 0xbfb8aa3b, v39
	v_rcp_f32_e32 v32, v32
	v_exp_f32_e32 v45, v45
	v_add_f32_e32 v36, 1.0, v36
	v_rcp_f32_e32 v36, v36
	v_mul_f32_e32 v32, v37, v32
	v_add_f32_e32 v37, 1.0, v45
	v_rcp_f32_e32 v37, v37
	v_lshl_add_u64 v[48:49], s[12:13], 0, v[48:49]
	v_mul_f32_e32 v45, v33, v32
	v_mul_f32_e32 v32, v38, v36
	v_lshlrev_b64 v[48:49], 7, v[48:49]
	v_mul_f32_e32 v38, v34, v32
	v_mul_f32_e32 v32, v39, v37
	v_mul_f32_e32 v35, v35, v32
	v_lshl_add_u64 v[36:37], v[132:133], 0, v[48:49]
	v_cvt_pk_bf16_f32 v34, v44, v45
	v_cvt_pk_bf16_f32 v32, v40, v41
	v_cvt_pk_bf16_f32 v33, v42, v43
	v_cvt_pk_bf16_f32 v35, v38, v35
	global_store_dwordx4 v[36:37], v[32:35], off
	s_nop 1
	v_mul_f32_e32 v34, 0xbfb8aa3b, v28
	v_exp_f32_e32 v34, v34
	v_mul_f32_e32 v35, 0xbfb8aa3b, v29
	v_exp_f32_e32 v35, v35
	v_add_u32_e32 v32, 0xa0, v142
	v_add_f32_e32 v34, 1.0, v34
	v_rcp_f32_e32 v34, v34
	v_add_f32_e32 v35, 1.0, v35
	v_rcp_f32_e32 v35, v35
	v_ashrrev_i32_e32 v33, 31, v32
	v_mul_f32_e32 v28, v28, v34
	v_mul_f32_e32 v24, v24, v28
	v_mul_f32_e32 v28, v29, v35
	v_mul_f32_e32 v29, 0xbfb8aa3b, v30
	v_exp_f32_e32 v29, v29
	v_mul_f32_e32 v34, 0xbfb8aa3b, v31
	v_exp_f32_e32 v34, v34
	v_mul_f32_e32 v25, v25, v28
	v_add_f32_e32 v28, 1.0, v29
	v_rcp_f32_e32 v28, v28
	v_add_f32_e32 v29, 1.0, v34
	v_mul_f32_e32 v34, 0xbfb8aa3b, v20
	v_rcp_f32_e32 v29, v29
	v_exp_f32_e32 v34, v34
	v_mul_f32_e32 v28, v30, v28
	v_mul_f32_e32 v26, v26, v28
	v_mul_f32_e32 v28, v31, v29
	v_add_f32_e32 v29, 1.0, v34
	v_rcp_f32_e32 v29, v29
	v_mul_f32_e32 v30, 0xbfb8aa3b, v21
	v_exp_f32_e32 v30, v30
	v_mul_f32_e32 v27, v27, v28
	v_mul_f32_e32 v20, v20, v29
	v_mul_f32_e32 v28, v16, v20
	v_mul_f32_e32 v20, 0xbfb8aa3b, v22
	v_add_f32_e32 v16, 1.0, v30
	v_exp_f32_e32 v20, v20
	v_mul_f32_e32 v29, 0xbfb8aa3b, v23
	v_rcp_f32_e32 v16, v16
	v_exp_f32_e32 v29, v29
	v_add_f32_e32 v20, 1.0, v20
	v_rcp_f32_e32 v20, v20
	v_mul_f32_e32 v16, v21, v16
	v_add_f32_e32 v21, 1.0, v29
	v_rcp_f32_e32 v21, v21
	v_lshl_add_u64 v[32:33], s[12:13], 0, v[32:33]
	v_mul_f32_e32 v29, v17, v16
	v_mul_f32_e32 v16, v22, v20
	v_lshlrev_b64 v[32:33], 7, v[32:33]
	v_mul_f32_e32 v22, v18, v16
	v_mul_f32_e32 v16, v23, v21
	v_mul_f32_e32 v19, v19, v16
	v_lshl_add_u64 v[20:21], v[132:133], 0, v[32:33]
	v_cvt_pk_bf16_f32 v18, v28, v29
	v_cvt_pk_bf16_f32 v16, v24, v25
	v_cvt_pk_bf16_f32 v17, v26, v27
	v_cvt_pk_bf16_f32 v19, v22, v19
	global_store_dwordx4 v[20:21], v[16:19], off
	s_nop 1
	v_mul_f32_e32 v18, 0xbfb8aa3b, v12
	v_exp_f32_e32 v18, v18
	v_mul_f32_e32 v19, 0xbfb8aa3b, v13
	v_exp_f32_e32 v19, v19
	v_add_u32_e32 v16, 0xb0, v142
	v_add_f32_e32 v18, 1.0, v18
	v_rcp_f32_e32 v18, v18
	v_add_f32_e32 v19, 1.0, v19
	v_rcp_f32_e32 v19, v19
	v_ashrrev_i32_e32 v17, 31, v16
	v_mul_f32_e32 v12, v12, v18
	v_mul_f32_e32 v8, v8, v12
	v_mul_f32_e32 v12, v13, v19
	v_mul_f32_e32 v13, 0xbfb8aa3b, v14
	v_exp_f32_e32 v13, v13
	v_mul_f32_e32 v18, 0xbfb8aa3b, v15
	v_exp_f32_e32 v18, v18
	v_mul_f32_e32 v9, v9, v12
	v_add_f32_e32 v12, 1.0, v13
	v_rcp_f32_e32 v12, v12
	v_add_f32_e32 v13, 1.0, v18
	v_mul_f32_e32 v18, 0xbfb8aa3b, v4
	v_rcp_f32_e32 v13, v13
	v_exp_f32_e32 v18, v18
	v_mul_f32_e32 v12, v14, v12
	v_mul_f32_e32 v10, v10, v12
	v_mul_f32_e32 v12, v15, v13
	v_add_f32_e32 v13, 1.0, v18
	v_rcp_f32_e32 v13, v13
	v_mul_f32_e32 v14, 0xbfb8aa3b, v5
	v_exp_f32_e32 v14, v14
	v_mul_f32_e32 v11, v11, v12
	v_mul_f32_e32 v4, v4, v13
	v_mul_f32_e32 v12, v0, v4
	v_mul_f32_e32 v4, 0xbfb8aa3b, v6
	v_add_f32_e32 v0, 1.0, v14
	v_exp_f32_e32 v4, v4
	v_mul_f32_e32 v13, 0xbfb8aa3b, v7
	v_rcp_f32_e32 v0, v0
	v_exp_f32_e32 v13, v13
	v_add_f32_e32 v4, 1.0, v4
	v_rcp_f32_e32 v4, v4
	v_mul_f32_e32 v0, v5, v0
	v_add_f32_e32 v5, 1.0, v13
	v_rcp_f32_e32 v5, v5
	v_lshl_add_u64 v[16:17], s[12:13], 0, v[16:17]
	v_mul_f32_e32 v13, v1, v0
	v_mul_f32_e32 v0, v6, v4
	v_lshlrev_b64 v[16:17], 7, v[16:17]
	v_mul_f32_e32 v6, v2, v0
	v_mul_f32_e32 v0, v7, v5
	v_mul_f32_e32 v3, v3, v0
	v_lshl_add_u64 v[4:5], v[132:133], 0, v[16:17]
	s_mov_b32 s13, s4
	s_mov_b32 s12, s6
	v_cvt_pk_bf16_f32 v0, v8, v9
	v_cvt_pk_bf16_f32 v1, v10, v11
	v_cvt_pk_bf16_f32 v2, v12, v13
	v_cvt_pk_bf16_f32 v3, v6, v3
	global_store_dwordx4 v[4:5], v[0:3], off
	s_cbranch_vccz .LBB0_207
	s_waitcnt vmcnt(0)
	s_cmpk_gt_u32 s38, 0xff
	s_cbranch_scc1 .LBB0_214
	s_barrier

; #define PG8_STAGE(bufoff, gbase, voff) do { _Pragma("unroll") for (int _i = 0; _i < 2; ++_i) \
;         __builtin_amdgcn_global_load_lds((const unsigned*)((const char*)(gbase) + (voff)[_i]), (LAS unsigned*)(lds + (bufoff) + ldsw + _i * 8192), 16, 0, 0); } while (0)
; #define PG8_LDA(dst, b, h) do { _Pragma("unroll") for (int m = 0; m < 4; ++m) _Pragma("unroll") for (int k = 0; k < 2; ++k) dst[m][k] = *(const LAS bf16x8*)(lds + PG8_SA(b, h) + aoff + m * 2048 + k * 1024); } while (0)
; #define PG8_LDB(dst, b, h) do { _Pragma("unroll") for (int n = 0; n < 2; ++n) _Pragma("unroll") for (int k = 0; k < 2; ++k) dst[n][k] = *(const LAS bf16x8*)(lds + PG8_SB(b, h) + boff + n * 2048 + k * 1024); } while (0)
; #define PG8_MMA(ai, bj, At, Bt) do { __builtin_amdgcn_s_setprio(1); _Pragma("unroll") for (int m = 0; m < 4; ++m) _Pragma("unroll") for (int n = 0; n < 2; ++n) _Pragma("unroll") for (int k = 0; k < 2; ++k) \
;         acc[ai][bj][m][n] = __builtin_amdgcn_mfma_f32_16x16x32_bf16(Bt[n][k], At[m][k], acc[ai][bj][m][n], 0, 0, 0); __builtin_amdgcn_s_setprio(0); } while (0)
; #define PG8_WAIT_V(n) asm volatile("s_waitcnt vmcnt(" #n ")" ::: "memory")
; #define PG8_WAIT_L(n) asm volatile("s_waitcnt lgkmcnt(" #n ")" ::: "memory")
; template <class Epi>
; __device__ __forceinline__ void gemm_phase(LAS unsigned char* lds, const Gemm g, const StaticOrder& S, const Epi& E) {
;     ...
;         for (int t = 0; t < nt; t += 2) {
;             const bool last = (t == nt - 2);
;             const char* a1 = cA + (size_t)(t + 1) * kstepA;
;             const char* a2 = last ? nA : cA + (size_t)(t + 2) * kstepA; const char* b2 = last ? nB : cB + (size_t)(t + 2) * kstepB;
;             const char* a3 = a2 + kstepA; const char* b3 = b2 + kstepB;
;             PG8_LDB(B0, 0, 0); PG8_SCHED; PG8_LDA(At, 0, 0); PG8_STAGE(PG8_SA(1, 1), a1 + hstep, voffA);
;             PG8_WAIT_L(8); PG8_BAR; PG8_WAIT_L(0); PG8_MMA(0, 0, At, B0); PG8_BAR; PG8_SCHED;
;             PG8_LDB(B1, 0, 1); PG8_STAGE(PG8_SB(0, 0), b2, voffB);
;             PG8_BAR; PG8_WAIT_L(0); PG8_MMA(0, 1, At, B1); PG8_BAR;
;             PG8_LDA(At, 0, 1); PG8_STAGE(PG8_SA(0, 0), a2, voffA);
;             PG8_BAR; PG8_WAIT_L(0); PG8_MMA(1, 0, At, B0); PG8_BAR; PG8_SCHED;
;             PG8_STAGE(PG8_SB(0, 1), b2 + hstep, voffB);
;             PG8_WAIT_V(6); PG8_BAR; PG8_MMA(1, 1, At, B1); PG8_BAR;
.LBB0_439:
	ds_read_b128 v[154:157], v150
	ds_read_b128 v[158:161], v150 offset:1024
	ds_read_b128 v[162:165], v150 offset:2048
	ds_read_b128 v[166:169], v150 offset:3072
	s_add_u32 s24, s20, 0x3fc000
	s_addc_u32 s25, s21, 0
	s_cmpk_eq_i32 s68, 0x54
	s_cselect_b32 s28, s55, s24
	s_cselect_b32 s29, s13, s25
	s_cselect_b32 s25, s11, s63
	s_cselect_b32 s24, s60, s61
	s_add_u32 s26, s28, 0x400000
	s_addc_u32 s27, s29, 0
	v_lshl_add_u64 v[144:145], s[20:21], 0, v[136:137]
	s_add_i32 m0, s19, 0xc000
	ds_read_b128 v[170:173], v151
	ds_read_b128 v[174:177], v151 offset:1024
	ds_read_b128 v[186:189], v151 offset:2048
	ds_read_b128 v[190:193], v151 offset:3072
	ds_read_b128 v[194:197], v151 offset:4096
	ds_read_b128 v[198:201], v151 offset:5120
	ds_read_b128 v[202:205], v151 offset:6144
	ds_read_b128 v[206:209], v151 offset:7168
	global_load_lds_dwordx4 v[144:145], off
	v_lshl_add_u64 v[144:145], s[20:21], 0, v[138:139]
	s_add_i32 m0, s19, 0xe000
	s_nop 0
	global_load_lds_dwordx4 v[144:145], off
	ds_read_b128 v[210:213], v152
	ds_read_b128 v[214:217], v152 offset:1024
	ds_read_b128 v[218:221], v152 offset:2048
	ds_read_b128 v[222:225], v152 offset:3072
	s_waitcnt lgkmcnt(0)
	s_waitcnt vmcnt(8)
	s_barrier
	s_nop 0
	v_mfma_f32_16x16x32_bf16 v[124:127], v[154:157], v[170:173], v[124:127]
	v_mfma_f32_16x16x32_bf16 v[120:123], v[162:165], v[170:173], v[120:123]
	v_mfma_f32_16x16x32_bf16 v[112:115], v[154:157], v[186:189], v[112:115]
	v_mfma_f32_16x16x32_bf16 v[104:107], v[162:165], v[186:189], v[104:107]
	v_mfma_f32_16x16x32_bf16 v[96:99], v[154:157], v[194:197], v[96:99]
	v_mfma_f32_16x16x32_bf16 v[88:91], v[162:165], v[194:197], v[88:91]
	v_mfma_f32_16x16x32_bf16 v[80:83], v[154:157], v[202:205], v[80:83]
	v_mfma_f32_16x16x32_bf16 v[72:75], v[162:165], v[202:205], v[72:75]
	v_mfma_f32_16x16x32_bf16 v[124:127], v[158:161], v[174:177], v[124:127]
	v_mfma_f32_16x16x32_bf16 v[120:123], v[166:169], v[174:177], v[120:123]
	v_mfma_f32_16x16x32_bf16 v[112:115], v[158:161], v[190:193], v[112:115]
	v_mfma_f32_16x16x32_bf16 v[104:107], v[166:169], v[190:193], v[104:107]
	v_mfma_f32_16x16x32_bf16 v[96:99], v[158:161], v[198:201], v[96:99]
	v_mfma_f32_16x16x32_bf16 v[88:91], v[166:169], v[198:201], v[88:91]
	v_mfma_f32_16x16x32_bf16 v[80:83], v[158:161], v[206:209], v[80:83]
	v_mfma_f32_16x16x32_bf16 v[72:75], v[166:169], v[206:209], v[72:75]
	v_mfma_f32_16x16x32_bf16 v[116:119], v[210:213], v[170:173], v[116:119]
	v_mfma_f32_16x16x32_bf16 v[108:111], v[218:221], v[170:173], v[108:111]
	v_mfma_f32_16x16x32_bf16 v[100:103], v[210:213], v[186:189], v[100:103]
	v_mfma_f32_16x16x32_bf16 v[92:95], v[218:221], v[186:189], v[92:95]
	v_mfma_f32_16x16x32_bf16 v[84:87], v[210:213], v[194:197], v[84:87]
	v_mfma_f32_16x16x32_bf16 v[76:79], v[218:221], v[194:197], v[76:79]
	v_mfma_f32_16x16x32_bf16 v[68:71], v[210:213], v[202:205], v[68:71]
	v_mfma_f32_16x16x32_bf16 v[64:67], v[218:221], v[202:205], v[64:67]
	v_mfma_f32_16x16x32_bf16 v[116:119], v[214:217], v[174:177], v[116:119]
	v_mfma_f32_16x16x32_bf16 v[108:111], v[222:225], v[174:177], v[108:111]
	v_mfma_f32_16x16x32_bf16 v[100:103], v[214:217], v[190:193], v[100:103]
	v_mfma_f32_16x16x32_bf16 v[92:95], v[222:225], v[190:193], v[92:95]
	v_mfma_f32_16x16x32_bf16 v[84:87], v[214:217], v[198:201], v[84:87]
	v_mfma_f32_16x16x32_bf16 v[76:79], v[222:225], v[198:201], v[76:79]
	v_mfma_f32_16x16x32_bf16 v[68:71], v[214:217], v[206:209], v[68:71]
	v_mfma_f32_16x16x32_bf16 v[64:67], v[222:225], v[206:209], v[64:67]
	s_nop 0
	s_barrier
	s_add_i32 s69, s45, s36
	v_lshl_add_u64 v[144:145], s[24:25], 0, v[130:131]
	s_mov_b32 m0, s69
	s_nop 0
	global_load_lds_dwordx4 v[144:145], off
	v_lshl_add_u64 v[144:145], s[24:25], 0, v[134:135]
	s_add_i32 m0, s69, 0x2000
	s_nop 0
	global_load_lds_dwordx4 v[144:145], off
	s_mov_b32 m0, s19
	v_lshl_add_u64 v[144:145], s[28:29], 0, v[128:129]
	ds_read_b128 v[170:173], v151 offset:16384
	ds_read_b128 v[174:177], v151 offset:17408
	ds_read_b128 v[186:189], v151 offset:18432
	ds_read_b128 v[190:193], v151 offset:19456
	ds_read_b128 v[194:197], v151 offset:20480
	ds_read_b128 v[198:201], v151 offset:21504
	ds_read_b128 v[202:205], v151 offset:22528
	ds_read_b128 v[206:209], v151 offset:23552
	global_load_lds_dwordx4 v[144:145], off
	v_lshl_add_u64 v[144:145], s[28:29], 0, v[132:133]
	s_mov_b32 m0, s37
	s_nop 0
	global_load_lds_dwordx4 v[144:145], off
	s_add_u32 s72, s24, 0x4000
	s_addc_u32 s73, s25, 0
	s_add_i32 s69, s48, s36
	v_lshl_add_u64 v[144:145], s[72:73], 0, v[130:131]
	s_mov_b32 m0, s69
	s_nop 0
	global_load_lds_dwordx4 v[144:145], off
	v_lshl_add_u64 v[144:145], s[72:73], 0, v[134:135]
	s_add_i32 m0, s69, 0x2000
	s_nop 0
	global_load_lds_dwordx4 v[144:145], off
	s_waitcnt lgkmcnt(0)
	s_waitcnt vmcnt(8)
	s_barrier
; #define PG8_STAGE(bufoff, gbase, voff) do { _Pragma("unroll") for (int _i = 0; _i < 2; ++_i) \
;         __builtin_amdgcn_global_load_lds((const unsigned*)((const char*)(gbase) + (voff)[_i]), (LAS unsigned*)(lds + (bufoff) + ldsw + _i * 8192), 16, 0, 0); } while (0)
; #define PG8_LDA(dst, b, h) do { _Pragma("unroll") for (int m = 0; m < 4; ++m) _Pragma("unroll") for (int k = 0; k < 2; ++k) dst[m][k] = *(const LAS bf16x8*)(lds + PG8_SA(b, h) + aoff + m * 2048 + k * 1024); } while (0)
; #define PG8_LDB(dst, b, h) do { _Pragma("unroll") for (int n = 0; n < 2; ++n) _Pragma("unroll") for (int k = 0; k < 2; ++k) dst[n][k] = *(const LAS bf16x8*)(lds + PG8_SB(b, h) + boff + n * 2048 + k * 1024); } while (0)
; #define PG8_MMA(ai, bj, At, Bt) do { __builtin_amdgcn_s_setprio(1); _Pragma("unroll") for (int m = 0; m < 4; ++m) _Pragma("unroll") for (int n = 0; n < 2; ++n) _Pragma("unroll") for (int k = 0; k < 2; ++k) \
;         acc[ai][bj][m][n] = __builtin_amdgcn_mfma_f32_16x16x32_bf16(Bt[n][k], At[m][k], acc[ai][bj][m][n], 0, 0, 0); __builtin_amdgcn_s_setprio(0); } while (0)
; #define PG8_WAIT_V(n) asm volatile("s_waitcnt vmcnt(" #n ")" ::: "memory")
; #define PG8_WAIT_L(n) asm volatile("s_waitcnt lgkmcnt(" #n ")" ::: "memory")
; #define PG8_BAR __builtin_amdgcn_s_barrier()
; #define PG8_SCHED __builtin_amdgcn_sched_barrier(0)
; template <class Epi>
; __device__ __forceinline__ void gemm_phase(LAS unsigned char* lds, const Gemm g, const StaticOrder& S, const Epi& E) {
;     ...
;             PG8_BAR; PG8_WAIT_L(0); PG8_MMA(1, 0, At, B0); PG8_BAR; PG8_SCHED;
;             PG8_STAGE(PG8_SB(0, 1), b2 + hstep, voffB);
;             PG8_WAIT_V(6); PG8_BAR; PG8_MMA(1, 1, At, B1); PG8_BAR;
;             PG8_LDB(B0, 1, 0); PG8_SCHED; PG8_LDA(At, 1, 0); PG8_STAGE(PG8_SA(0, 1), a2 + hstep, voffA);
;             PG8_WAIT_L(8); PG8_BAR; PG8_WAIT_L(0); PG8_MMA(0, 0, At, B0); PG8_BAR; PG8_SCHED;
;             PG8_LDB(B1, 1, 1); PG8_STAGE(PG8_SB(1, 0), b3, voffB);
;             PG8_BAR; PG8_WAIT_L(0); PG8_MMA(0, 1, At, B1); PG8_BAR;
;             PG8_LDA(At, 1, 1); PG8_STAGE(PG8_SA(1, 0), a3, voffA);
;             PG8_BAR; PG8_WAIT_L(0); PG8_MMA(1, 0, At, B0); PG8_BAR; PG8_SCHED;
	s_nop 0
	v_mfma_f32_16x16x32_bf16 v[60:63], v[154:157], v[170:173], v[60:63]
	v_mfma_f32_16x16x32_bf16 v[56:59], v[162:165], v[170:173], v[56:59]
	v_mfma_f32_16x16x32_bf16 v[52:55], v[154:157], v[186:189], v[52:55]
	v_mfma_f32_16x16x32_bf16 v[44:47], v[162:165], v[186:189], v[44:47]
	v_mfma_f32_16x16x32_bf16 v[36:39], v[154:157], v[194:197], v[36:39]
	v_mfma_f32_16x16x32_bf16 v[28:31], v[162:165], v[194:197], v[28:31]
	v_mfma_f32_16x16x32_bf16 v[20:23], v[154:157], v[202:205], v[20:23]
	v_mfma_f32_16x16x32_bf16 v[12:15], v[162:165], v[202:205], v[12:15]
	v_mfma_f32_16x16x32_bf16 v[60:63], v[158:161], v[174:177], v[60:63]
	v_mfma_f32_16x16x32_bf16 v[56:59], v[166:169], v[174:177], v[56:59]
	v_mfma_f32_16x16x32_bf16 v[52:55], v[158:161], v[190:193], v[52:55]
	v_mfma_f32_16x16x32_bf16 v[44:47], v[166:169], v[190:193], v[44:47]
	v_mfma_f32_16x16x32_bf16 v[36:39], v[158:161], v[198:201], v[36:39]
	v_mfma_f32_16x16x32_bf16 v[28:31], v[166:169], v[198:201], v[28:31]
	v_mfma_f32_16x16x32_bf16 v[20:23], v[158:161], v[206:209], v[20:23]
	v_mfma_f32_16x16x32_bf16 v[12:15], v[166:169], v[206:209], v[12:15]
	v_mfma_f32_16x16x32_bf16 v[48:51], v[210:213], v[170:173], v[48:51]
	v_mfma_f32_16x16x32_bf16 v[40:43], v[218:221], v[170:173], v[40:43]
	v_mfma_f32_16x16x32_bf16 v[32:35], v[210:213], v[186:189], v[32:35]
	v_mfma_f32_16x16x32_bf16 v[24:27], v[218:221], v[186:189], v[24:27]
	v_mfma_f32_16x16x32_bf16 v[16:19], v[210:213], v[194:197], v[16:19]
	v_mfma_f32_16x16x32_bf16 v[8:11], v[218:221], v[194:197], v[8:11]
	v_mfma_f32_16x16x32_bf16 v[4:7], v[210:213], v[202:205], v[4:7]
	v_mfma_f32_16x16x32_bf16 v[0:3], v[218:221], v[202:205], v[0:3]
	v_mfma_f32_16x16x32_bf16 v[48:51], v[214:217], v[174:177], v[48:51]
	v_mfma_f32_16x16x32_bf16 v[40:43], v[222:225], v[174:177], v[40:43]
	v_mfma_f32_16x16x32_bf16 v[32:35], v[214:217], v[190:193], v[32:35]
	v_mfma_f32_16x16x32_bf16 v[24:27], v[222:225], v[190:193], v[24:27]
	v_mfma_f32_16x16x32_bf16 v[16:19], v[214:217], v[198:201], v[16:19]
	v_mfma_f32_16x16x32_bf16 v[8:11], v[222:225], v[198:201], v[8:11]
	v_mfma_f32_16x16x32_bf16 v[4:7], v[214:217], v[206:209], v[4:7]
	v_mfma_f32_16x16x32_bf16 v[0:3], v[222:225], v[206:209], v[0:3]
	s_nop 0
	s_add_i32 s69, 0, 0x18000
	v_add_u32_e32 v144, s69, v148
	s_barrier
	ds_read_b128 v[154:157], v144
	ds_read_b128 v[158:161], v144 offset:1024
	ds_read_b128 v[162:165], v144 offset:2048
	ds_read_b128 v[166:169], v144 offset:3072
	s_add_u32 s28, s28, 0x4000
	s_addc_u32 s29, s29, 0
	s_mov_b32 m0, s38
	v_lshl_add_u64 v[144:145], s[28:29], 0, v[128:129]
	ds_read_b128 v[170:173], v151 offset:32768
	ds_read_b128 v[174:177], v151 offset:33792
	ds_read_b128 v[186:189], v151 offset:34816
	ds_read_b128 v[190:193], v151 offset:35840
	ds_read_b128 v[194:197], v151 offset:36864
	ds_read_b128 v[198:201], v151 offset:37888
	ds_read_b128 v[202:205], v151 offset:38912
	ds_read_b128 v[206:209], v151 offset:39936
	global_load_lds_dwordx4 v[144:145], off
	v_lshl_add_u64 v[144:145], s[28:29], 0, v[132:133]
	s_mov_b32 m0, s39
	s_nop 0
	global_load_lds_dwordx4 v[144:145], off
	v_add_u32_e32 v253, 0x1c000, v148
	ds_read_b128 v[210:213], v253
	ds_read_b128 v[214:217], v253 offset:1024
	ds_read_b128 v[218:221], v253 offset:2048
	ds_read_b128 v[222:225], v253 offset:3072
	s_waitcnt lgkmcnt(0)
	s_waitcnt vmcnt(8)
	s_barrier
	s_nop 0
	v_mfma_f32_16x16x32_bf16 v[124:127], v[154:157], v[170:173], v[124:127]
	v_mfma_f32_16x16x32_bf16 v[120:123], v[162:165], v[170:173], v[120:123]
	v_mfma_f32_16x16x32_bf16 v[112:115], v[154:157], v[186:189], v[112:115]
	v_mfma_f32_16x16x32_bf16 v[104:107], v[162:165], v[186:189], v[104:107]
	v_mfma_f32_16x16x32_bf16 v[96:99], v[154:157], v[194:197], v[96:99]
	v_mfma_f32_16x16x32_bf16 v[88:91], v[162:165], v[194:197], v[88:91]
	v_mfma_f32_16x16x32_bf16 v[80:83], v[154:157], v[202:205], v[80:83]
	v_mfma_f32_16x16x32_bf16 v[72:75], v[162:165], v[202:205], v[72:75]
	v_mfma_f32_16x16x32_bf16 v[124:127], v[158:161], v[174:177], v[124:127]
	v_mfma_f32_16x16x32_bf16 v[120:123], v[166:169], v[174:177], v[120:123]
	v_mfma_f32_16x16x32_bf16 v[112:115], v[158:161], v[190:193], v[112:115]
	v_mfma_f32_16x16x32_bf16 v[104:107], v[166:169], v[190:193], v[104:107]
	v_mfma_f32_16x16x32_bf16 v[96:99], v[158:161], v[198:201], v[96:99]
	v_mfma_f32_16x16x32_bf16 v[88:91], v[166:169], v[198:201], v[88:91]
	v_mfma_f32_16x16x32_bf16 v[80:83], v[158:161], v[206:209], v[80:83]
	v_mfma_f32_16x16x32_bf16 v[72:75], v[166:169], v[206:209], v[72:75]
	v_mfma_f32_16x16x32_bf16 v[116:119], v[210:213], v[170:173], v[116:119]
	v_mfma_f32_16x16x32_bf16 v[108:111], v[218:221], v[170:173], v[108:111]
	v_mfma_f32_16x16x32_bf16 v[100:103], v[210:213], v[186:189], v[100:103]
	v_mfma_f32_16x16x32_bf16 v[92:95], v[218:221], v[186:189], v[92:95]
	v_mfma_f32_16x16x32_bf16 v[84:87], v[210:213], v[194:197], v[84:87]
	v_mfma_f32_16x16x32_bf16 v[76:79], v[218:221], v[194:197], v[76:79]
	v_mfma_f32_16x16x32_bf16 v[68:71], v[210:213], v[202:205], v[68:71]
	v_mfma_f32_16x16x32_bf16 v[64:67], v[218:221], v[202:205], v[64:67]
	v_mfma_f32_16x16x32_bf16 v[116:119], v[214:217], v[174:177], v[116:119]
	v_mfma_f32_16x16x32_bf16 v[108:111], v[222:225], v[174:177], v[108:111]
	v_mfma_f32_16x16x32_bf16 v[100:103], v[214:217], v[190:193], v[100:103]
	v_mfma_f32_16x16x32_bf16 v[92:95], v[222:225], v[190:193], v[92:95]
	v_mfma_f32_16x16x32_bf16 v[84:87], v[214:217], v[198:201], v[84:87]
	v_mfma_f32_16x16x32_bf16 v[76:79], v[222:225], v[198:201], v[76:79]
	v_mfma_f32_16x16x32_bf16 v[68:71], v[214:217], v[206:209], v[68:71]
	v_mfma_f32_16x16x32_bf16 v[64:67], v[222:225], v[206:209], v[64:67]
	s_nop 0
	s_barrier
; #define PG8_STAGE(bufoff, gbase, voff) do { _Pragma("unroll") for (int _i = 0; _i < 2; ++_i) \
;         __builtin_amdgcn_global_load_lds((const unsigned*)((const char*)(gbase) + (voff)[_i]), (LAS unsigned*)(lds + (bufoff) + ldsw + _i * 8192), 16, 0, 0); } while (0)
; #define PG8_LDA(dst, b, h) do { _Pragma("unroll") for (int m = 0; m < 4; ++m) _Pragma("unroll") for (int k = 0; k < 2; ++k) dst[m][k] = *(const LAS bf16x8*)(lds + PG8_SA(b, h) + aoff + m * 2048 + k * 1024); } while (0)
; #define PG8_LDB(dst, b, h) do { _Pragma("unroll") for (int n = 0; n < 2; ++n) _Pragma("unroll") for (int k = 0; k < 2; ++k) dst[n][k] = *(const LAS bf16x8*)(lds + PG8_SB(b, h) + boff + n * 2048 + k * 1024); } while (0)
; #define PG8_MMA(ai, bj, At, Bt) do { __builtin_amdgcn_s_setprio(1); _Pragma("unroll") for (int m = 0; m < 4; ++m) _Pragma("unroll") for (int n = 0; n < 2; ++n) _Pragma("unroll") for (int k = 0; k < 2; ++k) \
;         acc[ai][bj][m][n] = __builtin_amdgcn_mfma_f32_16x16x32_bf16(Bt[n][k], At[m][k], acc[ai][bj][m][n], 0, 0, 0); __builtin_amdgcn_s_setprio(0); } while (0)
; #define PG8_WAIT_V(n) asm volatile("s_waitcnt vmcnt(" #n ")" ::: "memory")
; #define PG8_WAIT_L(n) asm volatile("s_waitcnt lgkmcnt(" #n ")" ::: "memory")
; #define PG8_BAR __builtin_amdgcn_s_barrier()
; #define PG8_SCHED __builtin_amdgcn_sched_barrier(0)
; template <class Epi>
; __device__ __forceinline__ void gemm_phase(LAS unsigned char* lds, const Gemm g, const StaticOrder& S, const Epi& E) {
;     ...
;             PG8_LDB(B1, 1, 1); PG8_STAGE(PG8_SB(1, 0), b3, voffB);
;             PG8_BAR; PG8_WAIT_L(0); PG8_MMA(0, 1, At, B1); PG8_BAR;
;             PG8_LDA(At, 1, 1); PG8_STAGE(PG8_SA(1, 0), a3, voffA);
;             PG8_BAR; PG8_WAIT_L(0); PG8_MMA(1, 0, At, B0); PG8_BAR; PG8_SCHED;
;             PG8_STAGE(PG8_SB(1, 1), b3 + hstep, voffB);
;             PG8_WAIT_V(6); PG8_BAR; PG8_MMA(1, 1, At, B1); PG8_BAR;
;         }
	s_add_i32 s72, 0, 0x1c000
	s_add_u32 s28, s24, 0x40000
	v_add_u32_e32 v144, s72, v148
	s_addc_u32 s29, s25, 0
	s_add_i32 s69, s69, s36
	s_nop 0
	v_lshl_add_u64 v[144:145], s[28:29], 0, v[130:131]
	s_mov_b32 m0, s69
	s_nop 0
	global_load_lds_dwordx4 v[144:145], off
	v_lshl_add_u64 v[144:145], s[28:29], 0, v[134:135]
	s_add_i32 m0, s69, 0x2000
	s_nop 0
	global_load_lds_dwordx4 v[144:145], off
	s_mov_b32 m0, s41
	v_lshl_add_u64 v[144:145], s[26:27], 0, v[128:129]
	ds_read_b128 v[170:173], v151 offset:49152
	ds_read_b128 v[174:177], v151 offset:50176
	ds_read_b128 v[186:189], v151 offset:51200
	ds_read_b128 v[190:193], v151 offset:52224
	ds_read_b128 v[194:197], v151 offset:53248
	ds_read_b128 v[198:201], v151 offset:54272
	ds_read_b128 v[202:205], v151 offset:55296
	ds_read_b128 v[206:209], v151 offset:56320
	global_load_lds_dwordx4 v[144:145], off
	v_lshl_add_u64 v[144:145], s[26:27], 0, v[132:133]
	s_mov_b32 m0, s42
	s_nop 0
	global_load_lds_dwordx4 v[144:145], off
	s_add_u32 s24, s24, 0x44000
	s_addc_u32 s25, s25, 0
	s_add_i32 s26, s72, s36
	v_lshl_add_u64 v[144:145], s[24:25], 0, v[130:131]
	s_mov_b32 m0, s26
	s_nop 0
	global_load_lds_dwordx4 v[144:145], off
	v_lshl_add_u64 v[144:145], s[24:25], 0, v[134:135]
	s_add_i32 m0, s26, 0x2000
	s_nop 0
	global_load_lds_dwordx4 v[144:145], off
	s_waitcnt lgkmcnt(0)
	s_waitcnt vmcnt(8)
	s_barrier
	s_nop 0
	v_mfma_f32_16x16x32_bf16 v[60:63], v[154:157], v[170:173], v[60:63]
	v_mfma_f32_16x16x32_bf16 v[56:59], v[162:165], v[170:173], v[56:59]
	v_mfma_f32_16x16x32_bf16 v[52:55], v[154:157], v[186:189], v[52:55]
	v_mfma_f32_16x16x32_bf16 v[44:47], v[162:165], v[186:189], v[44:47]
	v_mfma_f32_16x16x32_bf16 v[36:39], v[154:157], v[194:197], v[36:39]
	v_mfma_f32_16x16x32_bf16 v[28:31], v[162:165], v[194:197], v[28:31]
	v_mfma_f32_16x16x32_bf16 v[20:23], v[154:157], v[202:205], v[20:23]
	v_mfma_f32_16x16x32_bf16 v[12:15], v[162:165], v[202:205], v[12:15]
	v_mfma_f32_16x16x32_bf16 v[60:63], v[158:161], v[174:177], v[60:63]
	v_mfma_f32_16x16x32_bf16 v[56:59], v[166:169], v[174:177], v[56:59]
	v_mfma_f32_16x16x32_bf16 v[52:55], v[158:161], v[190:193], v[52:55]
	v_mfma_f32_16x16x32_bf16 v[44:47], v[166:169], v[190:193], v[44:47]
	v_mfma_f32_16x16x32_bf16 v[36:39], v[158:161], v[198:201], v[36:39]
	v_mfma_f32_16x16x32_bf16 v[28:31], v[166:169], v[198:201], v[28:31]
	v_mfma_f32_16x16x32_bf16 v[20:23], v[158:161], v[206:209], v[20:23]
	v_mfma_f32_16x16x32_bf16 v[12:15], v[166:169], v[206:209], v[12:15]
	v_mfma_f32_16x16x32_bf16 v[48:51], v[210:213], v[170:173], v[48:51]
	v_mfma_f32_16x16x32_bf16 v[40:43], v[218:221], v[170:173], v[40:43]
	v_mfma_f32_16x16x32_bf16 v[32:35], v[210:213], v[186:189], v[32:35]
	v_mfma_f32_16x16x32_bf16 v[24:27], v[218:221], v[186:189], v[24:27]
	v_mfma_f32_16x16x32_bf16 v[16:19], v[210:213], v[194:197], v[16:19]
	v_mfma_f32_16x16x32_bf16 v[8:11], v[218:221], v[194:197], v[8:11]
	v_mfma_f32_16x16x32_bf16 v[4:7], v[210:213], v[202:205], v[4:7]
	v_mfma_f32_16x16x32_bf16 v[0:3], v[218:221], v[202:205], v[0:3]
	v_mfma_f32_16x16x32_bf16 v[48:51], v[214:217], v[174:177], v[48:51]
	v_mfma_f32_16x16x32_bf16 v[40:43], v[222:225], v[174:177], v[40:43]
	v_mfma_f32_16x16x32_bf16 v[32:35], v[214:217], v[190:193], v[32:35]
	v_mfma_f32_16x16x32_bf16 v[24:27], v[222:225], v[190:193], v[24:27]
	v_mfma_f32_16x16x32_bf16 v[16:19], v[214:217], v[198:201], v[16:19]
	v_mfma_f32_16x16x32_bf16 v[8:11], v[222:225], v[198:201], v[8:11]
	v_mfma_f32_16x16x32_bf16 v[4:7], v[214:217], v[206:209], v[4:7]
	v_mfma_f32_16x16x32_bf16 v[0:3], v[222:225], v[206:209], v[0:3]
	s_nop 0
	s_add_i32 s68, s68, 2
	s_add_u32 s61, s61, 0x80000
	s_addc_u32 s63, s63, 0
	s_add_u32 s20, s20, 0x800000
	s_addc_u32 s21, s21, 0
	s_cmpk_gt_u32 s68, 0x55
	s_barrier
	s_cbranch_scc0 .LBB0_439
; __device__ __forceinline__ unsigned pk_bf16(float lo, float hi) { unsigned r; asm("v_cvt_pk_bf16_f32 %0, %1, %2" : "=v"(r) : "v"(lo), "v"(hi)); return r; }
;     __device__ __forceinline__ void operator()(const f32x4 (&acc)[2][2][4][2], const Unit& u, int wr, int wc, int fr, int fq) const {
;         const int row0 = u.pm * BM + wr * 64 + fr; const int col0 = u.pn * BM + wc * 32 + 8 * fq;
; #pragma unroll
;         for (int ai = 0; ai < 2; ++ai)
; #pragma unroll
;             for (int m = 0; m < 4; ++m) { bf16_t* rowp = O + (size_t)(row0 + ai * HALF + m * 16) * ldc + col0;
; #pragma unroll
;                 for (int bj = 0; bj < 2; ++bj) { const f32x4 v0 = acc[ai][bj][m][0], v1 = acc[ai][bj][m][1];
;                     u32x4 w; w.x = pk_bf16(v0[0], v0[1]); w.y = pk_bf16(v0[2], v0[3]); w.z = pk_bf16(v1[0], v1[1]); w.w = pk_bf16(v1[2], v1[3]);
;                     *(u32x4*)(rowp + bj * HALF) = w; } }
;     }
	v_lshl_add_u32 v154, s18, 8, v147
	v_lshl_or_b32 v144, s54, 8, v149
	v_ashrrev_i32_e32 v155, 31, v154
	v_ashrrev_i32_e32 v145, 31, v144
	v_lshlrev_b64 v[156:157], 12, v[154:155]
	v_lshl_add_u64 v[156:157], s[52:53], 0, v[156:157]
	v_lshlrev_b64 v[158:159], 1, v[144:145]
	v_lshl_add_u64 v[144:145], v[156:157], 0, v[158:159]
	s_mov_b32 s11, 0x80000
	v_cvt_pk_bf16_f32 v60, v60, v61
	v_cvt_pk_bf16_f32 v61, v62, v63
	v_cvt_pk_bf16_f32 v62, v56, v57
	v_add_co_u32_e32 v56, vcc, s11, v144
	v_cvt_pk_bf16_f32 v116, v116, v117
	v_cvt_pk_bf16_f32 v117, v118, v119
	v_cvt_pk_bf16_f32 v118, v108, v109
	v_or_b32_e32 v108, 16, v154
	s_nop 0
	v_addc_co_u32_e32 v57, vcc, 0, v145, vcc
	v_cvt_pk_bf16_f32 v48, v48, v49
	v_cvt_pk_bf16_f32 v49, v50, v51
	v_cvt_pk_bf16_f32 v51, v42, v43
	v_cvt_pk_bf16_f32 v42, v44, v45
	v_add_co_u32_e32 v44, vcc, s49, v144
	v_ashrrev_i32_e32 v109, 31, v108
	v_cvt_pk_bf16_f32 v100, v100, v101
	v_cvt_pk_bf16_f32 v101, v102, v103
	v_cvt_pk_bf16_f32 v102, v92, v93
	v_or_b32_e32 v92, 32, v154
	v_addc_co_u32_e32 v45, vcc, 0, v145, vcc
	v_lshlrev_b64 v[108:109], 12, v[108:109]
	v_ashrrev_i32_e32 v93, 31, v92
	v_cvt_pk_bf16_f32 v84, v84, v85
	v_cvt_pk_bf16_f32 v85, v86, v87
	v_cvt_pk_bf16_f32 v86, v76, v77
	v_or_b32_e32 v76, 48, v154
	s_mov_b64 s[20:21], 0x80000
	v_cvt_pk_bf16_f32 v32, v32, v33
	v_cvt_pk_bf16_f32 v33, v34, v35
	v_cvt_pk_bf16_f32 v35, v26, v27
	v_cvt_pk_bf16_f32 v26, v28, v29
	v_add_co_u32_e32 v28, vcc, s50, v144
	v_lshl_add_u64 v[108:109], s[52:53], 0, v[108:109]
	v_lshlrev_b64 v[92:93], 12, v[92:93]
	v_ashrrev_i32_e32 v77, 31, v76
	v_cvt_pk_bf16_f32 v68, v68, v69
	v_cvt_pk_bf16_f32 v69, v70, v71
	v_cvt_pk_bf16_f32 v70, v64, v65
	v_lshl_add_u64 v[64:65], v[144:145], 0, s[20:21]
	v_addc_co_u32_e32 v29, vcc, 0, v145, vcc
	v_cvt_pk_bf16_f32 v119, v110, v111
	global_store_dwordx4 v[144:145], v[116:119], off offset:256
	v_lshl_add_u64 v[92:93], s[52:53], 0, v[92:93]
	v_lshlrev_b64 v[76:77], 12, v[76:77]
	v_lshl_add_u64 v[116:117], v[108:109], 0, v[158:159]
	v_cvt_pk_bf16_f32 v50, v40, v41
	global_store_dwordx4 v[64:65], v[48:51], off offset:256
	v_cvt_pk_bf16_f32 v16, v16, v17
	v_cvt_pk_bf16_f32 v17, v18, v19
	v_cvt_pk_bf16_f32 v19, v10, v11
	v_cvt_pk_bf16_f32 v10, v12, v13
	v_add_co_u32_e32 v12, vcc, s51, v144
	s_nop 0
	v_lshl_add_u64 v[48:49], v[144:145], 0, s[4:5]
	v_cvt_pk_bf16_f32 v103, v94, v95
	global_store_dwordx4 v[116:117], v[100:103], off offset:256
	v_lshl_add_u64 v[76:77], s[52:53], 0, v[76:77]
	v_cvt_pk_bf16_f32 v34, v24, v25
	global_store_dwordx4 v[48:49], v[32:35], off offset:256
	v_lshl_add_u64 v[100:101], v[92:93], 0, v[158:159]
	v_addc_co_u32_e32 v13, vcc, 0, v145, vcc
	v_lshl_add_u64 v[32:33], v[144:145], 0, s[6:7]
	v_cvt_pk_bf16_f32 v87, v78, v79
	global_store_dwordx4 v[100:101], v[84:87], off offset:256
	v_cvt_pk_bf16_f32 v18, v8, v9
	global_store_dwordx4 v[32:33], v[16:19], off offset:256
	s_and_b64 vcc, exec, s[0:1]
	v_lshl_add_u64 v[84:85], v[76:77], 0, v[158:159]
	v_lshl_add_u64 v[16:17], v[144:145], 0, s[8:9]
	s_mov_b32 s54, s10
	s_mov_b32 s18, s12
	s_mov_b64 s[20:21], s[16:17]
	s_mov_b64 s[24:25], s[14:15]
	v_cvt_pk_bf16_f32 v124, v124, v125
	v_cvt_pk_bf16_f32 v125, v126, v127
	v_cvt_pk_bf16_f32 v126, v120, v121
	v_cvt_pk_bf16_f32 v127, v122, v123
	global_store_dwordx4 v[144:145], v[124:127], off
	v_cvt_pk_bf16_f32 v108, v112, v113
	v_cvt_pk_bf16_f32 v109, v114, v115
	v_cvt_pk_bf16_f32 v110, v104, v105
	v_cvt_pk_bf16_f32 v111, v106, v107
	global_store_dwordx4 v[116:117], v[108:111], off
	v_cvt_pk_bf16_f32 v92, v96, v97
	v_cvt_pk_bf16_f32 v93, v98, v99
	v_cvt_pk_bf16_f32 v94, v88, v89
	v_cvt_pk_bf16_f32 v95, v90, v91
	global_store_dwordx4 v[100:101], v[92:95], off
	v_cvt_pk_bf16_f32 v76, v80, v81
	v_cvt_pk_bf16_f32 v77, v82, v83
	v_cvt_pk_bf16_f32 v78, v72, v73
	v_cvt_pk_bf16_f32 v79, v74, v75
	global_store_dwordx4 v[84:85], v[76:79], off
	v_cvt_pk_bf16_f32 v71, v66, v67
	global_store_dwordx4 v[84:85], v[68:71], off offset:256
	v_cvt_pk_bf16_f32 v63, v58, v59
	global_store_dwordx4 v[56:57], v[60:63], off
	v_cvt_pk_bf16_f32 v40, v52, v53
	v_cvt_pk_bf16_f32 v41, v54, v55
	v_cvt_pk_bf16_f32 v43, v46, v47
	global_store_dwordx4 v[44:45], v[40:43], off
	v_cvt_pk_bf16_f32 v24, v36, v37
	v_cvt_pk_bf16_f32 v25, v38, v39
	v_cvt_pk_bf16_f32 v27, v30, v31
	global_store_dwordx4 v[28:29], v[24:27], off
	v_cvt_pk_bf16_f32 v8, v20, v21
	v_cvt_pk_bf16_f32 v9, v22, v23
	v_cvt_pk_bf16_f32 v11, v14, v15
	global_store_dwordx4 v[12:13], v[8:11], off
	v_cvt_pk_bf16_f32 v4, v4, v5
	v_cvt_pk_bf16_f32 v5, v6, v7
	v_cvt_pk_bf16_f32 v6, v0, v1
	v_cvt_pk_bf16_f32 v7, v2, v3
	global_store_dwordx4 v[16:17], v[4:7], off offset:256
	s_cbranch_vccz .LBB0_432
	s_waitcnt vmcnt(0)
	s_cmpk_gt_u32 s30, 0xff
	s_cbranch_scc1 .LBB0_443
	s_barrier

; #define PG8_STAGE(bufoff, gbase, voff) do { _Pragma("unroll") for (int _i = 0; _i < 2; ++_i) \
;         __builtin_amdgcn_global_load_lds((const unsigned*)((const char*)(gbase) + (voff)[_i]), (LAS unsigned*)(lds + (bufoff) + ldsw + _i * 8192), 16, 0, 0); } while (0)
; #define PG8_LDA(dst, b, h) do { _Pragma("unroll") for (int m = 0; m < 4; ++m) _Pragma("unroll") for (int k = 0; k < 2; ++k) dst[m][k] = *(const LAS bf16x8*)(lds + PG8_SA(b, h) + aoff + m * 2048 + k * 1024); } while (0)
; #define PG8_LDB(dst, b, h) do { _Pragma("unroll") for (int n = 0; n < 2; ++n) _Pragma("unroll") for (int k = 0; k < 2; ++k) dst[n][k] = *(const LAS bf16x8*)(lds + PG8_SB(b, h) + boff + n * 2048 + k * 1024); } while (0)
; #define PG8_MMA(ai, bj, At, Bt) do { __builtin_amdgcn_s_setprio(1); _Pragma("unroll") for (int m = 0; m < 4; ++m) _Pragma("unroll") for (int n = 0; n < 2; ++n) _Pragma("unroll") for (int k = 0; k < 2; ++k) \
;         acc[ai][bj][m][n] = __builtin_amdgcn_mfma_f32_16x16x32_bf16(Bt[n][k], At[m][k], acc[ai][bj][m][n], 0, 0, 0); __builtin_amdgcn_s_setprio(0); } while (0)
; #define PG8_WAIT_V(n) asm volatile("s_waitcnt vmcnt(" #n ")" ::: "memory")
; #define PG8_WAIT_L(n) asm volatile("s_waitcnt lgkmcnt(" #n ")" ::: "memory")
; template <class Epi>
; __device__ __forceinline__ void gemm_phase(LAS unsigned char* lds, const Gemm g, const StaticOrder& S, const Epi& E) {
;     ...
;         for (int t = 0; t < nt; t += 2) {
;             const bool last = (t == nt - 2);
;             const char* a1 = cA + (size_t)(t + 1) * kstepA;
;             const char* a2 = last ? nA : cA + (size_t)(t + 2) * kstepA; const char* b2 = last ? nB : cB + (size_t)(t + 2) * kstepB;
;             const char* a3 = a2 + kstepA; const char* b3 = b2 + kstepB;
;             PG8_LDB(B0, 0, 0); PG8_SCHED; PG8_LDA(At, 0, 0); PG8_STAGE(PG8_SA(1, 1), a1 + hstep, voffA);
;             PG8_WAIT_L(8); PG8_BAR; PG8_WAIT_L(0); PG8_MMA(0, 0, At, B0); PG8_BAR; PG8_SCHED;
;             PG8_LDB(B1, 0, 1); PG8_STAGE(PG8_SB(0, 0), b2, voffB);
;             PG8_BAR; PG8_WAIT_L(0); PG8_MMA(0, 1, At, B1); PG8_BAR;
;             PG8_LDA(At, 0, 1); PG8_STAGE(PG8_SA(0, 0), a2, voffA);
;             PG8_BAR; PG8_WAIT_L(0); PG8_MMA(1, 0, At, B0); PG8_BAR; PG8_SCHED;
;             PG8_STAGE(PG8_SB(0, 1), b2 + hstep, voffB);
;             PG8_WAIT_V(6); PG8_BAR; PG8_MMA(1, 1, At, B1); PG8_BAR;
.LBB0_563:
	v_add_u32_e32 v164, s42, v133
	ds_read_b128 v[150:153], v164
	ds_read_b128 v[156:159], v164 offset:1024
	ds_read_b128 v[160:163], v164 offset:2048
	ds_read_b128 v[164:167], v164 offset:3072
	s_add_u32 s24, s18, 0x3fc000
	s_addc_u32 s25, s19, 0
	s_and_b64 s[22:23], exec, s[22:23]
	s_cselect_b32 s24, s48, s24
	s_cselect_b32 s25, s7, s25
	s_add_u32 s22, s24, 0x400000
	s_addc_u32 s23, s25, 0
	v_lshl_add_u64 v[206:207], s[18:19], 0, v[142:143]
	s_add_i32 m0, s13, 0xc000
	ds_read_b128 v[168:171], v155
	ds_read_b128 v[172:175], v155 offset:1024
	ds_read_b128 v[176:179], v155 offset:2048
	ds_read_b128 v[186:189], v155 offset:3072
	ds_read_b128 v[190:193], v155 offset:4096
	ds_read_b128 v[194:197], v155 offset:5120
	ds_read_b128 v[198:201], v155 offset:6144
	ds_read_b128 v[202:205], v155 offset:7168
	global_load_lds_dwordx4 v[206:207], off
	v_lshl_add_u64 v[206:207], s[18:19], 0, v[144:145]
	s_add_i32 m0, s13, 0xe000
	s_nop 0
	global_load_lds_dwordx4 v[206:207], off
	v_add_u32_e32 v253, 0x14000, v133
	ds_read_b128 v[206:209], v253
	ds_read_b128 v[210:213], v253 offset:1024
	ds_read_b128 v[214:217], v253 offset:2048
	ds_read_b128 v[218:221], v253 offset:3072
	s_waitcnt lgkmcnt(0)
	s_waitcnt vmcnt(8)
	s_barrier
	s_nop 0
	v_mfma_f32_16x16x32_bf16 v[124:127], v[150:153], v[168:171], v[124:127]
	v_mfma_f32_16x16x32_bf16 v[120:123], v[160:163], v[168:171], v[120:123]
	v_mfma_f32_16x16x32_bf16 v[116:119], v[150:153], v[176:179], v[116:119]
	v_mfma_f32_16x16x32_bf16 v[108:111], v[160:163], v[176:179], v[108:111]
	v_mfma_f32_16x16x32_bf16 v[100:103], v[150:153], v[190:193], v[100:103]
	v_mfma_f32_16x16x32_bf16 v[92:95], v[160:163], v[190:193], v[92:95]
	v_mfma_f32_16x16x32_bf16 v[84:87], v[150:153], v[198:201], v[84:87]
	v_mfma_f32_16x16x32_bf16 v[76:79], v[160:163], v[198:201], v[76:79]
	v_mfma_f32_16x16x32_bf16 v[124:127], v[156:159], v[172:175], v[124:127]
	v_mfma_f32_16x16x32_bf16 v[120:123], v[164:167], v[172:175], v[120:123]
	v_mfma_f32_16x16x32_bf16 v[116:119], v[156:159], v[186:189], v[116:119]
	v_mfma_f32_16x16x32_bf16 v[108:111], v[164:167], v[186:189], v[108:111]
	v_mfma_f32_16x16x32_bf16 v[100:103], v[156:159], v[194:197], v[100:103]
	v_mfma_f32_16x16x32_bf16 v[92:95], v[164:167], v[194:197], v[92:95]
	v_mfma_f32_16x16x32_bf16 v[84:87], v[156:159], v[202:205], v[84:87]
	v_mfma_f32_16x16x32_bf16 v[76:79], v[164:167], v[202:205], v[76:79]
	v_mfma_f32_16x16x32_bf16 v[112:115], v[206:209], v[168:171], v[112:115]
	v_mfma_f32_16x16x32_bf16 v[104:107], v[214:217], v[168:171], v[104:107]
	v_mfma_f32_16x16x32_bf16 v[96:99], v[206:209], v[176:179], v[96:99]
	v_mfma_f32_16x16x32_bf16 v[88:91], v[214:217], v[176:179], v[88:91]
	v_mfma_f32_16x16x32_bf16 v[80:83], v[206:209], v[190:193], v[80:83]
	v_mfma_f32_16x16x32_bf16 v[72:75], v[214:217], v[190:193], v[72:75]
	v_mfma_f32_16x16x32_bf16 v[68:71], v[206:209], v[198:201], v[68:71]
	v_mfma_f32_16x16x32_bf16 v[64:67], v[214:217], v[198:201], v[64:67]
	v_mfma_f32_16x16x32_bf16 v[112:115], v[210:213], v[172:175], v[112:115]
	v_mfma_f32_16x16x32_bf16 v[104:107], v[218:221], v[172:175], v[104:107]
	v_mfma_f32_16x16x32_bf16 v[96:99], v[210:213], v[186:189], v[96:99]
	v_mfma_f32_16x16x32_bf16 v[88:91], v[218:221], v[186:189], v[88:91]
	v_mfma_f32_16x16x32_bf16 v[80:83], v[210:213], v[194:197], v[80:83]
	v_mfma_f32_16x16x32_bf16 v[72:75], v[218:221], v[194:197], v[72:75]
	v_mfma_f32_16x16x32_bf16 v[68:71], v[210:213], v[202:205], v[68:71]
	v_mfma_f32_16x16x32_bf16 v[64:67], v[218:221], v[202:205], v[64:67]
	s_nop 0
	s_barrier
	s_add_i32 s49, s42, s29
	v_add_u32_e32 v185, s43, v133
	v_lshl_add_u64 v[222:223], s[20:21], 0, v[138:139]
	s_mov_b32 m0, s49
	s_nop 0
	global_load_lds_dwordx4 v[222:223], off
	v_lshl_add_u64 v[222:223], s[20:21], 0, v[134:135]
	s_add_i32 m0, s49, 0x2000
	s_nop 0
	global_load_lds_dwordx4 v[222:223], off
	s_mov_b32 m0, s13
	v_lshl_add_u64 v[222:223], s[24:25], 0, v[140:141]
	ds_read_b128 v[168:171], v155 offset:16384
	ds_read_b128 v[172:175], v155 offset:17408
	ds_read_b128 v[176:179], v155 offset:18432
	ds_read_b128 v[186:189], v155 offset:19456
	ds_read_b128 v[190:193], v155 offset:20480
	ds_read_b128 v[194:197], v155 offset:21504
	ds_read_b128 v[198:201], v155 offset:22528
	ds_read_b128 v[202:205], v155 offset:23552
	global_load_lds_dwordx4 v[222:223], off
	v_lshl_add_u64 v[222:223], s[24:25], 0, v[136:137]
	s_mov_b32 m0, s34
	s_nop 0
	global_load_lds_dwordx4 v[222:223], off
	s_add_u32 s50, s20, 0x4000
	s_addc_u32 s51, s21, 0
	s_add_i32 s49, s43, s29
	v_lshl_add_u64 v[254:255], s[50:51], 0, v[138:139]
	s_mov_b32 m0, s49
	s_nop 0
	global_load_lds_dwordx4 v[254:255], off
	v_lshl_add_u64 v[254:255], s[50:51], 0, v[134:135]
	s_add_i32 m0, s49, 0x2000
	s_nop 0
	global_load_lds_dwordx4 v[254:255], off
	s_waitcnt lgkmcnt(0)
	s_waitcnt vmcnt(8)
	s_barrier
; #define PG8_STAGE(bufoff, gbase, voff) do { _Pragma("unroll") for (int _i = 0; _i < 2; ++_i) \
;         __builtin_amdgcn_global_load_lds((const unsigned*)((const char*)(gbase) + (voff)[_i]), (LAS unsigned*)(lds + (bufoff) + ldsw + _i * 8192), 16, 0, 0); } while (0)
; #define PG8_LDA(dst, b, h) do { _Pragma("unroll") for (int m = 0; m < 4; ++m) _Pragma("unroll") for (int k = 0; k < 2; ++k) dst[m][k] = *(const LAS bf16x8*)(lds + PG8_SA(b, h) + aoff + m * 2048 + k * 1024); } while (0)
; #define PG8_LDB(dst, b, h) do { _Pragma("unroll") for (int n = 0; n < 2; ++n) _Pragma("unroll") for (int k = 0; k < 2; ++k) dst[n][k] = *(const LAS bf16x8*)(lds + PG8_SB(b, h) + boff + n * 2048 + k * 1024); } while (0)
; #define PG8_MMA(ai, bj, At, Bt) do { __builtin_amdgcn_s_setprio(1); _Pragma("unroll") for (int m = 0; m < 4; ++m) _Pragma("unroll") for (int n = 0; n < 2; ++n) _Pragma("unroll") for (int k = 0; k < 2; ++k) \
;         acc[ai][bj][m][n] = __builtin_amdgcn_mfma_f32_16x16x32_bf16(Bt[n][k], At[m][k], acc[ai][bj][m][n], 0, 0, 0); __builtin_amdgcn_s_setprio(0); } while (0)
; #define PG8_WAIT_V(n) asm volatile("s_waitcnt vmcnt(" #n ")" ::: "memory")
; #define PG8_WAIT_L(n) asm volatile("s_waitcnt lgkmcnt(" #n ")" ::: "memory")
; #define PG8_BAR __builtin_amdgcn_s_barrier()
; #define PG8_SCHED __builtin_amdgcn_sched_barrier(0)
; template <class Epi>
; __device__ __forceinline__ void gemm_phase(LAS unsigned char* lds, const Gemm g, const StaticOrder& S, const Epi& E) {
;     ...
;             PG8_BAR; PG8_WAIT_L(0); PG8_MMA(1, 0, At, B0); PG8_BAR; PG8_SCHED;
;             PG8_STAGE(PG8_SB(0, 1), b2 + hstep, voffB);
;             PG8_WAIT_V(6); PG8_BAR; PG8_MMA(1, 1, At, B1); PG8_BAR;
;             PG8_LDB(B0, 1, 0); PG8_SCHED; PG8_LDA(At, 1, 0); PG8_STAGE(PG8_SA(0, 1), a2 + hstep, voffA);
;             PG8_WAIT_L(8); PG8_BAR; PG8_WAIT_L(0); PG8_MMA(0, 0, At, B0); PG8_BAR; PG8_SCHED;
;             PG8_LDB(B1, 1, 1); PG8_STAGE(PG8_SB(1, 0), b3, voffB);
;             PG8_BAR; PG8_WAIT_L(0); PG8_MMA(0, 1, At, B1); PG8_BAR;
;             PG8_LDA(At, 1, 1); PG8_STAGE(PG8_SA(1, 0), a3, voffA);
;             PG8_BAR; PG8_WAIT_L(0); PG8_MMA(1, 0, At, B0); PG8_BAR; PG8_SCHED;
	s_nop 0
	v_mfma_f32_16x16x32_bf16 v[60:63], v[150:153], v[168:171], v[60:63]
	v_mfma_f32_16x16x32_bf16 v[56:59], v[160:163], v[168:171], v[56:59]
	v_mfma_f32_16x16x32_bf16 v[52:55], v[150:153], v[176:179], v[52:55]
	v_mfma_f32_16x16x32_bf16 v[44:47], v[160:163], v[176:179], v[44:47]
	v_mfma_f32_16x16x32_bf16 v[36:39], v[150:153], v[190:193], v[36:39]
	v_mfma_f32_16x16x32_bf16 v[28:31], v[160:163], v[190:193], v[28:31]
	v_mfma_f32_16x16x32_bf16 v[20:23], v[150:153], v[198:201], v[20:23]
	v_mfma_f32_16x16x32_bf16 v[12:15], v[160:163], v[198:201], v[12:15]
	v_mfma_f32_16x16x32_bf16 v[60:63], v[156:159], v[172:175], v[60:63]
	v_mfma_f32_16x16x32_bf16 v[56:59], v[164:167], v[172:175], v[56:59]
	v_mfma_f32_16x16x32_bf16 v[52:55], v[156:159], v[186:189], v[52:55]
	v_mfma_f32_16x16x32_bf16 v[44:47], v[164:167], v[186:189], v[44:47]
	v_mfma_f32_16x16x32_bf16 v[36:39], v[156:159], v[194:197], v[36:39]
	v_mfma_f32_16x16x32_bf16 v[28:31], v[164:167], v[194:197], v[28:31]
	v_mfma_f32_16x16x32_bf16 v[20:23], v[156:159], v[202:205], v[20:23]
	v_mfma_f32_16x16x32_bf16 v[12:15], v[164:167], v[202:205], v[12:15]
	v_mfma_f32_16x16x32_bf16 v[48:51], v[206:209], v[168:171], v[48:51]
	v_mfma_f32_16x16x32_bf16 v[40:43], v[214:217], v[168:171], v[40:43]
	v_mfma_f32_16x16x32_bf16 v[32:35], v[206:209], v[176:179], v[32:35]
	v_mfma_f32_16x16x32_bf16 v[24:27], v[214:217], v[176:179], v[24:27]
	v_mfma_f32_16x16x32_bf16 v[16:19], v[206:209], v[190:193], v[16:19]
	v_mfma_f32_16x16x32_bf16 v[8:11], v[214:217], v[190:193], v[8:11]
	v_mfma_f32_16x16x32_bf16 v[4:7], v[206:209], v[198:201], v[4:7]
	v_mfma_f32_16x16x32_bf16 v[0:3], v[214:217], v[198:201], v[0:3]
	v_mfma_f32_16x16x32_bf16 v[48:51], v[210:213], v[172:175], v[48:51]
	v_mfma_f32_16x16x32_bf16 v[40:43], v[218:221], v[172:175], v[40:43]
	v_mfma_f32_16x16x32_bf16 v[32:35], v[210:213], v[186:189], v[32:35]
	v_mfma_f32_16x16x32_bf16 v[24:27], v[218:221], v[186:189], v[24:27]
	v_mfma_f32_16x16x32_bf16 v[16:19], v[210:213], v[194:197], v[16:19]
	v_mfma_f32_16x16x32_bf16 v[8:11], v[218:221], v[194:197], v[8:11]
	v_mfma_f32_16x16x32_bf16 v[4:7], v[210:213], v[202:205], v[4:7]
	v_mfma_f32_16x16x32_bf16 v[0:3], v[218:221], v[202:205], v[0:3]
	s_nop 0
	s_add_i32 s49, 0, 0x18000
	v_add_u32_e32 v164, s49, v133
	s_barrier
	ds_read_b128 v[150:153], v164
	ds_read_b128 v[156:159], v164 offset:1024
	ds_read_b128 v[160:163], v164 offset:2048
	ds_read_b128 v[164:167], v164 offset:3072
	s_add_u32 s24, s24, 0x4000
	s_addc_u32 s25, s25, 0
	s_mov_b32 m0, s35
	v_lshl_add_u64 v[206:207], s[24:25], 0, v[140:141]
	ds_read_b128 v[168:171], v155 offset:32768
	ds_read_b128 v[172:175], v155 offset:33792
	ds_read_b128 v[176:179], v155 offset:34816
	ds_read_b128 v[186:189], v155 offset:35840
	ds_read_b128 v[190:193], v155 offset:36864
	ds_read_b128 v[194:197], v155 offset:37888
	ds_read_b128 v[198:201], v155 offset:38912
	ds_read_b128 v[202:205], v155 offset:39936
	global_load_lds_dwordx4 v[206:207], off
	v_lshl_add_u64 v[206:207], s[24:25], 0, v[136:137]
	s_mov_b32 m0, s36
	s_nop 0
	global_load_lds_dwordx4 v[206:207], off
	v_add_u32_e32 v253, 0x1c000, v133
	ds_read_b128 v[206:209], v253
	ds_read_b128 v[210:213], v253 offset:1024
	ds_read_b128 v[214:217], v253 offset:2048
	ds_read_b128 v[218:221], v253 offset:3072
	s_waitcnt lgkmcnt(0)
	s_waitcnt vmcnt(8)
	s_barrier
	s_nop 0
	v_mfma_f32_16x16x32_bf16 v[124:127], v[150:153], v[168:171], v[124:127]
	v_mfma_f32_16x16x32_bf16 v[120:123], v[160:163], v[168:171], v[120:123]
	v_mfma_f32_16x16x32_bf16 v[116:119], v[150:153], v[176:179], v[116:119]
	v_mfma_f32_16x16x32_bf16 v[108:111], v[160:163], v[176:179], v[108:111]
	v_mfma_f32_16x16x32_bf16 v[100:103], v[150:153], v[190:193], v[100:103]
	v_mfma_f32_16x16x32_bf16 v[92:95], v[160:163], v[190:193], v[92:95]
	v_mfma_f32_16x16x32_bf16 v[84:87], v[150:153], v[198:201], v[84:87]
	v_mfma_f32_16x16x32_bf16 v[76:79], v[160:163], v[198:201], v[76:79]
	v_mfma_f32_16x16x32_bf16 v[124:127], v[156:159], v[172:175], v[124:127]
	v_mfma_f32_16x16x32_bf16 v[120:123], v[164:167], v[172:175], v[120:123]
	v_mfma_f32_16x16x32_bf16 v[116:119], v[156:159], v[186:189], v[116:119]
	v_mfma_f32_16x16x32_bf16 v[108:111], v[164:167], v[186:189], v[108:111]
	v_mfma_f32_16x16x32_bf16 v[100:103], v[156:159], v[194:197], v[100:103]
	v_mfma_f32_16x16x32_bf16 v[92:95], v[164:167], v[194:197], v[92:95]
	v_mfma_f32_16x16x32_bf16 v[84:87], v[156:159], v[202:205], v[84:87]
	v_mfma_f32_16x16x32_bf16 v[76:79], v[164:167], v[202:205], v[76:79]
	v_mfma_f32_16x16x32_bf16 v[112:115], v[206:209], v[168:171], v[112:115]
	v_mfma_f32_16x16x32_bf16 v[104:107], v[214:217], v[168:171], v[104:107]
	v_mfma_f32_16x16x32_bf16 v[96:99], v[206:209], v[176:179], v[96:99]
	v_mfma_f32_16x16x32_bf16 v[88:91], v[214:217], v[176:179], v[88:91]
	v_mfma_f32_16x16x32_bf16 v[80:83], v[206:209], v[190:193], v[80:83]
	v_mfma_f32_16x16x32_bf16 v[72:75], v[214:217], v[190:193], v[72:75]
	v_mfma_f32_16x16x32_bf16 v[68:71], v[206:209], v[198:201], v[68:71]
	v_mfma_f32_16x16x32_bf16 v[64:67], v[214:217], v[198:201], v[64:67]
	v_mfma_f32_16x16x32_bf16 v[112:115], v[210:213], v[172:175], v[112:115]
	v_mfma_f32_16x16x32_bf16 v[104:107], v[218:221], v[172:175], v[104:107]
	v_mfma_f32_16x16x32_bf16 v[96:99], v[210:213], v[186:189], v[96:99]
	v_mfma_f32_16x16x32_bf16 v[88:91], v[218:221], v[186:189], v[88:91]
	v_mfma_f32_16x16x32_bf16 v[80:83], v[210:213], v[194:197], v[80:83]
	v_mfma_f32_16x16x32_bf16 v[72:75], v[218:221], v[194:197], v[72:75]
	v_mfma_f32_16x16x32_bf16 v[68:71], v[210:213], v[202:205], v[68:71]
	v_mfma_f32_16x16x32_bf16 v[64:67], v[218:221], v[202:205], v[64:67]
	s_nop 0
	s_barrier
; #define PG8_STAGE(bufoff, gbase, voff) do { _Pragma("unroll") for (int _i = 0; _i < 2; ++_i) \
;         __builtin_amdgcn_global_load_lds((const unsigned*)((const char*)(gbase) + (voff)[_i]), (LAS unsigned*)(lds + (bufoff) + ldsw + _i * 8192), 16, 0, 0); } while (0)
; #define PG8_LDA(dst, b, h) do { _Pragma("unroll") for (int m = 0; m < 4; ++m) _Pragma("unroll") for (int k = 0; k < 2; ++k) dst[m][k] = *(const LAS bf16x8*)(lds + PG8_SA(b, h) + aoff + m * 2048 + k * 1024); } while (0)
; #define PG8_LDB(dst, b, h) do { _Pragma("unroll") for (int n = 0; n < 2; ++n) _Pragma("unroll") for (int k = 0; k < 2; ++k) dst[n][k] = *(const LAS bf16x8*)(lds + PG8_SB(b, h) + boff + n * 2048 + k * 1024); } while (0)
; #define PG8_MMA(ai, bj, At, Bt) do { __builtin_amdgcn_s_setprio(1); _Pragma("unroll") for (int m = 0; m < 4; ++m) _Pragma("unroll") for (int n = 0; n < 2; ++n) _Pragma("unroll") for (int k = 0; k < 2; ++k) \
;         acc[ai][bj][m][n] = __builtin_amdgcn_mfma_f32_16x16x32_bf16(Bt[n][k], At[m][k], acc[ai][bj][m][n], 0, 0, 0); __builtin_amdgcn_s_setprio(0); } while (0)
; #define PG8_WAIT_V(n) asm volatile("s_waitcnt vmcnt(" #n ")" ::: "memory")
; #define PG8_WAIT_L(n) asm volatile("s_waitcnt lgkmcnt(" #n ")" ::: "memory")
; #define PG8_BAR __builtin_amdgcn_s_barrier()
; #define PG8_SCHED __builtin_amdgcn_sched_barrier(0)
; template <class Epi>
; __device__ __forceinline__ void gemm_phase(LAS unsigned char* lds, const Gemm g, const StaticOrder& S, const Epi& E) {
;     ...
;             PG8_LDB(B1, 1, 1); PG8_STAGE(PG8_SB(1, 0), b3, voffB);
;             PG8_BAR; PG8_WAIT_L(0); PG8_MMA(0, 1, At, B1); PG8_BAR;
;             PG8_LDA(At, 1, 1); PG8_STAGE(PG8_SA(1, 0), a3, voffA);
;             PG8_BAR; PG8_WAIT_L(0); PG8_MMA(1, 0, At, B0); PG8_BAR; PG8_SCHED;
;             PG8_STAGE(PG8_SB(1, 1), b3 + hstep, voffB);
;             PG8_WAIT_V(6); PG8_BAR; PG8_MMA(1, 1, At, B1); PG8_BAR;
;         }
	s_add_i32 s50, 0, 0x1c000
	s_add_u32 s24, s20, 0xa0000
	s_addc_u32 s25, s21, 0
	s_add_i32 s49, s49, s29
	v_add_u32_e32 v185, s50, v133
	v_lshl_add_u64 v[222:223], s[24:25], 0, v[138:139]
	s_mov_b32 m0, s49
	s_nop 0
	global_load_lds_dwordx4 v[222:223], off
	v_lshl_add_u64 v[222:223], s[24:25], 0, v[134:135]
	s_add_i32 m0, s49, 0x2000
	s_nop 0
	global_load_lds_dwordx4 v[222:223], off
	s_mov_b32 m0, s38
	v_lshl_add_u64 v[222:223], s[22:23], 0, v[140:141]
	ds_read_b128 v[168:171], v155 offset:49152
	ds_read_b128 v[172:175], v155 offset:50176
	ds_read_b128 v[176:179], v155 offset:51200
	ds_read_b128 v[186:189], v155 offset:52224
	ds_read_b128 v[190:193], v155 offset:53248
	ds_read_b128 v[194:197], v155 offset:54272
	ds_read_b128 v[198:201], v155 offset:55296
	ds_read_b128 v[202:205], v155 offset:56320
	global_load_lds_dwordx4 v[222:223], off
	v_lshl_add_u64 v[222:223], s[22:23], 0, v[136:137]
	s_mov_b32 m0, s39
	s_nop 0
	global_load_lds_dwordx4 v[222:223], off
	s_add_u32 s20, s20, 0xa4000
	s_addc_u32 s21, s21, 0
	s_add_i32 s22, s50, s29
	v_lshl_add_u64 v[254:255], s[20:21], 0, v[138:139]
	s_mov_b32 m0, s22
	s_nop 0
	global_load_lds_dwordx4 v[254:255], off
	v_lshl_add_u64 v[254:255], s[20:21], 0, v[134:135]
	s_add_i32 m0, s22, 0x2000
	s_nop 0
	global_load_lds_dwordx4 v[254:255], off
	s_waitcnt lgkmcnt(0)
	s_waitcnt vmcnt(8)
	s_barrier
	s_nop 0
	v_mfma_f32_16x16x32_bf16 v[60:63], v[150:153], v[168:171], v[60:63]
	v_mfma_f32_16x16x32_bf16 v[56:59], v[160:163], v[168:171], v[56:59]
	v_mfma_f32_16x16x32_bf16 v[52:55], v[150:153], v[176:179], v[52:55]
	v_mfma_f32_16x16x32_bf16 v[44:47], v[160:163], v[176:179], v[44:47]
	v_mfma_f32_16x16x32_bf16 v[36:39], v[150:153], v[190:193], v[36:39]
	v_mfma_f32_16x16x32_bf16 v[28:31], v[160:163], v[190:193], v[28:31]
	v_mfma_f32_16x16x32_bf16 v[20:23], v[150:153], v[198:201], v[20:23]
	v_mfma_f32_16x16x32_bf16 v[12:15], v[160:163], v[198:201], v[12:15]
	v_mfma_f32_16x16x32_bf16 v[60:63], v[156:159], v[172:175], v[60:63]
	v_mfma_f32_16x16x32_bf16 v[56:59], v[164:167], v[172:175], v[56:59]
	v_mfma_f32_16x16x32_bf16 v[52:55], v[156:159], v[186:189], v[52:55]
	v_mfma_f32_16x16x32_bf16 v[44:47], v[164:167], v[186:189], v[44:47]
	v_mfma_f32_16x16x32_bf16 v[36:39], v[156:159], v[194:197], v[36:39]
	v_mfma_f32_16x16x32_bf16 v[28:31], v[164:167], v[194:197], v[28:31]
	v_mfma_f32_16x16x32_bf16 v[20:23], v[156:159], v[202:205], v[20:23]
	v_mfma_f32_16x16x32_bf16 v[12:15], v[164:167], v[202:205], v[12:15]
	v_mfma_f32_16x16x32_bf16 v[48:51], v[206:209], v[168:171], v[48:51]
	v_mfma_f32_16x16x32_bf16 v[40:43], v[214:217], v[168:171], v[40:43]
	v_mfma_f32_16x16x32_bf16 v[32:35], v[206:209], v[176:179], v[32:35]
	v_mfma_f32_16x16x32_bf16 v[24:27], v[214:217], v[176:179], v[24:27]
	v_mfma_f32_16x16x32_bf16 v[16:19], v[206:209], v[190:193], v[16:19]
	v_mfma_f32_16x16x32_bf16 v[8:11], v[214:217], v[190:193], v[8:11]
	v_mfma_f32_16x16x32_bf16 v[4:7], v[206:209], v[198:201], v[4:7]
	v_mfma_f32_16x16x32_bf16 v[0:3], v[214:217], v[198:201], v[0:3]
	v_mfma_f32_16x16x32_bf16 v[48:51], v[210:213], v[172:175], v[48:51]
	v_mfma_f32_16x16x32_bf16 v[40:43], v[218:221], v[172:175], v[40:43]
	v_mfma_f32_16x16x32_bf16 v[32:35], v[210:213], v[186:189], v[32:35]
	v_mfma_f32_16x16x32_bf16 v[24:27], v[218:221], v[186:189], v[24:27]
	v_mfma_f32_16x16x32_bf16 v[16:19], v[210:213], v[194:197], v[16:19]
	v_mfma_f32_16x16x32_bf16 v[8:11], v[218:221], v[194:197], v[8:11]
	v_mfma_f32_16x16x32_bf16 v[4:7], v[210:213], v[202:205], v[4:7]
	v_mfma_f32_16x16x32_bf16 v[0:3], v[218:221], v[202:205], v[0:3]
	s_nop 0
	s_add_i32 s1, s1, 2
	s_add_u32 s16, s16, 0x140000
	s_addc_u32 s17, s17, 0
	s_add_u32 s18, s18, 0x800000
	s_addc_u32 s19, s19, 0
	s_cmp_gt_u32 s1, 29
	s_barrier
	s_cbranch_scc1 .LBB0_559

; #define PG8_STAGE(bufoff, gbase, voff) do { _Pragma("unroll") for (int _i = 0; _i < 2; ++_i) \
;         __builtin_amdgcn_global_load_lds((const unsigned*)((const char*)(gbase) + (voff)[_i]), (LAS unsigned*)(lds + (bufoff) + ldsw + _i * 8192), 16, 0, 0); } while (0)
; #define PG8_LDA(dst, b, h) do { _Pragma("unroll") for (int m = 0; m < 4; ++m) _Pragma("unroll") for (int k = 0; k < 2; ++k) dst[m][k] = *(const LAS bf16x8*)(lds + PG8_SA(b, h) + aoff + m * 2048 + k * 1024); } while (0)
; #define PG8_LDB(dst, b, h) do { _Pragma("unroll") for (int n = 0; n < 2; ++n) _Pragma("unroll") for (int k = 0; k < 2; ++k) dst[n][k] = *(const LAS bf16x8*)(lds + PG8_SB(b, h) + boff + n * 2048 + k * 1024); } while (0)
; #define PG8_MMA(ai, bj, At, Bt) do { __builtin_amdgcn_s_setprio(1); _Pragma("unroll") for (int m = 0; m < 4; ++m) _Pragma("unroll") for (int n = 0; n < 2; ++n) _Pragma("unroll") for (int k = 0; k < 2; ++k) \
;         acc[ai][bj][m][n] = __builtin_amdgcn_mfma_f32_16x16x32_bf16(Bt[n][k], At[m][k], acc[ai][bj][m][n], 0, 0, 0); __builtin_amdgcn_s_setprio(0); } while (0)
; #define PG8_WAIT_V(n) asm volatile("s_waitcnt vmcnt(" #n ")" ::: "memory")
; #define PG8_WAIT_L(n) asm volatile("s_waitcnt lgkmcnt(" #n ")" ::: "memory")
; template <class Epi>
; __device__ __forceinline__ void gemm_phase(LAS unsigned char* lds, const Gemm g, const StaticOrder& S, const Epi& E) {
;     ...
;         for (int t = 0; t < nt; t += 2) {
;             const bool last = (t == nt - 2);
;             const char* a1 = cA + (size_t)(t + 1) * kstepA;
;             const char* a2 = last ? nA : cA + (size_t)(t + 2) * kstepA; const char* b2 = last ? nB : cB + (size_t)(t + 2) * kstepB;
;             const char* a3 = a2 + kstepA; const char* b3 = b2 + kstepB;
;             PG8_LDB(B0, 0, 0); PG8_SCHED; PG8_LDA(At, 0, 0); PG8_STAGE(PG8_SA(1, 1), a1 + hstep, voffA);
;             PG8_WAIT_L(8); PG8_BAR; PG8_WAIT_L(0); PG8_MMA(0, 0, At, B0); PG8_BAR; PG8_SCHED;
;             PG8_LDB(B1, 0, 1); PG8_STAGE(PG8_SB(0, 0), b2, voffB);
;             PG8_BAR; PG8_WAIT_L(0); PG8_MMA(0, 1, At, B1); PG8_BAR;
;             PG8_LDA(At, 0, 1); PG8_STAGE(PG8_SA(0, 0), a2, voffA);
;             PG8_BAR; PG8_WAIT_L(0); PG8_MMA(1, 0, At, B0); PG8_BAR; PG8_SCHED;
;             PG8_STAGE(PG8_SB(0, 1), b2 + hstep, voffB);
;             PG8_WAIT_V(6); PG8_BAR; PG8_MMA(1, 1, At, B1); PG8_BAR;
.LBB0_762:
	ds_read_b128 v[156:159], v153
	ds_read_b128 v[160:163], v153 offset:1024
	ds_read_b128 v[164:167], v153 offset:2048
	ds_read_b128 v[168:171], v153 offset:3072
	s_add_u32 s26, s24, 0x3fc000
	s_addc_u32 s27, s25, 0
	s_cmp_eq_u32 s62, 28
	s_cselect_b32 s30, s58, s26
	s_cselect_b32 s31, s17, s27
	s_cselect_b32 s27, s15, s61
	s_cselect_b32 s26, s59, s60
	s_add_u32 s28, s30, 0x400000
	s_addc_u32 s29, s31, 0
	v_lshl_add_u64 v[150:151], s[24:25], 0, v[142:143]
	s_add_i32 m0, s23, 0xc000
	ds_read_b128 v[172:175], v154
	ds_read_b128 v[176:179], v154 offset:1024
	ds_read_b128 v[184:187], v154 offset:2048
	ds_read_b128 v[188:191], v154 offset:3072
	ds_read_b128 v[192:195], v154 offset:4096
	ds_read_b128 v[196:199], v154 offset:5120
	ds_read_b128 v[200:203], v154 offset:6144
	ds_read_b128 v[204:207], v154 offset:7168
	global_load_lds_dwordx4 v[150:151], off
	v_lshl_add_u64 v[150:151], s[24:25], 0, v[144:145]
	s_add_i32 m0, s23, 0xe000
	s_nop 0
	global_load_lds_dwordx4 v[150:151], off
	ds_read_b128 v[208:211], v155
	ds_read_b128 v[212:215], v155 offset:1024
	ds_read_b128 v[216:219], v155 offset:2048
	ds_read_b128 v[220:223], v155 offset:3072
	s_waitcnt lgkmcnt(0)
	s_waitcnt vmcnt(8)
	s_barrier
	s_nop 0
	v_mfma_f32_16x16x32_bf16 v[124:127], v[156:159], v[172:175], v[124:127]
	v_mfma_f32_16x16x32_bf16 v[120:123], v[164:167], v[172:175], v[120:123]
	v_mfma_f32_16x16x32_bf16 v[112:115], v[156:159], v[184:187], v[112:115]
	v_mfma_f32_16x16x32_bf16 v[104:107], v[164:167], v[184:187], v[104:107]
	v_mfma_f32_16x16x32_bf16 v[96:99], v[156:159], v[192:195], v[96:99]
	v_mfma_f32_16x16x32_bf16 v[88:91], v[164:167], v[192:195], v[88:91]
	v_mfma_f32_16x16x32_bf16 v[80:83], v[156:159], v[200:203], v[80:83]
	v_mfma_f32_16x16x32_bf16 v[72:75], v[164:167], v[200:203], v[72:75]
	v_mfma_f32_16x16x32_bf16 v[124:127], v[160:163], v[176:179], v[124:127]
	v_mfma_f32_16x16x32_bf16 v[120:123], v[168:171], v[176:179], v[120:123]
	v_mfma_f32_16x16x32_bf16 v[112:115], v[160:163], v[188:191], v[112:115]
	v_mfma_f32_16x16x32_bf16 v[104:107], v[168:171], v[188:191], v[104:107]
	v_mfma_f32_16x16x32_bf16 v[96:99], v[160:163], v[196:199], v[96:99]
	v_mfma_f32_16x16x32_bf16 v[88:91], v[168:171], v[196:199], v[88:91]
	v_mfma_f32_16x16x32_bf16 v[80:83], v[160:163], v[204:207], v[80:83]
	v_mfma_f32_16x16x32_bf16 v[72:75], v[168:171], v[204:207], v[72:75]
	v_mfma_f32_16x16x32_bf16 v[116:119], v[208:211], v[172:175], v[116:119]
	v_mfma_f32_16x16x32_bf16 v[108:111], v[216:219], v[172:175], v[108:111]
	v_mfma_f32_16x16x32_bf16 v[100:103], v[208:211], v[184:187], v[100:103]
	v_mfma_f32_16x16x32_bf16 v[92:95], v[216:219], v[184:187], v[92:95]
	v_mfma_f32_16x16x32_bf16 v[84:87], v[208:211], v[192:195], v[84:87]
	v_mfma_f32_16x16x32_bf16 v[76:79], v[216:219], v[192:195], v[76:79]
	v_mfma_f32_16x16x32_bf16 v[68:71], v[208:211], v[200:203], v[68:71]
	v_mfma_f32_16x16x32_bf16 v[64:67], v[216:219], v[200:203], v[64:67]
	v_mfma_f32_16x16x32_bf16 v[116:119], v[212:215], v[176:179], v[116:119]
	v_mfma_f32_16x16x32_bf16 v[108:111], v[220:223], v[176:179], v[108:111]
	v_mfma_f32_16x16x32_bf16 v[100:103], v[212:215], v[188:191], v[100:103]
	v_mfma_f32_16x16x32_bf16 v[92:95], v[220:223], v[188:191], v[92:95]
	v_mfma_f32_16x16x32_bf16 v[84:87], v[212:215], v[196:199], v[84:87]
	v_mfma_f32_16x16x32_bf16 v[76:79], v[220:223], v[196:199], v[76:79]
	v_mfma_f32_16x16x32_bf16 v[68:71], v[212:215], v[204:207], v[68:71]
	v_mfma_f32_16x16x32_bf16 v[64:67], v[220:223], v[204:207], v[64:67]
	s_nop 0
	s_barrier
	s_add_i32 s63, s49, s38
	v_lshl_add_u64 v[150:151], s[26:27], 0, v[136:137]
	s_mov_b32 m0, s63
	s_nop 0
	global_load_lds_dwordx4 v[150:151], off
	v_lshl_add_u64 v[150:151], s[26:27], 0, v[140:141]
	s_add_i32 m0, s63, 0x2000
	s_nop 0
	global_load_lds_dwordx4 v[150:151], off
	s_mov_b32 m0, s23
	v_lshl_add_u64 v[150:151], s[30:31], 0, v[134:135]
	ds_read_b128 v[172:175], v154 offset:16384
	ds_read_b128 v[176:179], v154 offset:17408
	ds_read_b128 v[184:187], v154 offset:18432
	ds_read_b128 v[188:191], v154 offset:19456
	ds_read_b128 v[192:195], v154 offset:20480
	ds_read_b128 v[196:199], v154 offset:21504
	ds_read_b128 v[200:203], v154 offset:22528
	ds_read_b128 v[204:207], v154 offset:23552
	global_load_lds_dwordx4 v[150:151], off
	v_lshl_add_u64 v[150:151], s[30:31], 0, v[138:139]
	s_mov_b32 m0, s39
	s_nop 0
	global_load_lds_dwordx4 v[150:151], off
	s_add_u32 s64, s26, 0x4000
	s_addc_u32 s65, s27, 0
	s_add_i32 s63, s50, s38
	v_lshl_add_u64 v[150:151], s[64:65], 0, v[136:137]
	s_mov_b32 m0, s63
	s_nop 0
	global_load_lds_dwordx4 v[150:151], off
	v_lshl_add_u64 v[150:151], s[64:65], 0, v[140:141]
	s_add_i32 m0, s63, 0x2000
	s_nop 0
	global_load_lds_dwordx4 v[150:151], off
	s_waitcnt lgkmcnt(0)
	s_waitcnt vmcnt(8)
	s_barrier
; #define PG8_STAGE(bufoff, gbase, voff) do { _Pragma("unroll") for (int _i = 0; _i < 2; ++_i) \
;         __builtin_amdgcn_global_load_lds((const unsigned*)((const char*)(gbase) + (voff)[_i]), (LAS unsigned*)(lds + (bufoff) + ldsw + _i * 8192), 16, 0, 0); } while (0)
; #define PG8_LDA(dst, b, h) do { _Pragma("unroll") for (int m = 0; m < 4; ++m) _Pragma("unroll") for (int k = 0; k < 2; ++k) dst[m][k] = *(const LAS bf16x8*)(lds + PG8_SA(b, h) + aoff + m * 2048 + k * 1024); } while (0)
; #define PG8_LDB(dst, b, h) do { _Pragma("unroll") for (int n = 0; n < 2; ++n) _Pragma("unroll") for (int k = 0; k < 2; ++k) dst[n][k] = *(const LAS bf16x8*)(lds + PG8_SB(b, h) + boff + n * 2048 + k * 1024); } while (0)
; #define PG8_MMA(ai, bj, At, Bt) do { __builtin_amdgcn_s_setprio(1); _Pragma("unroll") for (int m = 0; m < 4; ++m) _Pragma("unroll") for (int n = 0; n < 2; ++n) _Pragma("unroll") for (int k = 0; k < 2; ++k) \
;         acc[ai][bj][m][n] = __builtin_amdgcn_mfma_f32_16x16x32_bf16(Bt[n][k], At[m][k], acc[ai][bj][m][n], 0, 0, 0); __builtin_amdgcn_s_setprio(0); } while (0)
; #define PG8_WAIT_V(n) asm volatile("s_waitcnt vmcnt(" #n ")" ::: "memory")
; #define PG8_WAIT_L(n) asm volatile("s_waitcnt lgkmcnt(" #n ")" ::: "memory")
; #define PG8_BAR __builtin_amdgcn_s_barrier()
; #define PG8_SCHED __builtin_amdgcn_sched_barrier(0)
; template <class Epi>
; __device__ __forceinline__ void gemm_phase(LAS unsigned char* lds, const Gemm g, const StaticOrder& S, const Epi& E) {
;     ...
;             PG8_BAR; PG8_WAIT_L(0); PG8_MMA(1, 0, At, B0); PG8_BAR; PG8_SCHED;
;             PG8_STAGE(PG8_SB(0, 1), b2 + hstep, voffB);
;             PG8_WAIT_V(6); PG8_BAR; PG8_MMA(1, 1, At, B1); PG8_BAR;
;             PG8_LDB(B0, 1, 0); PG8_SCHED; PG8_LDA(At, 1, 0); PG8_STAGE(PG8_SA(0, 1), a2 + hstep, voffA);
;             PG8_WAIT_L(8); PG8_BAR; PG8_WAIT_L(0); PG8_MMA(0, 0, At, B0); PG8_BAR; PG8_SCHED;
;             PG8_LDB(B1, 1, 1); PG8_STAGE(PG8_SB(1, 0), b3, voffB);
;             PG8_BAR; PG8_WAIT_L(0); PG8_MMA(0, 1, At, B1); PG8_BAR;
;             PG8_LDA(At, 1, 1); PG8_STAGE(PG8_SA(1, 0), a3, voffA);
;             PG8_BAR; PG8_WAIT_L(0); PG8_MMA(1, 0, At, B0); PG8_BAR; PG8_SCHED;
	s_nop 0
	v_mfma_f32_16x16x32_bf16 v[60:63], v[156:159], v[172:175], v[60:63]
	v_mfma_f32_16x16x32_bf16 v[56:59], v[164:167], v[172:175], v[56:59]
	v_mfma_f32_16x16x32_bf16 v[52:55], v[156:159], v[184:187], v[52:55]
	v_mfma_f32_16x16x32_bf16 v[44:47], v[164:167], v[184:187], v[44:47]
	v_mfma_f32_16x16x32_bf16 v[36:39], v[156:159], v[192:195], v[36:39]
	v_mfma_f32_16x16x32_bf16 v[28:31], v[164:167], v[192:195], v[28:31]
	v_mfma_f32_16x16x32_bf16 v[20:23], v[156:159], v[200:203], v[20:23]
	v_mfma_f32_16x16x32_bf16 v[12:15], v[164:167], v[200:203], v[12:15]
	v_mfma_f32_16x16x32_bf16 v[60:63], v[160:163], v[176:179], v[60:63]
	v_mfma_f32_16x16x32_bf16 v[56:59], v[168:171], v[176:179], v[56:59]
	v_mfma_f32_16x16x32_bf16 v[52:55], v[160:163], v[188:191], v[52:55]
	v_mfma_f32_16x16x32_bf16 v[44:47], v[168:171], v[188:191], v[44:47]
	v_mfma_f32_16x16x32_bf16 v[36:39], v[160:163], v[196:199], v[36:39]
	v_mfma_f32_16x16x32_bf16 v[28:31], v[168:171], v[196:199], v[28:31]
	v_mfma_f32_16x16x32_bf16 v[20:23], v[160:163], v[204:207], v[20:23]
	v_mfma_f32_16x16x32_bf16 v[12:15], v[168:171], v[204:207], v[12:15]
	v_mfma_f32_16x16x32_bf16 v[48:51], v[208:211], v[172:175], v[48:51]
	v_mfma_f32_16x16x32_bf16 v[40:43], v[216:219], v[172:175], v[40:43]
	v_mfma_f32_16x16x32_bf16 v[32:35], v[208:211], v[184:187], v[32:35]
	v_mfma_f32_16x16x32_bf16 v[24:27], v[216:219], v[184:187], v[24:27]
	v_mfma_f32_16x16x32_bf16 v[16:19], v[208:211], v[192:195], v[16:19]
	v_mfma_f32_16x16x32_bf16 v[8:11], v[216:219], v[192:195], v[8:11]
	v_mfma_f32_16x16x32_bf16 v[4:7], v[208:211], v[200:203], v[4:7]
	v_mfma_f32_16x16x32_bf16 v[0:3], v[216:219], v[200:203], v[0:3]
	v_mfma_f32_16x16x32_bf16 v[48:51], v[212:215], v[176:179], v[48:51]
	v_mfma_f32_16x16x32_bf16 v[40:43], v[220:223], v[176:179], v[40:43]
	v_mfma_f32_16x16x32_bf16 v[32:35], v[212:215], v[188:191], v[32:35]
	v_mfma_f32_16x16x32_bf16 v[24:27], v[220:223], v[188:191], v[24:27]
	v_mfma_f32_16x16x32_bf16 v[16:19], v[212:215], v[196:199], v[16:19]
	v_mfma_f32_16x16x32_bf16 v[8:11], v[220:223], v[196:199], v[8:11]
	v_mfma_f32_16x16x32_bf16 v[4:7], v[212:215], v[204:207], v[4:7]
	v_mfma_f32_16x16x32_bf16 v[0:3], v[220:223], v[204:207], v[0:3]
	s_nop 0
	s_add_i32 s63, 0, 0x18000
	v_add_u32_e32 v150, s63, v133
	s_barrier
	ds_read_b128 v[156:159], v150
	ds_read_b128 v[160:163], v150 offset:1024
	ds_read_b128 v[164:167], v150 offset:2048
	ds_read_b128 v[168:171], v150 offset:3072
	s_add_u32 s30, s30, 0x4000
	s_addc_u32 s31, s31, 0
	s_mov_b32 m0, s40
	v_lshl_add_u64 v[150:151], s[30:31], 0, v[134:135]
	ds_read_b128 v[172:175], v154 offset:32768
	ds_read_b128 v[176:179], v154 offset:33792
	ds_read_b128 v[184:187], v154 offset:34816
	ds_read_b128 v[188:191], v154 offset:35840
	ds_read_b128 v[192:195], v154 offset:36864
	ds_read_b128 v[196:199], v154 offset:37888
	ds_read_b128 v[200:203], v154 offset:38912
	ds_read_b128 v[204:207], v154 offset:39936
	global_load_lds_dwordx4 v[150:151], off
	v_lshl_add_u64 v[150:151], s[30:31], 0, v[138:139]
	s_mov_b32 m0, s41
	s_nop 0
	global_load_lds_dwordx4 v[150:151], off
	v_add_u32_e32 v253, 0x1c000, v133
	ds_read_b128 v[208:211], v253
	ds_read_b128 v[212:215], v253 offset:1024
	ds_read_b128 v[216:219], v253 offset:2048
	ds_read_b128 v[220:223], v253 offset:3072
	s_waitcnt lgkmcnt(0)
	s_waitcnt vmcnt(8)
	s_barrier
	s_nop 0
	v_mfma_f32_16x16x32_bf16 v[124:127], v[156:159], v[172:175], v[124:127]
	v_mfma_f32_16x16x32_bf16 v[120:123], v[164:167], v[172:175], v[120:123]
	v_mfma_f32_16x16x32_bf16 v[112:115], v[156:159], v[184:187], v[112:115]
	v_mfma_f32_16x16x32_bf16 v[104:107], v[164:167], v[184:187], v[104:107]
	v_mfma_f32_16x16x32_bf16 v[96:99], v[156:159], v[192:195], v[96:99]
	v_mfma_f32_16x16x32_bf16 v[88:91], v[164:167], v[192:195], v[88:91]
	v_mfma_f32_16x16x32_bf16 v[80:83], v[156:159], v[200:203], v[80:83]
	v_mfma_f32_16x16x32_bf16 v[72:75], v[164:167], v[200:203], v[72:75]
	v_mfma_f32_16x16x32_bf16 v[124:127], v[160:163], v[176:179], v[124:127]
	v_mfma_f32_16x16x32_bf16 v[120:123], v[168:171], v[176:179], v[120:123]
	v_mfma_f32_16x16x32_bf16 v[112:115], v[160:163], v[188:191], v[112:115]
	v_mfma_f32_16x16x32_bf16 v[104:107], v[168:171], v[188:191], v[104:107]
	v_mfma_f32_16x16x32_bf16 v[96:99], v[160:163], v[196:199], v[96:99]
	v_mfma_f32_16x16x32_bf16 v[88:91], v[168:171], v[196:199], v[88:91]
	v_mfma_f32_16x16x32_bf16 v[80:83], v[160:163], v[204:207], v[80:83]
	v_mfma_f32_16x16x32_bf16 v[72:75], v[168:171], v[204:207], v[72:75]
	v_mfma_f32_16x16x32_bf16 v[116:119], v[208:211], v[172:175], v[116:119]
	v_mfma_f32_16x16x32_bf16 v[108:111], v[216:219], v[172:175], v[108:111]
	v_mfma_f32_16x16x32_bf16 v[100:103], v[208:211], v[184:187], v[100:103]
	v_mfma_f32_16x16x32_bf16 v[92:95], v[216:219], v[184:187], v[92:95]
	v_mfma_f32_16x16x32_bf16 v[84:87], v[208:211], v[192:195], v[84:87]
	v_mfma_f32_16x16x32_bf16 v[76:79], v[216:219], v[192:195], v[76:79]
	v_mfma_f32_16x16x32_bf16 v[68:71], v[208:211], v[200:203], v[68:71]
	v_mfma_f32_16x16x32_bf16 v[64:67], v[216:219], v[200:203], v[64:67]
	v_mfma_f32_16x16x32_bf16 v[116:119], v[212:215], v[176:179], v[116:119]
	v_mfma_f32_16x16x32_bf16 v[108:111], v[220:223], v[176:179], v[108:111]
	v_mfma_f32_16x16x32_bf16 v[100:103], v[212:215], v[188:191], v[100:103]
	v_mfma_f32_16x16x32_bf16 v[92:95], v[220:223], v[188:191], v[92:95]
	v_mfma_f32_16x16x32_bf16 v[84:87], v[212:215], v[196:199], v[84:87]
	v_mfma_f32_16x16x32_bf16 v[76:79], v[220:223], v[196:199], v[76:79]
	v_mfma_f32_16x16x32_bf16 v[68:71], v[212:215], v[204:207], v[68:71]
	v_mfma_f32_16x16x32_bf16 v[64:67], v[220:223], v[204:207], v[64:67]
	s_nop 0
	s_barrier
; #define PG8_STAGE(bufoff, gbase, voff) do { _Pragma("unroll") for (int _i = 0; _i < 2; ++_i) \
;         __builtin_amdgcn_global_load_lds((const unsigned*)((const char*)(gbase) + (voff)[_i]), (LAS unsigned*)(lds + (bufoff) + ldsw + _i * 8192), 16, 0, 0); } while (0)
; #define PG8_LDA(dst, b, h) do { _Pragma("unroll") for (int m = 0; m < 4; ++m) _Pragma("unroll") for (int k = 0; k < 2; ++k) dst[m][k] = *(const LAS bf16x8*)(lds + PG8_SA(b, h) + aoff + m * 2048 + k * 1024); } while (0)
; #define PG8_LDB(dst, b, h) do { _Pragma("unroll") for (int n = 0; n < 2; ++n) _Pragma("unroll") for (int k = 0; k < 2; ++k) dst[n][k] = *(const LAS bf16x8*)(lds + PG8_SB(b, h) + boff + n * 2048 + k * 1024); } while (0)
; #define PG8_MMA(ai, bj, At, Bt) do { __builtin_amdgcn_s_setprio(1); _Pragma("unroll") for (int m = 0; m < 4; ++m) _Pragma("unroll") for (int n = 0; n < 2; ++n) _Pragma("unroll") for (int k = 0; k < 2; ++k) \
;         acc[ai][bj][m][n] = __builtin_amdgcn_mfma_f32_16x16x32_bf16(Bt[n][k], At[m][k], acc[ai][bj][m][n], 0, 0, 0); __builtin_amdgcn_s_setprio(0); } while (0)
; #define PG8_WAIT_V(n) asm volatile("s_waitcnt vmcnt(" #n ")" ::: "memory")
; #define PG8_WAIT_L(n) asm volatile("s_waitcnt lgkmcnt(" #n ")" ::: "memory")
; #define PG8_BAR __builtin_amdgcn_s_barrier()
; #define PG8_SCHED __builtin_amdgcn_sched_barrier(0)
; template <class Epi>
; __device__ __forceinline__ void gemm_phase(LAS unsigned char* lds, const Gemm g, const StaticOrder& S, const Epi& E) {
;     ...
;             PG8_LDB(B1, 1, 1); PG8_STAGE(PG8_SB(1, 0), b3, voffB);
;             PG8_BAR; PG8_WAIT_L(0); PG8_MMA(0, 1, At, B1); PG8_BAR;
;             PG8_LDA(At, 1, 1); PG8_STAGE(PG8_SA(1, 0), a3, voffA);
;             PG8_BAR; PG8_WAIT_L(0); PG8_MMA(1, 0, At, B0); PG8_BAR; PG8_SCHED;
;             PG8_STAGE(PG8_SB(1, 1), b3 + hstep, voffB);
;             PG8_WAIT_V(6); PG8_BAR; PG8_MMA(1, 1, At, B1); PG8_BAR;
;         }
	s_add_i32 s64, 0, 0x1c000
	s_add_u32 s30, s26, 0x40000
	v_add_u32_e32 v150, s64, v133
	s_addc_u32 s31, s27, 0
	s_add_i32 s63, s63, s38
	s_nop 0
	v_lshl_add_u64 v[150:151], s[30:31], 0, v[136:137]
	s_mov_b32 m0, s63
	s_nop 0
	global_load_lds_dwordx4 v[150:151], off
	v_lshl_add_u64 v[150:151], s[30:31], 0, v[140:141]
	s_add_i32 m0, s63, 0x2000
	s_nop 0
	global_load_lds_dwordx4 v[150:151], off
	s_mov_b32 m0, s43
	v_lshl_add_u64 v[150:151], s[28:29], 0, v[134:135]
	ds_read_b128 v[172:175], v154 offset:49152
	ds_read_b128 v[176:179], v154 offset:50176
	ds_read_b128 v[184:187], v154 offset:51200
	ds_read_b128 v[188:191], v154 offset:52224
	ds_read_b128 v[192:195], v154 offset:53248
	ds_read_b128 v[196:199], v154 offset:54272
	ds_read_b128 v[200:203], v154 offset:55296
	ds_read_b128 v[204:207], v154 offset:56320
	global_load_lds_dwordx4 v[150:151], off
	v_lshl_add_u64 v[150:151], s[28:29], 0, v[138:139]
	s_mov_b32 m0, s44
	s_nop 0
	global_load_lds_dwordx4 v[150:151], off
	s_add_u32 s26, s26, 0x44000
	s_addc_u32 s27, s27, 0
	s_add_i32 s28, s64, s38
	v_lshl_add_u64 v[150:151], s[26:27], 0, v[136:137]
	s_mov_b32 m0, s28
	s_nop 0
	global_load_lds_dwordx4 v[150:151], off
	v_lshl_add_u64 v[150:151], s[26:27], 0, v[140:141]
	s_add_i32 m0, s28, 0x2000
	s_nop 0
	global_load_lds_dwordx4 v[150:151], off
	s_waitcnt lgkmcnt(0)
	s_waitcnt vmcnt(8)
	s_barrier
	s_nop 0
	v_mfma_f32_16x16x32_bf16 v[60:63], v[156:159], v[172:175], v[60:63]
	v_mfma_f32_16x16x32_bf16 v[56:59], v[164:167], v[172:175], v[56:59]
	v_mfma_f32_16x16x32_bf16 v[52:55], v[156:159], v[184:187], v[52:55]
	v_mfma_f32_16x16x32_bf16 v[44:47], v[164:167], v[184:187], v[44:47]
	v_mfma_f32_16x16x32_bf16 v[36:39], v[156:159], v[192:195], v[36:39]
	v_mfma_f32_16x16x32_bf16 v[28:31], v[164:167], v[192:195], v[28:31]
	v_mfma_f32_16x16x32_bf16 v[20:23], v[156:159], v[200:203], v[20:23]
	v_mfma_f32_16x16x32_bf16 v[12:15], v[164:167], v[200:203], v[12:15]
	v_mfma_f32_16x16x32_bf16 v[60:63], v[160:163], v[176:179], v[60:63]
	v_mfma_f32_16x16x32_bf16 v[56:59], v[168:171], v[176:179], v[56:59]
	v_mfma_f32_16x16x32_bf16 v[52:55], v[160:163], v[188:191], v[52:55]
	v_mfma_f32_16x16x32_bf16 v[44:47], v[168:171], v[188:191], v[44:47]
	v_mfma_f32_16x16x32_bf16 v[36:39], v[160:163], v[196:199], v[36:39]
	v_mfma_f32_16x16x32_bf16 v[28:31], v[168:171], v[196:199], v[28:31]
	v_mfma_f32_16x16x32_bf16 v[20:23], v[160:163], v[204:207], v[20:23]
	v_mfma_f32_16x16x32_bf16 v[12:15], v[168:171], v[204:207], v[12:15]
	v_mfma_f32_16x16x32_bf16 v[48:51], v[208:211], v[172:175], v[48:51]
	v_mfma_f32_16x16x32_bf16 v[40:43], v[216:219], v[172:175], v[40:43]
	v_mfma_f32_16x16x32_bf16 v[32:35], v[208:211], v[184:187], v[32:35]
	v_mfma_f32_16x16x32_bf16 v[24:27], v[216:219], v[184:187], v[24:27]
	v_mfma_f32_16x16x32_bf16 v[16:19], v[208:211], v[192:195], v[16:19]
	v_mfma_f32_16x16x32_bf16 v[8:11], v[216:219], v[192:195], v[8:11]
	v_mfma_f32_16x16x32_bf16 v[4:7], v[208:211], v[200:203], v[4:7]
	v_mfma_f32_16x16x32_bf16 v[0:3], v[216:219], v[200:203], v[0:3]
	v_mfma_f32_16x16x32_bf16 v[48:51], v[212:215], v[176:179], v[48:51]
	v_mfma_f32_16x16x32_bf16 v[40:43], v[220:223], v[176:179], v[40:43]
	v_mfma_f32_16x16x32_bf16 v[32:35], v[212:215], v[188:191], v[32:35]
	v_mfma_f32_16x16x32_bf16 v[24:27], v[220:223], v[188:191], v[24:27]
	v_mfma_f32_16x16x32_bf16 v[16:19], v[212:215], v[196:199], v[16:19]
	v_mfma_f32_16x16x32_bf16 v[8:11], v[220:223], v[196:199], v[8:11]
	v_mfma_f32_16x16x32_bf16 v[4:7], v[212:215], v[204:207], v[4:7]
	v_mfma_f32_16x16x32_bf16 v[0:3], v[220:223], v[204:207], v[0:3]
	s_nop 0
	s_add_i32 s62, s62, 2
	s_add_u32 s60, s60, 0x80000
	s_addc_u32 s61, s61, 0
	s_add_u32 s24, s24, 0x800000
	s_addc_u32 s25, s25, 0
	s_cmp_gt_u32 s62, 29
	s_barrier
	s_cbranch_scc0 .LBB0_762
; __device__ __forceinline__ unsigned pk_bf16(float lo, float hi) { unsigned r; asm("v_cvt_pk_bf16_f32 %0, %1, %2" : "=v"(r) : "v"(lo), "v"(hi)); return r; }
; #define PG8_WAIT_V(n) asm volatile("s_waitcnt vmcnt(" #n ")" ::: "memory")
; #define PG8_BAR __builtin_amdgcn_s_barrier()
;     __device__ __forceinline__ void operator()(const f32x4 (&acc)[2][2][4][2], const Unit& u, int wr, int wc, int fr, int fq) const {
;         const int row0 = u.pm * BM + wr * 64 + fr; const int col0 = u.pn * BM + wc * 32 + 8 * fq;
; #pragma unroll
;         for (int ai = 0; ai < 2; ++ai)
; #pragma unroll
;             for (int m = 0; m < 4; ++m) { bf16_t* rowp = O + (size_t)(row0 + ai * HALF + m * 16) * ldc + col0;
; #pragma unroll
;                 for (int bj = 0; bj < 2; ++bj) { const f32x4 v0 = acc[ai][bj][m][0], v1 = acc[ai][bj][m][1];
;                     u32x4 w; w.x = pk_bf16(v0[0], v0[1]); w.y = pk_bf16(v0[2], v0[3]); w.z = pk_bf16(v1[0], v1[1]); w.w = pk_bf16(v1[2], v1[3]);
;                     *(u32x4*)(rowp + bj * HALF) = w; } }
; template <class Epi>
; __device__ __forceinline__ void gemm_phase(LAS unsigned char* lds, const Gemm g, const StaticOrder& S, const Epi& E) {
;     ...
;         if (!has_next) break;
; #pragma unroll
;         for (int a = 0; a < 2; ++a)
; #pragma unroll
;             for (int b = 0; b < 2; ++b)
; #pragma unroll
;                 for (int m = 0; m < 4; ++m)
; #pragma unroll
;                     for (int n = 0; n < 2; ++n) acc[a][b][m][n] = (f32x4){0.f, 0.f, 0.f, 0.f};
;         cur = nxt; cA = nA; cB = nB; ++ui;
;     }
;     PG8_WAIT_V(0);
;     if (wr == 0) PG8_BAR;
;     PG8_BAR;
	v_lshl_add_u32 v156, s22, 8, v131
	v_lshl_or_b32 v150, s57, 8, v152
	v_ashrrev_i32_e32 v157, 31, v156
	v_ashrrev_i32_e32 v151, 31, v150
	v_lshlrev_b64 v[158:159], 12, v[156:157]
	v_lshl_add_u64 v[158:159], s[52:53], 0, v[158:159]
	v_lshlrev_b64 v[160:161], 1, v[150:151]
	v_lshl_add_u64 v[150:151], v[158:159], 0, v[160:161]
	v_cvt_pk_bf16_f32 v60, v60, v61
	v_cvt_pk_bf16_f32 v61, v62, v63
	v_cvt_pk_bf16_f32 v62, v56, v57
	v_add_co_u32_e32 v56, vcc, s51, v150
	v_cvt_pk_bf16_f32 v116, v116, v117
	v_cvt_pk_bf16_f32 v117, v118, v119
	v_cvt_pk_bf16_f32 v118, v108, v109
	v_or_b32_e32 v108, 16, v156
	s_nop 0
	v_addc_co_u32_e32 v57, vcc, 0, v151, vcc
	v_cvt_pk_bf16_f32 v48, v48, v49
	v_cvt_pk_bf16_f32 v49, v50, v51
	v_cvt_pk_bf16_f32 v51, v42, v43
	v_cvt_pk_bf16_f32 v42, v44, v45
	v_add_co_u32_e32 v44, vcc, s54, v150
	v_ashrrev_i32_e32 v109, 31, v108
	v_cvt_pk_bf16_f32 v100, v100, v101
	v_cvt_pk_bf16_f32 v101, v102, v103
	v_cvt_pk_bf16_f32 v102, v92, v93
	v_or_b32_e32 v92, 32, v156
	v_addc_co_u32_e32 v45, vcc, 0, v151, vcc
	v_lshlrev_b64 v[108:109], 12, v[108:109]
	v_ashrrev_i32_e32 v93, 31, v92
	v_cvt_pk_bf16_f32 v84, v84, v85
	v_cvt_pk_bf16_f32 v85, v86, v87
	v_cvt_pk_bf16_f32 v86, v76, v77
	v_or_b32_e32 v76, 48, v156
	v_cvt_pk_bf16_f32 v32, v32, v33
	v_cvt_pk_bf16_f32 v33, v34, v35
	v_cvt_pk_bf16_f32 v35, v26, v27
	v_cvt_pk_bf16_f32 v26, v28, v29
	v_add_co_u32_e32 v28, vcc, s55, v150
	v_lshl_add_u64 v[108:109], s[52:53], 0, v[108:109]
	v_lshlrev_b64 v[92:93], 12, v[92:93]
	v_ashrrev_i32_e32 v77, 31, v76
	v_cvt_pk_bf16_f32 v68, v68, v69
	v_cvt_pk_bf16_f32 v69, v70, v71
	v_cvt_pk_bf16_f32 v70, v64, v65
	v_lshl_add_u64 v[64:65], v[150:151], 0, s[0:1]
	v_addc_co_u32_e32 v29, vcc, 0, v151, vcc
	v_cvt_pk_bf16_f32 v119, v110, v111
	global_store_dwordx4 v[150:151], v[116:119], off offset:256
	v_lshl_add_u64 v[92:93], s[52:53], 0, v[92:93]
	v_lshlrev_b64 v[76:77], 12, v[76:77]
	v_lshl_add_u64 v[116:117], v[108:109], 0, v[160:161]
	v_cvt_pk_bf16_f32 v50, v40, v41
	global_store_dwordx4 v[64:65], v[48:51], off offset:256
	v_cvt_pk_bf16_f32 v16, v16, v17
	v_cvt_pk_bf16_f32 v17, v18, v19
	v_cvt_pk_bf16_f32 v19, v10, v11
	v_cvt_pk_bf16_f32 v10, v12, v13
	v_add_co_u32_e32 v12, vcc, s56, v150
	s_nop 0
	v_lshl_add_u64 v[48:49], v[150:151], 0, s[8:9]
	v_cvt_pk_bf16_f32 v103, v94, v95
	global_store_dwordx4 v[116:117], v[100:103], off offset:256
	v_lshl_add_u64 v[76:77], s[52:53], 0, v[76:77]
	v_cvt_pk_bf16_f32 v34, v24, v25
	global_store_dwordx4 v[48:49], v[32:35], off offset:256
	v_lshl_add_u64 v[100:101], v[92:93], 0, v[160:161]
	v_addc_co_u32_e32 v13, vcc, 0, v151, vcc
	v_lshl_add_u64 v[32:33], v[150:151], 0, s[10:11]
	v_cvt_pk_bf16_f32 v87, v78, v79
	global_store_dwordx4 v[100:101], v[84:87], off offset:256
	v_cvt_pk_bf16_f32 v18, v8, v9
	global_store_dwordx4 v[32:33], v[16:19], off offset:256
	s_and_b64 vcc, exec, s[6:7]
	v_lshl_add_u64 v[84:85], v[76:77], 0, v[160:161]
	v_lshl_add_u64 v[16:17], v[150:151], 0, s[12:13]
	s_mov_b32 s57, s14
	s_mov_b32 s22, s16
	s_mov_b64 s[24:25], s[20:21]
	s_mov_b64 s[26:27], s[18:19]
	v_cvt_pk_bf16_f32 v124, v124, v125
	v_cvt_pk_bf16_f32 v125, v126, v127
	v_cvt_pk_bf16_f32 v126, v120, v121
	v_cvt_pk_bf16_f32 v127, v122, v123
	global_store_dwordx4 v[150:151], v[124:127], off
	v_cvt_pk_bf16_f32 v108, v112, v113
	v_cvt_pk_bf16_f32 v109, v114, v115
	v_cvt_pk_bf16_f32 v110, v104, v105
	v_cvt_pk_bf16_f32 v111, v106, v107
	global_store_dwordx4 v[116:117], v[108:111], off
	v_cvt_pk_bf16_f32 v92, v96, v97
	v_cvt_pk_bf16_f32 v93, v98, v99
	v_cvt_pk_bf16_f32 v94, v88, v89
	v_cvt_pk_bf16_f32 v95, v90, v91
	global_store_dwordx4 v[100:101], v[92:95], off
	v_cvt_pk_bf16_f32 v76, v80, v81
	v_cvt_pk_bf16_f32 v77, v82, v83
	v_cvt_pk_bf16_f32 v78, v72, v73
	v_cvt_pk_bf16_f32 v79, v74, v75
	global_store_dwordx4 v[84:85], v[76:79], off
	v_cvt_pk_bf16_f32 v71, v66, v67
	global_store_dwordx4 v[84:85], v[68:71], off offset:256
	v_cvt_pk_bf16_f32 v63, v58, v59
	global_store_dwordx4 v[56:57], v[60:63], off
	v_cvt_pk_bf16_f32 v40, v52, v53
	v_cvt_pk_bf16_f32 v41, v54, v55
	v_cvt_pk_bf16_f32 v43, v46, v47
	global_store_dwordx4 v[44:45], v[40:43], off
	v_cvt_pk_bf16_f32 v24, v36, v37
	v_cvt_pk_bf16_f32 v25, v38, v39
	v_cvt_pk_bf16_f32 v27, v30, v31
	global_store_dwordx4 v[28:29], v[24:27], off
	v_cvt_pk_bf16_f32 v8, v20, v21
	v_cvt_pk_bf16_f32 v9, v22, v23
	v_cvt_pk_bf16_f32 v11, v14, v15
	global_store_dwordx4 v[12:13], v[8:11], off
	v_cvt_pk_bf16_f32 v4, v4, v5
	v_cvt_pk_bf16_f32 v5, v6, v7
	v_cvt_pk_bf16_f32 v6, v0, v1
	v_cvt_pk_bf16_f32 v7, v2, v3
	global_store_dwordx4 v[16:17], v[4:7], off offset:256
	s_cbranch_vccz .LBB0_755
	s_waitcnt vmcnt(0)
	s_cmpk_gt_u32 s34, 0xff
	s_cbranch_scc1 .LBB0_766
	s_barrier

; #define PG8_STAGE(bufoff, gbase, voff) do { _Pragma("unroll") for (int _i = 0; _i < 2; ++_i) \
;         __builtin_amdgcn_global_load_lds((const unsigned*)((const char*)(gbase) + (voff)[_i]), (LAS unsigned*)(lds + (bufoff) + ldsw + _i * 8192), 16, 0, 0); } while (0)
; #define PG8_LDA(dst, b, h) do { _Pragma("unroll") for (int m = 0; m < 4; ++m) _Pragma("unroll") for (int k = 0; k < 2; ++k) dst[m][k] = *(const LAS bf16x8*)(lds + PG8_SA(b, h) + aoff + m * 2048 + k * 1024); } while (0)
; #define PG8_LDB(dst, b, h) do { _Pragma("unroll") for (int n = 0; n < 2; ++n) _Pragma("unroll") for (int k = 0; k < 2; ++k) dst[n][k] = *(const LAS bf16x8*)(lds + PG8_SB(b, h) + boff + n * 2048 + k * 1024); } while (0)
; #define PG8_MMA(ai, bj, At, Bt) do { __builtin_amdgcn_s_setprio(1); _Pragma("unroll") for (int m = 0; m < 4; ++m) _Pragma("unroll") for (int n = 0; n < 2; ++n) _Pragma("unroll") for (int k = 0; k < 2; ++k) \
;         acc[ai][bj][m][n] = __builtin_amdgcn_mfma_f32_16x16x32_bf16(Bt[n][k], At[m][k], acc[ai][bj][m][n], 0, 0, 0); __builtin_amdgcn_s_setprio(0); } while (0)
; template <class Epi>
; __device__ __forceinline__ void gemm_phase(LAS unsigned char* lds, const Gemm g, const StaticOrder& S, const Epi& E) {
;     ...
;         const char* nA = has_next ? (const char*)g.A + (size_t)nxt.pm * tstep : cA; const char* nB = has_next ? (const char*)g.Bt + (size_t)nxt.pn * tstep : cB;
;         for (int t = 0; t < nt; t += 2) {
;             const bool last = (t == nt - 2);
;             const char* a1 = cA + (size_t)(t + 1) * kstepA;
;             const char* a2 = last ? nA : cA + (size_t)(t + 2) * kstepA; const char* b2 = last ? nB : cB + (size_t)(t + 2) * kstepB;
;             const char* a3 = a2 + kstepA; const char* b3 = b2 + kstepB;
;             PG8_LDB(B0, 0, 0); PG8_SCHED; PG8_LDA(At, 0, 0); PG8_STAGE(PG8_SA(1, 1), a1 + hstep, voffA);
;             PG8_WAIT_L(8); PG8_BAR; PG8_WAIT_L(0); PG8_MMA(0, 0, At, B0); PG8_BAR; PG8_SCHED;
;             PG8_LDB(B1, 0, 1); PG8_STAGE(PG8_SB(0, 0), b2, voffB);
;             PG8_BAR; PG8_WAIT_L(0); PG8_MMA(0, 1, At, B1); PG8_BAR;
;             PG8_LDA(At, 0, 1); PG8_STAGE(PG8_SA(0, 0), a2, voffA);
;             PG8_BAR; PG8_WAIT_L(0); PG8_MMA(1, 0, At, B0); PG8_BAR; PG8_SCHED;
;             PG8_STAGE(PG8_SB(0, 1), b2 + hstep, voffB);
;             PG8_WAIT_V(6); PG8_BAR; PG8_MMA(1, 1, At, B1); PG8_BAR;
.LBB0_885:
	ds_read_b128 v[152:155], v148
	ds_read_b128 v[156:159], v148 offset:1024
	ds_read_b128 v[160:163], v148 offset:2048
	ds_read_b128 v[164:167], v148 offset:3072
	s_add_u32 s18, s16, 0x3fc000
	s_addc_u32 s19, s17, 0
	s_cmp_eq_u32 s50, 28
	s_cselect_b32 s22, s44, s18
	s_cselect_b32 s23, s9, s19
	s_cselect_b32 s18, s45, s48
	s_cselect_b32 s19, s1, s49
	s_add_u32 s20, s22, 0x400000
	s_addc_u32 s21, s23, 0
	v_lshl_add_u64 v[144:145], s[16:17], 0, v[136:137]
	s_add_i32 m0, s30, 0xc000
	ds_read_b128 v[168:171], v149
	ds_read_b128 v[172:175], v149 offset:1024
	ds_read_b128 v[176:179], v149 offset:2048
	ds_read_b128 v[184:187], v149 offset:3072
	ds_read_b128 v[188:191], v149 offset:4096
	ds_read_b128 v[192:195], v149 offset:5120
	ds_read_b128 v[196:199], v149 offset:6144
	ds_read_b128 v[200:203], v149 offset:7168
	global_load_lds_dwordx4 v[144:145], off
	v_lshl_add_u64 v[144:145], s[16:17], 0, v[138:139]
	s_add_i32 m0, s30, 0xe000
	s_nop 0
	global_load_lds_dwordx4 v[144:145], off
	ds_read_b128 v[204:207], v150
	ds_read_b128 v[208:211], v150 offset:1024
	ds_read_b128 v[212:215], v150 offset:2048
	ds_read_b128 v[216:219], v150 offset:3072
	s_waitcnt lgkmcnt(0)
	s_waitcnt vmcnt(8)
	s_barrier
	s_nop 0
	v_mfma_f32_16x16x32_bf16 v[124:127], v[152:155], v[168:171], v[124:127]
	v_mfma_f32_16x16x32_bf16 v[120:123], v[160:163], v[168:171], v[120:123]
	v_mfma_f32_16x16x32_bf16 v[108:111], v[152:155], v[176:179], v[108:111]
	v_mfma_f32_16x16x32_bf16 v[104:107], v[160:163], v[176:179], v[104:107]
	v_mfma_f32_16x16x32_bf16 v[92:95], v[152:155], v[188:191], v[92:95]
	v_mfma_f32_16x16x32_bf16 v[88:91], v[160:163], v[188:191], v[88:91]
	v_mfma_f32_16x16x32_bf16 v[76:79], v[152:155], v[196:199], v[76:79]
	v_mfma_f32_16x16x32_bf16 v[72:75], v[160:163], v[196:199], v[72:75]
	v_mfma_f32_16x16x32_bf16 v[124:127], v[156:159], v[172:175], v[124:127]
	v_mfma_f32_16x16x32_bf16 v[120:123], v[164:167], v[172:175], v[120:123]
	v_mfma_f32_16x16x32_bf16 v[108:111], v[156:159], v[184:187], v[108:111]
	v_mfma_f32_16x16x32_bf16 v[104:107], v[164:167], v[184:187], v[104:107]
	v_mfma_f32_16x16x32_bf16 v[92:95], v[156:159], v[192:195], v[92:95]
	v_mfma_f32_16x16x32_bf16 v[88:91], v[164:167], v[192:195], v[88:91]
	v_mfma_f32_16x16x32_bf16 v[76:79], v[156:159], v[200:203], v[76:79]
	v_mfma_f32_16x16x32_bf16 v[72:75], v[164:167], v[200:203], v[72:75]
	v_mfma_f32_16x16x32_bf16 v[116:119], v[204:207], v[168:171], v[116:119]
	v_mfma_f32_16x16x32_bf16 v[112:115], v[212:215], v[168:171], v[112:115]
	v_mfma_f32_16x16x32_bf16 v[100:103], v[204:207], v[176:179], v[100:103]
	v_mfma_f32_16x16x32_bf16 v[96:99], v[212:215], v[176:179], v[96:99]
	v_mfma_f32_16x16x32_bf16 v[84:87], v[204:207], v[188:191], v[84:87]
	v_mfma_f32_16x16x32_bf16 v[80:83], v[212:215], v[188:191], v[80:83]
	v_mfma_f32_16x16x32_bf16 v[68:71], v[204:207], v[196:199], v[68:71]
	v_mfma_f32_16x16x32_bf16 v[64:67], v[212:215], v[196:199], v[64:67]
	v_mfma_f32_16x16x32_bf16 v[116:119], v[208:211], v[172:175], v[116:119]
	v_mfma_f32_16x16x32_bf16 v[112:115], v[216:219], v[172:175], v[112:115]
	v_mfma_f32_16x16x32_bf16 v[100:103], v[208:211], v[184:187], v[100:103]
	v_mfma_f32_16x16x32_bf16 v[96:99], v[216:219], v[184:187], v[96:99]
	v_mfma_f32_16x16x32_bf16 v[84:87], v[208:211], v[192:195], v[84:87]
	v_mfma_f32_16x16x32_bf16 v[80:83], v[216:219], v[192:195], v[80:83]
	v_mfma_f32_16x16x32_bf16 v[68:71], v[208:211], v[200:203], v[68:71]
	v_mfma_f32_16x16x32_bf16 v[64:67], v[216:219], v[200:203], v[64:67]
	s_nop 0
	s_barrier
	s_add_i32 s51, s42, s27
	v_lshl_add_u64 v[144:145], s[18:19], 0, v[132:133]
	s_mov_b32 m0, s51
	s_nop 0
	global_load_lds_dwordx4 v[144:145], off
	v_lshl_add_u64 v[144:145], s[18:19], 0, v[130:131]
	s_add_i32 m0, s51, 0x2000
	s_nop 0
	global_load_lds_dwordx4 v[144:145], off
	s_mov_b32 m0, s30
	v_lshl_add_u64 v[144:145], s[22:23], 0, v[132:133]
	ds_read_b128 v[168:171], v149 offset:16384
	ds_read_b128 v[172:175], v149 offset:17408
	ds_read_b128 v[176:179], v149 offset:18432
	ds_read_b128 v[184:187], v149 offset:19456
	ds_read_b128 v[188:191], v149 offset:20480
	ds_read_b128 v[192:195], v149 offset:21504
	ds_read_b128 v[196:199], v149 offset:22528
	ds_read_b128 v[200:203], v149 offset:23552
	global_load_lds_dwordx4 v[144:145], off
	v_lshl_add_u64 v[144:145], s[22:23], 0, v[130:131]
	s_mov_b32 m0, s31
	s_nop 0
	global_load_lds_dwordx4 v[144:145], off
	s_add_u32 s54, s18, 0x4000
	s_addc_u32 s55, s19, 0
	s_add_i32 s51, s43, s27
	v_lshl_add_u64 v[144:145], s[54:55], 0, v[132:133]
	s_mov_b32 m0, s51
	s_nop 0
	global_load_lds_dwordx4 v[144:145], off
	v_lshl_add_u64 v[144:145], s[54:55], 0, v[130:131]
	s_add_i32 m0, s51, 0x2000
	s_nop 0
	global_load_lds_dwordx4 v[144:145], off
	s_waitcnt lgkmcnt(0)
	s_waitcnt vmcnt(8)
	s_barrier
; #define PG8_STAGE(bufoff, gbase, voff) do { _Pragma("unroll") for (int _i = 0; _i < 2; ++_i) \
;         __builtin_amdgcn_global_load_lds((const unsigned*)((const char*)(gbase) + (voff)[_i]), (LAS unsigned*)(lds + (bufoff) + ldsw + _i * 8192), 16, 0, 0); } while (0)
; #define PG8_LDA(dst, b, h) do { _Pragma("unroll") for (int m = 0; m < 4; ++m) _Pragma("unroll") for (int k = 0; k < 2; ++k) dst[m][k] = *(const LAS bf16x8*)(lds + PG8_SA(b, h) + aoff + m * 2048 + k * 1024); } while (0)
; #define PG8_LDB(dst, b, h) do { _Pragma("unroll") for (int n = 0; n < 2; ++n) _Pragma("unroll") for (int k = 0; k < 2; ++k) dst[n][k] = *(const LAS bf16x8*)(lds + PG8_SB(b, h) + boff + n * 2048 + k * 1024); } while (0)
; #define PG8_MMA(ai, bj, At, Bt) do { __builtin_amdgcn_s_setprio(1); _Pragma("unroll") for (int m = 0; m < 4; ++m) _Pragma("unroll") for (int n = 0; n < 2; ++n) _Pragma("unroll") for (int k = 0; k < 2; ++k) \
;         acc[ai][bj][m][n] = __builtin_amdgcn_mfma_f32_16x16x32_bf16(Bt[n][k], At[m][k], acc[ai][bj][m][n], 0, 0, 0); __builtin_amdgcn_s_setprio(0); } while (0)
; #define PG8_WAIT_V(n) asm volatile("s_waitcnt vmcnt(" #n ")" ::: "memory")
; #define PG8_WAIT_L(n) asm volatile("s_waitcnt lgkmcnt(" #n ")" ::: "memory")
; #define PG8_BAR __builtin_amdgcn_s_barrier()
; #define PG8_SCHED __builtin_amdgcn_sched_barrier(0)
; template <class Epi>
; __device__ __forceinline__ void gemm_phase(LAS unsigned char* lds, const Gemm g, const StaticOrder& S, const Epi& E) {
;     ...
;             PG8_BAR; PG8_WAIT_L(0); PG8_MMA(1, 0, At, B0); PG8_BAR; PG8_SCHED;
;             PG8_STAGE(PG8_SB(0, 1), b2 + hstep, voffB);
;             PG8_WAIT_V(6); PG8_BAR; PG8_MMA(1, 1, At, B1); PG8_BAR;
;             PG8_LDB(B0, 1, 0); PG8_SCHED; PG8_LDA(At, 1, 0); PG8_STAGE(PG8_SA(0, 1), a2 + hstep, voffA);
;             PG8_WAIT_L(8); PG8_BAR; PG8_WAIT_L(0); PG8_MMA(0, 0, At, B0); PG8_BAR; PG8_SCHED;
;             PG8_LDB(B1, 1, 1); PG8_STAGE(PG8_SB(1, 0), b3, voffB);
;             PG8_BAR; PG8_WAIT_L(0); PG8_MMA(0, 1, At, B1); PG8_BAR;
;             PG8_LDA(At, 1, 1); PG8_STAGE(PG8_SA(1, 0), a3, voffA);
;             PG8_BAR; PG8_WAIT_L(0); PG8_MMA(1, 0, At, B0); PG8_BAR; PG8_SCHED;
	s_nop 0
	v_mfma_f32_16x16x32_bf16 v[60:63], v[152:155], v[168:171], v[60:63]
	v_mfma_f32_16x16x32_bf16 v[56:59], v[160:163], v[168:171], v[56:59]
	v_mfma_f32_16x16x32_bf16 v[44:47], v[152:155], v[176:179], v[44:47]
	v_mfma_f32_16x16x32_bf16 v[40:43], v[160:163], v[176:179], v[40:43]
	v_mfma_f32_16x16x32_bf16 v[28:31], v[152:155], v[188:191], v[28:31]
	v_mfma_f32_16x16x32_bf16 v[24:27], v[160:163], v[188:191], v[24:27]
	v_mfma_f32_16x16x32_bf16 v[12:15], v[152:155], v[196:199], v[12:15]
	v_mfma_f32_16x16x32_bf16 v[8:11], v[160:163], v[196:199], v[8:11]
	v_mfma_f32_16x16x32_bf16 v[60:63], v[156:159], v[172:175], v[60:63]
	v_mfma_f32_16x16x32_bf16 v[56:59], v[164:167], v[172:175], v[56:59]
	v_mfma_f32_16x16x32_bf16 v[44:47], v[156:159], v[184:187], v[44:47]
	v_mfma_f32_16x16x32_bf16 v[40:43], v[164:167], v[184:187], v[40:43]
	v_mfma_f32_16x16x32_bf16 v[28:31], v[156:159], v[192:195], v[28:31]
	v_mfma_f32_16x16x32_bf16 v[24:27], v[164:167], v[192:195], v[24:27]
	v_mfma_f32_16x16x32_bf16 v[12:15], v[156:159], v[200:203], v[12:15]
	v_mfma_f32_16x16x32_bf16 v[8:11], v[164:167], v[200:203], v[8:11]
	v_mfma_f32_16x16x32_bf16 v[52:55], v[204:207], v[168:171], v[52:55]
	v_mfma_f32_16x16x32_bf16 v[48:51], v[212:215], v[168:171], v[48:51]
	v_mfma_f32_16x16x32_bf16 v[36:39], v[204:207], v[176:179], v[36:39]
	v_mfma_f32_16x16x32_bf16 v[32:35], v[212:215], v[176:179], v[32:35]
	v_mfma_f32_16x16x32_bf16 v[20:23], v[204:207], v[188:191], v[20:23]
	v_mfma_f32_16x16x32_bf16 v[16:19], v[212:215], v[188:191], v[16:19]
	v_mfma_f32_16x16x32_bf16 v[4:7], v[204:207], v[196:199], v[4:7]
	v_mfma_f32_16x16x32_bf16 v[0:3], v[212:215], v[196:199], v[0:3]
	v_mfma_f32_16x16x32_bf16 v[52:55], v[208:211], v[172:175], v[52:55]
	v_mfma_f32_16x16x32_bf16 v[48:51], v[216:219], v[172:175], v[48:51]
	v_mfma_f32_16x16x32_bf16 v[36:39], v[208:211], v[184:187], v[36:39]
	v_mfma_f32_16x16x32_bf16 v[32:35], v[216:219], v[184:187], v[32:35]
	v_mfma_f32_16x16x32_bf16 v[20:23], v[208:211], v[192:195], v[20:23]
	v_mfma_f32_16x16x32_bf16 v[16:19], v[216:219], v[192:195], v[16:19]
	v_mfma_f32_16x16x32_bf16 v[4:7], v[208:211], v[200:203], v[4:7]
	v_mfma_f32_16x16x32_bf16 v[0:3], v[216:219], v[200:203], v[0:3]
	s_nop 0
	s_add_i32 s51, 0, 0x18000
	v_add_u32_e32 v144, s51, v147
	s_barrier
	ds_read_b128 v[152:155], v144
	ds_read_b128 v[156:159], v144 offset:1024
	ds_read_b128 v[160:163], v144 offset:2048
	ds_read_b128 v[164:167], v144 offset:3072
	s_add_u32 s22, s22, 0x4000
	s_addc_u32 s23, s23, 0
	s_mov_b32 m0, s34
	v_lshl_add_u64 v[144:145], s[22:23], 0, v[132:133]
	ds_read_b128 v[168:171], v149 offset:32768
	ds_read_b128 v[172:175], v149 offset:33792
	ds_read_b128 v[176:179], v149 offset:34816
	ds_read_b128 v[184:187], v149 offset:35840
	ds_read_b128 v[188:191], v149 offset:36864
	ds_read_b128 v[192:195], v149 offset:37888
	ds_read_b128 v[196:199], v149 offset:38912
	ds_read_b128 v[200:203], v149 offset:39936
	global_load_lds_dwordx4 v[144:145], off
	v_lshl_add_u64 v[144:145], s[22:23], 0, v[130:131]
	s_mov_b32 m0, s35
	s_nop 0
	global_load_lds_dwordx4 v[144:145], off
	v_add_u32_e32 v253, 0x1c000, v147
	ds_read_b128 v[204:207], v253
	ds_read_b128 v[208:211], v253 offset:1024
	ds_read_b128 v[212:215], v253 offset:2048
	ds_read_b128 v[216:219], v253 offset:3072
	s_waitcnt lgkmcnt(0)
	s_waitcnt vmcnt(8)
	s_barrier
	s_nop 0
	v_mfma_f32_16x16x32_bf16 v[124:127], v[152:155], v[168:171], v[124:127]
	v_mfma_f32_16x16x32_bf16 v[120:123], v[160:163], v[168:171], v[120:123]
	v_mfma_f32_16x16x32_bf16 v[108:111], v[152:155], v[176:179], v[108:111]
	v_mfma_f32_16x16x32_bf16 v[104:107], v[160:163], v[176:179], v[104:107]
	v_mfma_f32_16x16x32_bf16 v[92:95], v[152:155], v[188:191], v[92:95]
	v_mfma_f32_16x16x32_bf16 v[88:91], v[160:163], v[188:191], v[88:91]
	v_mfma_f32_16x16x32_bf16 v[76:79], v[152:155], v[196:199], v[76:79]
	v_mfma_f32_16x16x32_bf16 v[72:75], v[160:163], v[196:199], v[72:75]
	v_mfma_f32_16x16x32_bf16 v[124:127], v[156:159], v[172:175], v[124:127]
	v_mfma_f32_16x16x32_bf16 v[120:123], v[164:167], v[172:175], v[120:123]
	v_mfma_f32_16x16x32_bf16 v[108:111], v[156:159], v[184:187], v[108:111]
	v_mfma_f32_16x16x32_bf16 v[104:107], v[164:167], v[184:187], v[104:107]
	v_mfma_f32_16x16x32_bf16 v[92:95], v[156:159], v[192:195], v[92:95]
	v_mfma_f32_16x16x32_bf16 v[88:91], v[164:167], v[192:195], v[88:91]
	v_mfma_f32_16x16x32_bf16 v[76:79], v[156:159], v[200:203], v[76:79]
	v_mfma_f32_16x16x32_bf16 v[72:75], v[164:167], v[200:203], v[72:75]
	v_mfma_f32_16x16x32_bf16 v[116:119], v[204:207], v[168:171], v[116:119]
	v_mfma_f32_16x16x32_bf16 v[112:115], v[212:215], v[168:171], v[112:115]
	v_mfma_f32_16x16x32_bf16 v[100:103], v[204:207], v[176:179], v[100:103]
	v_mfma_f32_16x16x32_bf16 v[96:99], v[212:215], v[176:179], v[96:99]
	v_mfma_f32_16x16x32_bf16 v[84:87], v[204:207], v[188:191], v[84:87]
	v_mfma_f32_16x16x32_bf16 v[80:83], v[212:215], v[188:191], v[80:83]
	v_mfma_f32_16x16x32_bf16 v[68:71], v[204:207], v[196:199], v[68:71]
	v_mfma_f32_16x16x32_bf16 v[64:67], v[212:215], v[196:199], v[64:67]
	v_mfma_f32_16x16x32_bf16 v[116:119], v[208:211], v[172:175], v[116:119]
	v_mfma_f32_16x16x32_bf16 v[112:115], v[216:219], v[172:175], v[112:115]
	v_mfma_f32_16x16x32_bf16 v[100:103], v[208:211], v[184:187], v[100:103]
	v_mfma_f32_16x16x32_bf16 v[96:99], v[216:219], v[184:187], v[96:99]
	v_mfma_f32_16x16x32_bf16 v[84:87], v[208:211], v[192:195], v[84:87]
	v_mfma_f32_16x16x32_bf16 v[80:83], v[216:219], v[192:195], v[80:83]
	v_mfma_f32_16x16x32_bf16 v[68:71], v[208:211], v[200:203], v[68:71]
	v_mfma_f32_16x16x32_bf16 v[64:67], v[216:219], v[200:203], v[64:67]
	s_nop 0
	s_barrier
; __device__ __forceinline__ unsigned pk_bf16(float lo, float hi) { unsigned r; asm("v_cvt_pk_bf16_f32 %0, %1, %2" : "=v"(r) : "v"(lo), "v"(hi)); return r; }
; __device__ __forceinline__ size_t blk_off(int row, int col, int nrows) { return ((size_t)(col >> 6) * nrows + row) * 64 + (col & 63); }
; __device__ __forceinline__ float sigmoidf_fast(float v) { return __builtin_amdgcn_rcpf(1.0f + __expf(-v)); }
; #define PG8_STAGE(bufoff, gbase, voff) do { _Pragma("unroll") for (int _i = 0; _i < 2; ++_i) \
;         __builtin_amdgcn_global_load_lds((const unsigned*)((const char*)(gbase) + (voff)[_i]), (LAS unsigned*)(lds + (bufoff) + ldsw + _i * 8192), 16, 0, 0); } while (0)
; #define PG8_LDA(dst, b, h) do { _Pragma("unroll") for (int m = 0; m < 4; ++m) _Pragma("unroll") for (int k = 0; k < 2; ++k) dst[m][k] = *(const LAS bf16x8*)(lds + PG8_SA(b, h) + aoff + m * 2048 + k * 1024); } while (0)
; #define PG8_WAIT_V(n) asm volatile("s_waitcnt vmcnt(" #n ")" ::: "memory")
; #define PG8_WAIT_L(n) asm volatile("s_waitcnt lgkmcnt(" #n ")" ::: "memory")
;     __device__ __forceinline__ void operator()(const f32x4 (&acc)[2][2][4][2], const Unit& u, int wr, int wc, int fr, int fq) const {
;         const int row0 = u.pm * BM + wr * 64 + fr; const int col0 = u.pn * HALF + wc * 32 + 8 * fq;
; #pragma unroll
;         for (int ai = 0; ai < 2; ++ai)
; #pragma unroll
;             for (int m = 0; m < 4; ++m) { bf16_t* rowp = O + blk_off(row0 + ai * HALF + m * 16, col0, nrows);
;                 float v[8];
; #pragma unroll
;                 for (int bj = 0; bj < 2; ++bj)
; #pragma unroll
;                     for (int j = 0; j < 4; ++j) { const float g = acc[ai][bj][m][0][j], up = acc[ai][bj][m][1][j]; v[bj * 4 + j] = g * sigmoidf_fast(g) * up; }
;                 u32x4 w; w.x = pk_bf16(v[0], v[1]); w.y = pk_bf16(v[2], v[3]); w.z = pk_bf16(v[4], v[5]); w.w = pk_bf16(v[6], v[7]);
;                 *(u32x4*)rowp = w; }
; template <class Epi>
; __device__ __forceinline__ void gemm_phase(LAS unsigned char* lds, const Gemm g, const StaticOrder& S, const Epi& E) {
;     ...
;             PG8_LDA(At, 1, 1); PG8_STAGE(PG8_SA(1, 0), a3, voffA);
;             PG8_BAR; PG8_WAIT_L(0); PG8_MMA(1, 0, At, B0); PG8_BAR; PG8_SCHED;
;             PG8_STAGE(PG8_SB(1, 1), b3 + hstep, voffB);
;             PG8_WAIT_V(6); PG8_BAR; PG8_MMA(1, 1, At, B1); PG8_BAR;
;         }
	s_add_i32 s54, 0, 0x1c000
	s_add_u32 s22, s18, 0x160000
	v_add_u32_e32 v144, s54, v147
	s_addc_u32 s23, s19, 0
	s_add_i32 s51, s51, s27
	s_nop 0
	v_lshl_add_u64 v[144:145], s[22:23], 0, v[132:133]
	s_mov_b32 m0, s51
	s_nop 0
	global_load_lds_dwordx4 v[144:145], off
	v_lshl_add_u64 v[144:145], s[22:23], 0, v[130:131]
	s_add_i32 m0, s51, 0x2000
	s_nop 0
	global_load_lds_dwordx4 v[144:145], off
	s_mov_b32 m0, s38
	v_lshl_add_u64 v[144:145], s[20:21], 0, v[132:133]
	ds_read_b128 v[168:171], v149 offset:49152
	ds_read_b128 v[172:175], v149 offset:50176
	ds_read_b128 v[176:179], v149 offset:51200
	ds_read_b128 v[184:187], v149 offset:52224
	ds_read_b128 v[188:191], v149 offset:53248
	ds_read_b128 v[192:195], v149 offset:54272
	ds_read_b128 v[196:199], v149 offset:55296
	ds_read_b128 v[200:203], v149 offset:56320
	global_load_lds_dwordx4 v[144:145], off
	v_lshl_add_u64 v[144:145], s[20:21], 0, v[130:131]
	s_mov_b32 m0, s39
	s_nop 0
	global_load_lds_dwordx4 v[144:145], off
	s_add_u32 s18, s18, 0x164000
	s_addc_u32 s19, s19, 0
	s_add_i32 s20, s54, s27
	v_lshl_add_u64 v[144:145], s[18:19], 0, v[132:133]
	s_mov_b32 m0, s20
	s_nop 0
	global_load_lds_dwordx4 v[144:145], off
	v_lshl_add_u64 v[144:145], s[18:19], 0, v[130:131]
	s_add_i32 m0, s20, 0x2000
	s_nop 0
	global_load_lds_dwordx4 v[144:145], off
	s_waitcnt lgkmcnt(0)
	s_waitcnt vmcnt(8)
	s_barrier
	s_nop 0
	v_mfma_f32_16x16x32_bf16 v[60:63], v[152:155], v[168:171], v[60:63]
	v_mfma_f32_16x16x32_bf16 v[56:59], v[160:163], v[168:171], v[56:59]
	v_mfma_f32_16x16x32_bf16 v[44:47], v[152:155], v[176:179], v[44:47]
	v_mfma_f32_16x16x32_bf16 v[40:43], v[160:163], v[176:179], v[40:43]
	v_mfma_f32_16x16x32_bf16 v[28:31], v[152:155], v[188:191], v[28:31]
	v_mfma_f32_16x16x32_bf16 v[24:27], v[160:163], v[188:191], v[24:27]
	v_mfma_f32_16x16x32_bf16 v[12:15], v[152:155], v[196:199], v[12:15]
	v_mfma_f32_16x16x32_bf16 v[8:11], v[160:163], v[196:199], v[8:11]
	v_mfma_f32_16x16x32_bf16 v[60:63], v[156:159], v[172:175], v[60:63]
	v_mfma_f32_16x16x32_bf16 v[56:59], v[164:167], v[172:175], v[56:59]
	v_mfma_f32_16x16x32_bf16 v[44:47], v[156:159], v[184:187], v[44:47]
	v_mfma_f32_16x16x32_bf16 v[40:43], v[164:167], v[184:187], v[40:43]
	v_mfma_f32_16x16x32_bf16 v[28:31], v[156:159], v[192:195], v[28:31]
	v_mfma_f32_16x16x32_bf16 v[24:27], v[164:167], v[192:195], v[24:27]
	v_mfma_f32_16x16x32_bf16 v[12:15], v[156:159], v[200:203], v[12:15]
	v_mfma_f32_16x16x32_bf16 v[8:11], v[164:167], v[200:203], v[8:11]
	v_mfma_f32_16x16x32_bf16 v[52:55], v[204:207], v[168:171], v[52:55]
	v_mfma_f32_16x16x32_bf16 v[48:51], v[212:215], v[168:171], v[48:51]
	v_mfma_f32_16x16x32_bf16 v[36:39], v[204:207], v[176:179], v[36:39]
	v_mfma_f32_16x16x32_bf16 v[32:35], v[212:215], v[176:179], v[32:35]
	v_mfma_f32_16x16x32_bf16 v[20:23], v[204:207], v[188:191], v[20:23]
	v_mfma_f32_16x16x32_bf16 v[16:19], v[212:215], v[188:191], v[16:19]
	v_mfma_f32_16x16x32_bf16 v[4:7], v[204:207], v[196:199], v[4:7]
	v_mfma_f32_16x16x32_bf16 v[0:3], v[212:215], v[196:199], v[0:3]
	v_mfma_f32_16x16x32_bf16 v[52:55], v[208:211], v[172:175], v[52:55]
	v_mfma_f32_16x16x32_bf16 v[48:51], v[216:219], v[172:175], v[48:51]
	v_mfma_f32_16x16x32_bf16 v[36:39], v[208:211], v[184:187], v[36:39]
	v_mfma_f32_16x16x32_bf16 v[32:35], v[216:219], v[184:187], v[32:35]
	v_mfma_f32_16x16x32_bf16 v[20:23], v[208:211], v[192:195], v[20:23]
	v_mfma_f32_16x16x32_bf16 v[16:19], v[216:219], v[192:195], v[16:19]
	v_mfma_f32_16x16x32_bf16 v[4:7], v[208:211], v[200:203], v[4:7]
	v_mfma_f32_16x16x32_bf16 v[0:3], v[216:219], v[200:203], v[0:3]
	s_nop 0
	s_add_i32 s50, s50, 2
	s_add_u32 s48, s48, 0x2c0000
	s_addc_u32 s49, s49, 0
	s_add_u32 s16, s16, 0x800000
	s_addc_u32 s17, s17, 0
	s_cmp_gt_u32 s50, 29
	s_barrier
	s_cbranch_scc0 .LBB0_885
	s_lshl_b32 s1, s15, 7
	v_mul_f32_e32 v151, 0xbfb8aa3b, v124
	s_or_b32 s1, s1, s37
	v_exp_f32_e32 v151, v151
	v_mul_f32_e32 v152, 0xbfb8aa3b, v125
	v_lshl_add_u32 v144, s14, 8, v146
	s_ashr_i32 s14, s1, 6
	v_exp_f32_e32 v154, v152
	s_ashr_i32 s15, s14, 31
	s_lshl_b64 s[14:15], s[14:15], 15
	v_ashrrev_i32_e32 v145, 31, v144
	v_lshl_add_u64 v[152:153], s[14:15], 0, v[144:145]
	v_add_f32_e32 v145, 1.0, v151
	v_rcp_f32_e32 v145, v145
	v_add_f32_e32 v151, 1.0, v154
	v_rcp_f32_e32 v151, v151
	v_lshlrev_b64 v[152:153], 7, v[152:153]
	v_mul_f32_e32 v124, v124, v145
	v_mul_f32_e32 v120, v120, v124
	v_mul_f32_e32 v124, v125, v151
	v_mul_f32_e32 v125, 0xbfb8aa3b, v126
	v_exp_f32_e32 v125, v125
	v_mul_f32_e32 v145, 0xbfb8aa3b, v127
	v_exp_f32_e32 v145, v145
	v_mul_f32_e32 v121, v121, v124
	v_add_f32_e32 v124, 1.0, v125
	v_rcp_f32_e32 v124, v124
	v_add_f32_e32 v125, 1.0, v145
	v_mul_f32_e32 v145, 0xbfb8aa3b, v116
	v_rcp_f32_e32 v125, v125
	v_exp_f32_e32 v145, v145
	v_mul_f32_e32 v124, v126, v124
	v_mul_f32_e32 v122, v122, v124
	v_mul_f32_e32 v124, v127, v125
	v_add_f32_e32 v125, 1.0, v145
	v_rcp_f32_e32 v125, v125
	v_mul_f32_e32 v126, 0xbfb8aa3b, v117
	v_exp_f32_e32 v126, v126
	v_mul_f32_e32 v123, v123, v124
	v_mul_f32_e32 v116, v116, v125
	v_mul_f32_e32 v124, v112, v116
	v_mul_f32_e32 v116, 0xbfb8aa3b, v118
	v_add_f32_e32 v112, 1.0, v126
	v_exp_f32_e32 v116, v116
	v_mul_f32_e32 v125, 0xbfb8aa3b, v119
	v_rcp_f32_e32 v112, v112
	v_exp_f32_e32 v125, v125
	v_add_f32_e32 v116, 1.0, v116
	v_rcp_f32_e32 v116, v116
	v_mul_f32_e32 v112, v117, v112
	v_add_f32_e32 v117, 1.0, v125
	v_rcp_f32_e32 v117, v117
	v_mul_f32_e32 v125, v113, v112
	v_mul_f32_e32 v112, v118, v116
	v_mul_f32_e32 v118, v114, v112
	v_mul_f32_e32 v112, v119, v117
	v_mul_f32_e32 v115, v115, v112
	v_lshl_add_u64 v[116:117], v[134:135], 0, v[152:153]
	v_cvt_pk_bf16_f32 v114, v124, v125
	v_cvt_pk_bf16_f32 v112, v120, v121
; __device__ __forceinline__ unsigned pk_bf16(float lo, float hi) { unsigned r; asm("v_cvt_pk_bf16_f32 %0, %1, %2" : "=v"(r) : "v"(lo), "v"(hi)); return r; }
; __device__ __forceinline__ size_t blk_off(int row, int col, int nrows) { return ((size_t)(col >> 6) * nrows + row) * 64 + (col & 63); }
; __device__ __forceinline__ float sigmoidf_fast(float v) { return __builtin_amdgcn_rcpf(1.0f + __expf(-v)); }
;     __device__ __forceinline__ void operator()(const f32x4 (&acc)[2][2][4][2], const Unit& u, int wr, int wc, int fr, int fq) const {
;     ...
;         for (int ai = 0; ai < 2; ++ai)
; #pragma unroll
;             for (int m = 0; m < 4; ++m) { bf16_t* rowp = O + blk_off(row0 + ai * HALF + m * 16, col0, nrows);
;                 float v[8];
; #pragma unroll
;                 for (int bj = 0; bj < 2; ++bj)
; #pragma unroll
;                     for (int j = 0; j < 4; ++j) { const float g = acc[ai][bj][m][0][j], up = acc[ai][bj][m][1][j]; v[bj * 4 + j] = g * sigmoidf_fast(g) * up; }
;                 u32x4 w; w.x = pk_bf16(v[0], v[1]); w.y = pk_bf16(v[2], v[3]); w.z = pk_bf16(v[4], v[5]); w.w = pk_bf16(v[6], v[7]);
;                 *(u32x4*)rowp = w; }
	v_cvt_pk_bf16_f32 v113, v122, v123
	v_cvt_pk_bf16_f32 v115, v118, v115
	global_store_dwordx4 v[116:117], v[112:115], off
	s_and_b64 vcc, exec, s[6:7]
	s_mov_b64 s[16:17], s[12:13]
	v_mul_f32_e32 v114, 0xbfb8aa3b, v108
	v_exp_f32_e32 v114, v114
	v_mul_f32_e32 v115, 0xbfb8aa3b, v109
	v_exp_f32_e32 v115, v115
	v_or_b32_e32 v112, 16, v144
	v_add_f32_e32 v114, 1.0, v114
	v_rcp_f32_e32 v114, v114
	v_add_f32_e32 v115, 1.0, v115
	v_rcp_f32_e32 v115, v115
	v_ashrrev_i32_e32 v113, 31, v112
	v_mul_f32_e32 v108, v108, v114
	v_mul_f32_e32 v104, v104, v108
	v_mul_f32_e32 v108, v109, v115
	v_mul_f32_e32 v109, 0xbfb8aa3b, v110
	v_exp_f32_e32 v109, v109
	v_mul_f32_e32 v114, 0xbfb8aa3b, v111
	v_exp_f32_e32 v114, v114
	v_mul_f32_e32 v105, v105, v108
	v_add_f32_e32 v108, 1.0, v109
	v_rcp_f32_e32 v108, v108
	v_add_f32_e32 v109, 1.0, v114
	v_mul_f32_e32 v114, 0xbfb8aa3b, v100
	v_rcp_f32_e32 v109, v109
	v_exp_f32_e32 v114, v114
	v_mul_f32_e32 v108, v110, v108
	v_mul_f32_e32 v106, v106, v108
	v_mul_f32_e32 v108, v111, v109
	v_add_f32_e32 v109, 1.0, v114
	v_rcp_f32_e32 v109, v109
	v_mul_f32_e32 v110, 0xbfb8aa3b, v101
	v_exp_f32_e32 v110, v110
	v_mul_f32_e32 v107, v107, v108
	v_mul_f32_e32 v100, v100, v109
	v_mul_f32_e32 v108, v96, v100
	v_mul_f32_e32 v100, 0xbfb8aa3b, v102
	v_add_f32_e32 v96, 1.0, v110
	v_exp_f32_e32 v100, v100
	v_mul_f32_e32 v109, 0xbfb8aa3b, v103
	v_rcp_f32_e32 v96, v96
	v_exp_f32_e32 v109, v109
	v_add_f32_e32 v100, 1.0, v100
	v_rcp_f32_e32 v100, v100
	v_mul_f32_e32 v96, v101, v96
	v_add_f32_e32 v101, 1.0, v109
	v_rcp_f32_e32 v101, v101
	v_lshl_add_u64 v[112:113], s[14:15], 0, v[112:113]
	v_mul_f32_e32 v109, v97, v96
	v_mul_f32_e32 v96, v102, v100
	v_lshlrev_b64 v[112:113], 7, v[112:113]
	v_mul_f32_e32 v102, v98, v96
	v_mul_f32_e32 v96, v103, v101
	v_mul_f32_e32 v99, v99, v96
	v_lshl_add_u64 v[100:101], v[134:135], 0, v[112:113]
	v_cvt_pk_bf16_f32 v98, v108, v109
	v_cvt_pk_bf16_f32 v96, v104, v105
	v_cvt_pk_bf16_f32 v97, v106, v107
	v_cvt_pk_bf16_f32 v99, v102, v99
	global_store_dwordx4 v[100:101], v[96:99], off
	s_mov_b64 s[18:19], s[10:11]
	s_nop 0
	v_mul_f32_e32 v98, 0xbfb8aa3b, v92
	v_exp_f32_e32 v98, v98
	v_mul_f32_e32 v99, 0xbfb8aa3b, v93
	v_exp_f32_e32 v99, v99
	v_or_b32_e32 v96, 32, v144
	v_add_f32_e32 v98, 1.0, v98
	v_rcp_f32_e32 v98, v98
	v_add_f32_e32 v99, 1.0, v99
	v_rcp_f32_e32 v99, v99
	v_ashrrev_i32_e32 v97, 31, v96
	v_mul_f32_e32 v92, v92, v98
	v_mul_f32_e32 v88, v88, v92
	v_mul_f32_e32 v92, v93, v99
	v_mul_f32_e32 v93, 0xbfb8aa3b, v94
	v_exp_f32_e32 v93, v93
	v_mul_f32_e32 v98, 0xbfb8aa3b, v95
	v_exp_f32_e32 v98, v98
	v_mul_f32_e32 v89, v89, v92
	v_add_f32_e32 v92, 1.0, v93
	v_rcp_f32_e32 v92, v92
	v_add_f32_e32 v93, 1.0, v98
	v_mul_f32_e32 v98, 0xbfb8aa3b, v84
	v_rcp_f32_e32 v93, v93
	v_exp_f32_e32 v98, v98
	v_mul_f32_e32 v92, v94, v92
	v_mul_f32_e32 v90, v90, v92
	v_mul_f32_e32 v92, v95, v93
	v_add_f32_e32 v93, 1.0, v98
	v_rcp_f32_e32 v93, v93
	v_mul_f32_e32 v94, 0xbfb8aa3b, v85
	v_exp_f32_e32 v94, v94
	v_mul_f32_e32 v91, v91, v92
	v_mul_f32_e32 v84, v84, v93
	v_mul_f32_e32 v92, v80, v84
	v_mul_f32_e32 v84, 0xbfb8aa3b, v86
	v_add_f32_e32 v80, 1.0, v94
	v_exp_f32_e32 v84, v84
	v_mul_f32_e32 v93, 0xbfb8aa3b, v87
	v_rcp_f32_e32 v80, v80
	v_exp_f32_e32 v93, v93
	v_add_f32_e32 v84, 1.0, v84
	v_rcp_f32_e32 v84, v84
	v_mul_f32_e32 v80, v85, v80
	v_add_f32_e32 v85, 1.0, v93
	v_rcp_f32_e32 v85, v85
	v_lshl_add_u64 v[96:97], s[14:15], 0, v[96:97]
	v_mul_f32_e32 v93, v81, v80
	v_mul_f32_e32 v80, v86, v84
	v_lshlrev_b64 v[96:97], 7, v[96:97]
	v_mul_f32_e32 v86, v82, v80
	v_mul_f32_e32 v80, v87, v85
	v_mul_f32_e32 v83, v83, v80
	v_lshl_add_u64 v[84:85], v[134:135], 0, v[96:97]
	v_cvt_pk_bf16_f32 v82, v92, v93
	v_cvt_pk_bf16_f32 v80, v88, v89
	v_cvt_pk_bf16_f32 v81, v90, v91
	v_cvt_pk_bf16_f32 v83, v86, v83
	global_store_dwordx4 v[84:85], v[80:83], off
	s_nop 1
	v_mul_f32_e32 v82, 0xbfb8aa3b, v76
	v_exp_f32_e32 v82, v82
	v_mul_f32_e32 v83, 0xbfb8aa3b, v77
	v_exp_f32_e32 v83, v83
	v_or_b32_e32 v80, 48, v144
	v_add_f32_e32 v82, 1.0, v82
	v_rcp_f32_e32 v82, v82
	v_add_f32_e32 v83, 1.0, v83
	v_rcp_f32_e32 v83, v83
	v_ashrrev_i32_e32 v81, 31, v80
	v_mul_f32_e32 v76, v76, v82
	v_mul_f32_e32 v72, v72, v76
	v_mul_f32_e32 v76, v77, v83
	v_mul_f32_e32 v77, 0xbfb8aa3b, v78
	v_exp_f32_e32 v77, v77
	v_mul_f32_e32 v82, 0xbfb8aa3b, v79
	v_exp_f32_e32 v82, v82
	v_mul_f32_e32 v73, v73, v76
	v_add_f32_e32 v76, 1.0, v77
	v_rcp_f32_e32 v76, v76
	v_add_f32_e32 v77, 1.0, v82
	v_mul_f32_e32 v82, 0xbfb8aa3b, v68
	v_rcp_f32_e32 v77, v77
	v_exp_f32_e32 v82, v82
	v_mul_f32_e32 v76, v78, v76
	v_mul_f32_e32 v74, v74, v76
	v_mul_f32_e32 v76, v79, v77
	v_add_f32_e32 v77, 1.0, v82
	v_rcp_f32_e32 v77, v77
	v_mul_f32_e32 v78, 0xbfb8aa3b, v69
	v_exp_f32_e32 v78, v78
	v_mul_f32_e32 v75, v75, v76
	v_mul_f32_e32 v68, v68, v77
	v_mul_f32_e32 v76, v64, v68
	v_mul_f32_e32 v68, 0xbfb8aa3b, v70
	v_add_f32_e32 v64, 1.0, v78
	v_exp_f32_e32 v68, v68
	v_mul_f32_e32 v77, 0xbfb8aa3b, v71
	v_rcp_f32_e32 v64, v64
	v_exp_f32_e32 v77, v77
	v_add_f32_e32 v68, 1.0, v68
	v_rcp_f32_e32 v68, v68
	v_mul_f32_e32 v64, v69, v64
	v_add_f32_e32 v69, 1.0, v77
	v_rcp_f32_e32 v69, v69
	v_lshl_add_u64 v[80:81], s[14:15], 0, v[80:81]
	v_mul_f32_e32 v77, v65, v64
	v_mul_f32_e32 v64, v70, v68
	v_lshlrev_b64 v[80:81], 7, v[80:81]
	v_mul_f32_e32 v70, v66, v64
	v_mul_f32_e32 v64, v71, v69
	v_mul_f32_e32 v67, v67, v64
	v_lshl_add_u64 v[68:69], v[134:135], 0, v[80:81]
	v_cvt_pk_bf16_f32 v66, v76, v77
	v_cvt_pk_bf16_f32 v64, v72, v73
	v_cvt_pk_bf16_f32 v65, v74, v75
	v_cvt_pk_bf16_f32 v67, v70, v67
	global_store_dwordx4 v[68:69], v[64:67], off
	s_nop 1
	v_mul_f32_e32 v66, 0xbfb8aa3b, v60
	v_exp_f32_e32 v66, v66
; __device__ __forceinline__ unsigned pk_bf16(float lo, float hi) { unsigned r; asm("v_cvt_pk_bf16_f32 %0, %1, %2" : "=v"(r) : "v"(lo), "v"(hi)); return r; }
; __device__ __forceinline__ size_t blk_off(int row, int col, int nrows) { return ((size_t)(col >> 6) * nrows + row) * 64 + (col & 63); }
; __device__ __forceinline__ float sigmoidf_fast(float v) { return __builtin_amdgcn_rcpf(1.0f + __expf(-v)); }
; #define PG8_WAIT_V(n) asm volatile("s_waitcnt vmcnt(" #n ")" ::: "memory")
; #define PG8_BAR __builtin_amdgcn_s_barrier()
;     __device__ __forceinline__ void operator()(const f32x4 (&acc)[2][2][4][2], const Unit& u, int wr, int wc, int fr, int fq) const {
;     ...
;         for (int ai = 0; ai < 2; ++ai)
; #pragma unroll
;             for (int m = 0; m < 4; ++m) { bf16_t* rowp = O + blk_off(row0 + ai * HALF + m * 16, col0, nrows);
;                 float v[8];
; #pragma unroll
;                 for (int bj = 0; bj < 2; ++bj)
; #pragma unroll
;                     for (int j = 0; j < 4; ++j) { const float g = acc[ai][bj][m][0][j], up = acc[ai][bj][m][1][j]; v[bj * 4 + j] = g * sigmoidf_fast(g) * up; }
;                 u32x4 w; w.x = pk_bf16(v[0], v[1]); w.y = pk_bf16(v[2], v[3]); w.z = pk_bf16(v[4], v[5]); w.w = pk_bf16(v[6], v[7]);
;                 *(u32x4*)rowp = w; }
; template <class Epi>
; __device__ __forceinline__ void gemm_phase(LAS unsigned char* lds, const Gemm g, const StaticOrder& S, const Epi& E) {
;     ...
;         if (!has_next) break;
; #pragma unroll
;         for (int a = 0; a < 2; ++a)
; #pragma unroll
;             for (int b = 0; b < 2; ++b)
; #pragma unroll
;                 for (int m = 0; m < 4; ++m)
; #pragma unroll
;                     for (int n = 0; n < 2; ++n) acc[a][b][m][n] = (f32x4){0.f, 0.f, 0.f, 0.f};
;         cur = nxt; cA = nA; cB = nB; ++ui;
;     }
;     PG8_WAIT_V(0);
;     if (wr == 0) PG8_BAR;
	v_mul_f32_e32 v67, 0xbfb8aa3b, v61
	v_exp_f32_e32 v67, v67
	v_add_u32_e32 v64, 0x80, v144
	v_add_f32_e32 v66, 1.0, v66
	v_rcp_f32_e32 v66, v66
	v_add_f32_e32 v67, 1.0, v67
	v_rcp_f32_e32 v67, v67
	v_ashrrev_i32_e32 v65, 31, v64
	v_mul_f32_e32 v60, v60, v66
	v_mul_f32_e32 v56, v56, v60
	v_mul_f32_e32 v60, v61, v67
	v_mul_f32_e32 v61, 0xbfb8aa3b, v62
	v_exp_f32_e32 v61, v61
	v_mul_f32_e32 v66, 0xbfb8aa3b, v63
	v_exp_f32_e32 v66, v66
	v_mul_f32_e32 v57, v57, v60
	v_add_f32_e32 v60, 1.0, v61
	v_rcp_f32_e32 v60, v60
	v_add_f32_e32 v61, 1.0, v66
	v_mul_f32_e32 v66, 0xbfb8aa3b, v52
	v_rcp_f32_e32 v61, v61
	v_exp_f32_e32 v66, v66
	v_mul_f32_e32 v60, v62, v60
	v_mul_f32_e32 v58, v58, v60
	v_mul_f32_e32 v60, v63, v61
	v_add_f32_e32 v61, 1.0, v66
	v_rcp_f32_e32 v61, v61
	v_mul_f32_e32 v62, 0xbfb8aa3b, v53
	v_exp_f32_e32 v62, v62
	v_mul_f32_e32 v59, v59, v60
	v_mul_f32_e32 v52, v52, v61
	v_mul_f32_e32 v60, v48, v52
	v_mul_f32_e32 v52, 0xbfb8aa3b, v54
	v_add_f32_e32 v48, 1.0, v62
	v_exp_f32_e32 v52, v52
	v_mul_f32_e32 v61, 0xbfb8aa3b, v55
	v_rcp_f32_e32 v48, v48
	v_exp_f32_e32 v61, v61
	v_add_f32_e32 v52, 1.0, v52
	v_rcp_f32_e32 v52, v52
	v_mul_f32_e32 v48, v53, v48
	v_add_f32_e32 v53, 1.0, v61
	v_rcp_f32_e32 v53, v53
	v_lshl_add_u64 v[64:65], s[14:15], 0, v[64:65]
	v_mul_f32_e32 v61, v49, v48
	v_mul_f32_e32 v48, v54, v52
	v_lshlrev_b64 v[64:65], 7, v[64:65]
	v_mul_f32_e32 v54, v50, v48
	v_mul_f32_e32 v48, v55, v53
	v_mul_f32_e32 v51, v51, v48
	v_lshl_add_u64 v[52:53], v[134:135], 0, v[64:65]
	v_cvt_pk_bf16_f32 v50, v60, v61
	v_cvt_pk_bf16_f32 v48, v56, v57
	v_cvt_pk_bf16_f32 v49, v58, v59
	v_cvt_pk_bf16_f32 v51, v54, v51
	global_store_dwordx4 v[52:53], v[48:51], off
	s_nop 1
	v_mul_f32_e32 v50, 0xbfb8aa3b, v44
	v_exp_f32_e32 v50, v50
	v_mul_f32_e32 v51, 0xbfb8aa3b, v45
	v_exp_f32_e32 v51, v51
	v_add_u32_e32 v48, 0x90, v144
	v_add_f32_e32 v50, 1.0, v50
	v_rcp_f32_e32 v50, v50
	v_add_f32_e32 v51, 1.0, v51
	v_rcp_f32_e32 v51, v51
	v_ashrrev_i32_e32 v49, 31, v48
	v_mul_f32_e32 v44, v44, v50
	v_mul_f32_e32 v40, v40, v44
	v_mul_f32_e32 v44, v45, v51
	v_mul_f32_e32 v45, 0xbfb8aa3b, v46
	v_exp_f32_e32 v45, v45
	v_mul_f32_e32 v50, 0xbfb8aa3b, v47
	v_exp_f32_e32 v50, v50
	v_mul_f32_e32 v41, v41, v44
	v_add_f32_e32 v44, 1.0, v45
	v_rcp_f32_e32 v44, v44
	v_add_f32_e32 v45, 1.0, v50
	v_mul_f32_e32 v50, 0xbfb8aa3b, v36
	v_rcp_f32_e32 v45, v45
	v_exp_f32_e32 v50, v50
	v_mul_f32_e32 v44, v46, v44
	v_mul_f32_e32 v42, v42, v44
	v_mul_f32_e32 v44, v47, v45
	v_add_f32_e32 v45, 1.0, v50
	v_rcp_f32_e32 v45, v45
	v_mul_f32_e32 v46, 0xbfb8aa3b, v37
	v_exp_f32_e32 v46, v46
	v_mul_f32_e32 v43, v43, v44
	v_mul_f32_e32 v36, v36, v45
	v_mul_f32_e32 v44, v32, v36
	v_mul_f32_e32 v36, 0xbfb8aa3b, v38
	v_add_f32_e32 v32, 1.0, v46
	v_exp_f32_e32 v36, v36
	v_mul_f32_e32 v45, 0xbfb8aa3b, v39
	v_rcp_f32_e32 v32, v32
	v_exp_f32_e32 v45, v45
	v_add_f32_e32 v36, 1.0, v36
	v_rcp_f32_e32 v36, v36
	v_mul_f32_e32 v32, v37, v32
	v_add_f32_e32 v37, 1.0, v45
	v_rcp_f32_e32 v37, v37
	v_lshl_add_u64 v[48:49], s[14:15], 0, v[48:49]
	v_mul_f32_e32 v45, v33, v32
	v_mul_f32_e32 v32, v38, v36
	v_lshlrev_b64 v[48:49], 7, v[48:49]
	v_mul_f32_e32 v38, v34, v32
	v_mul_f32_e32 v32, v39, v37
	v_mul_f32_e32 v35, v35, v32
	v_lshl_add_u64 v[36:37], v[134:135], 0, v[48:49]
	v_cvt_pk_bf16_f32 v34, v44, v45
	v_cvt_pk_bf16_f32 v32, v40, v41
	v_cvt_pk_bf16_f32 v33, v42, v43
	v_cvt_pk_bf16_f32 v35, v38, v35
	global_store_dwordx4 v[36:37], v[32:35], off
	s_nop 1
	v_mul_f32_e32 v34, 0xbfb8aa3b, v28
	v_exp_f32_e32 v34, v34
	v_mul_f32_e32 v35, 0xbfb8aa3b, v29
	v_exp_f32_e32 v35, v35
	v_add_u32_e32 v32, 0xa0, v144
	v_add_f32_e32 v34, 1.0, v34
	v_rcp_f32_e32 v34, v34
	v_add_f32_e32 v35, 1.0, v35
	v_rcp_f32_e32 v35, v35
	v_ashrrev_i32_e32 v33, 31, v32
	v_mul_f32_e32 v28, v28, v34
	v_mul_f32_e32 v24, v24, v28
	v_mul_f32_e32 v28, v29, v35
	v_mul_f32_e32 v29, 0xbfb8aa3b, v30
	v_exp_f32_e32 v29, v29
	v_mul_f32_e32 v34, 0xbfb8aa3b, v31
	v_exp_f32_e32 v34, v34
	v_mul_f32_e32 v25, v25, v28
	v_add_f32_e32 v28, 1.0, v29
	v_rcp_f32_e32 v28, v28
	v_add_f32_e32 v29, 1.0, v34
	v_mul_f32_e32 v34, 0xbfb8aa3b, v20
	v_rcp_f32_e32 v29, v29
	v_exp_f32_e32 v34, v34
	v_mul_f32_e32 v28, v30, v28
	v_mul_f32_e32 v26, v26, v28
	v_mul_f32_e32 v28, v31, v29
	v_add_f32_e32 v29, 1.0, v34
	v_rcp_f32_e32 v29, v29
	v_mul_f32_e32 v30, 0xbfb8aa3b, v21
	v_exp_f32_e32 v30, v30
	v_mul_f32_e32 v27, v27, v28
	v_mul_f32_e32 v20, v20, v29
	v_mul_f32_e32 v28, v16, v20
	v_mul_f32_e32 v20, 0xbfb8aa3b, v22
	v_add_f32_e32 v16, 1.0, v30
	v_exp_f32_e32 v20, v20
	v_mul_f32_e32 v29, 0xbfb8aa3b, v23
	v_rcp_f32_e32 v16, v16
	v_exp_f32_e32 v29, v29
	v_add_f32_e32 v20, 1.0, v20
	v_rcp_f32_e32 v20, v20
	v_mul_f32_e32 v16, v21, v16
	v_add_f32_e32 v21, 1.0, v29
	v_rcp_f32_e32 v21, v21
	v_lshl_add_u64 v[32:33], s[14:15], 0, v[32:33]
	v_mul_f32_e32 v29, v17, v16
	v_mul_f32_e32 v16, v22, v20
	v_lshlrev_b64 v[32:33], 7, v[32:33]
	v_mul_f32_e32 v22, v18, v16
	v_mul_f32_e32 v16, v23, v21
	v_mul_f32_e32 v19, v19, v16
	v_lshl_add_u64 v[20:21], v[134:135], 0, v[32:33]
	v_cvt_pk_bf16_f32 v18, v28, v29
	v_cvt_pk_bf16_f32 v16, v24, v25
	v_cvt_pk_bf16_f32 v17, v26, v27
	v_cvt_pk_bf16_f32 v19, v22, v19
	global_store_dwordx4 v[20:21], v[16:19], off
	s_nop 1
	v_mul_f32_e32 v18, 0xbfb8aa3b, v12
	v_exp_f32_e32 v18, v18
	v_mul_f32_e32 v19, 0xbfb8aa3b, v13
	v_exp_f32_e32 v19, v19
	v_add_u32_e32 v16, 0xb0, v144
	v_add_f32_e32 v18, 1.0, v18
	v_rcp_f32_e32 v18, v18
	v_add_f32_e32 v19, 1.0, v19
	v_rcp_f32_e32 v19, v19
	v_ashrrev_i32_e32 v17, 31, v16
	v_mul_f32_e32 v12, v12, v18
	v_mul_f32_e32 v8, v8, v12
	v_mul_f32_e32 v12, v13, v19
	v_mul_f32_e32 v13, 0xbfb8aa3b, v14
	v_exp_f32_e32 v13, v13
	v_mul_f32_e32 v18, 0xbfb8aa3b, v15
	v_exp_f32_e32 v18, v18
	v_mul_f32_e32 v9, v9, v12
	v_add_f32_e32 v12, 1.0, v13
	v_rcp_f32_e32 v12, v12
	v_add_f32_e32 v13, 1.0, v18
	v_mul_f32_e32 v18, 0xbfb8aa3b, v4
	v_rcp_f32_e32 v13, v13
	v_exp_f32_e32 v18, v18
	v_mul_f32_e32 v12, v14, v12
	v_mul_f32_e32 v10, v10, v12
	v_mul_f32_e32 v12, v15, v13
	v_add_f32_e32 v13, 1.0, v18
	v_rcp_f32_e32 v13, v13
	v_mul_f32_e32 v14, 0xbfb8aa3b, v5
	v_exp_f32_e32 v14, v14
	v_mul_f32_e32 v11, v11, v12
	v_mul_f32_e32 v4, v4, v13
	v_mul_f32_e32 v12, v0, v4
	v_mul_f32_e32 v4, 0xbfb8aa3b, v6
	v_add_f32_e32 v0, 1.0, v14
	v_exp_f32_e32 v4, v4
	v_mul_f32_e32 v13, 0xbfb8aa3b, v7
	v_rcp_f32_e32 v0, v0
	v_exp_f32_e32 v13, v13
	v_add_f32_e32 v4, 1.0, v4
	v_rcp_f32_e32 v4, v4
	v_mul_f32_e32 v0, v5, v0
	v_add_f32_e32 v5, 1.0, v13
	v_rcp_f32_e32 v5, v5
	v_lshl_add_u64 v[16:17], s[14:15], 0, v[16:17]
	v_mul_f32_e32 v13, v1, v0
	v_mul_f32_e32 v0, v6, v4
	v_lshlrev_b64 v[16:17], 7, v[16:17]
	v_mul_f32_e32 v6, v2, v0
	v_mul_f32_e32 v0, v7, v5
	v_mul_f32_e32 v3, v3, v0
	v_lshl_add_u64 v[4:5], v[134:135], 0, v[16:17]
	s_mov_b32 s15, s0
	s_mov_b32 s14, s8
	v_cvt_pk_bf16_f32 v0, v8, v9
	v_cvt_pk_bf16_f32 v1, v10, v11
	v_cvt_pk_bf16_f32 v2, v12, v13
	v_cvt_pk_bf16_f32 v3, v6, v3
	global_store_dwordx4 v[4:5], v[0:3], off
	s_cbranch_vccz .LBB0_882
	s_waitcnt vmcnt(0)
	s_cmpk_gt_u32 s24, 0xff
	s_cbranch_scc1 .LBB0_889
	s_barrier

; #define PG8_STAGE(bufoff, gbase, voff) do { _Pragma("unroll") for (int _i = 0; _i < 2; ++_i) \
;         __builtin_amdgcn_global_load_lds((const unsigned*)((const char*)(gbase) + (voff)[_i]), (LAS unsigned*)(lds + (bufoff) + ldsw + _i * 8192), 16, 0, 0); } while (0)
; #define PG8_LDA(dst, b, h) do { _Pragma("unroll") for (int m = 0; m < 4; ++m) _Pragma("unroll") for (int k = 0; k < 2; ++k) dst[m][k] = *(const LAS bf16x8*)(lds + PG8_SA(b, h) + aoff + m * 2048 + k * 1024); } while (0)
; #define PG8_LDB(dst, b, h) do { _Pragma("unroll") for (int n = 0; n < 2; ++n) _Pragma("unroll") for (int k = 0; k < 2; ++k) dst[n][k] = *(const LAS bf16x8*)(lds + PG8_SB(b, h) + boff + n * 2048 + k * 1024); } while (0)
; #define PG8_MMA(ai, bj, At, Bt) do { __builtin_amdgcn_s_setprio(1); _Pragma("unroll") for (int m = 0; m < 4; ++m) _Pragma("unroll") for (int n = 0; n < 2; ++n) _Pragma("unroll") for (int k = 0; k < 2; ++k) \
;         acc[ai][bj][m][n] = __builtin_amdgcn_mfma_f32_16x16x32_bf16(Bt[n][k], At[m][k], acc[ai][bj][m][n], 0, 0, 0); __builtin_amdgcn_s_setprio(0); } while (0)
; #define PG8_WAIT_V(n) asm volatile("s_waitcnt vmcnt(" #n ")" ::: "memory")
; #define PG8_WAIT_L(n) asm volatile("s_waitcnt lgkmcnt(" #n ")" ::: "memory")
; template <class Epi>
; __device__ __forceinline__ void gemm_phase(LAS unsigned char* lds, const Gemm g, const StaticOrder& S, const Epi& E) {
;     ...
;         for (int t = 0; t < nt; t += 2) {
;             const bool last = (t == nt - 2);
;             const char* a1 = cA + (size_t)(t + 1) * kstepA;
;             const char* a2 = last ? nA : cA + (size_t)(t + 2) * kstepA; const char* b2 = last ? nB : cB + (size_t)(t + 2) * kstepB;
;             const char* a3 = a2 + kstepA; const char* b3 = b2 + kstepB;
;             PG8_LDB(B0, 0, 0); PG8_SCHED; PG8_LDA(At, 0, 0); PG8_STAGE(PG8_SA(1, 1), a1 + hstep, voffA);
;             PG8_WAIT_L(8); PG8_BAR; PG8_WAIT_L(0); PG8_MMA(0, 0, At, B0); PG8_BAR; PG8_SCHED;
;             PG8_LDB(B1, 0, 1); PG8_STAGE(PG8_SB(0, 0), b2, voffB);
;             PG8_BAR; PG8_WAIT_L(0); PG8_MMA(0, 1, At, B1); PG8_BAR;
;             PG8_LDA(At, 0, 1); PG8_STAGE(PG8_SA(0, 0), a2, voffA);
;             PG8_BAR; PG8_WAIT_L(0); PG8_MMA(1, 0, At, B0); PG8_BAR; PG8_SCHED;
;             PG8_STAGE(PG8_SB(0, 1), b2 + hstep, voffB);
;             PG8_WAIT_V(6); PG8_BAR; PG8_MMA(1, 1, At, B1); PG8_BAR;
.LBB0_957:
	ds_read_b128 v[154:157], v151
	ds_read_b128 v[158:161], v151 offset:1024
	ds_read_b128 v[162:165], v151 offset:2048
	ds_read_b128 v[166:169], v151 offset:3072
	s_add_u32 s24, s22, 0x3fc000
	s_addc_u32 s25, s23, 0
	s_cmpk_eq_i32 s60, 0x54
	s_cselect_b32 s28, s56, s24
	s_cselect_b32 s29, s15, s25
	s_cselect_b32 s25, s13, s59
	s_cselect_b32 s24, s57, s58
	s_add_u32 s26, s28, 0x400000
	s_addc_u32 s27, s29, 0
	v_lshl_add_u64 v[146:147], s[22:23], 0, v[138:139]
	s_add_i32 m0, s21, 0xc000
	ds_read_b128 v[170:173], v152
	ds_read_b128 v[174:177], v152 offset:1024
	ds_read_b128 v[184:187], v152 offset:2048
	ds_read_b128 v[188:191], v152 offset:3072
	ds_read_b128 v[192:195], v152 offset:4096
	ds_read_b128 v[196:199], v152 offset:5120
	ds_read_b128 v[200:203], v152 offset:6144
	ds_read_b128 v[204:207], v152 offset:7168
	global_load_lds_dwordx4 v[146:147], off
	v_lshl_add_u64 v[146:147], s[22:23], 0, v[140:141]
	s_add_i32 m0, s21, 0xe000
	s_nop 0
	global_load_lds_dwordx4 v[146:147], off
	ds_read_b128 v[208:211], v153
	ds_read_b128 v[212:215], v153 offset:1024
	ds_read_b128 v[216:219], v153 offset:2048
	ds_read_b128 v[220:223], v153 offset:3072
	s_waitcnt lgkmcnt(0)
	s_waitcnt vmcnt(8)
	s_barrier
	s_nop 0
	v_mfma_f32_16x16x32_bf16 v[124:127], v[154:157], v[170:173], v[124:127]
	v_mfma_f32_16x16x32_bf16 v[120:123], v[162:165], v[170:173], v[120:123]
	v_mfma_f32_16x16x32_bf16 v[112:115], v[154:157], v[184:187], v[112:115]
	v_mfma_f32_16x16x32_bf16 v[104:107], v[162:165], v[184:187], v[104:107]
	v_mfma_f32_16x16x32_bf16 v[96:99], v[154:157], v[192:195], v[96:99]
	v_mfma_f32_16x16x32_bf16 v[88:91], v[162:165], v[192:195], v[88:91]
	v_mfma_f32_16x16x32_bf16 v[80:83], v[154:157], v[200:203], v[80:83]
	v_mfma_f32_16x16x32_bf16 v[72:75], v[162:165], v[200:203], v[72:75]
	v_mfma_f32_16x16x32_bf16 v[124:127], v[158:161], v[174:177], v[124:127]
	v_mfma_f32_16x16x32_bf16 v[120:123], v[166:169], v[174:177], v[120:123]
	v_mfma_f32_16x16x32_bf16 v[112:115], v[158:161], v[188:191], v[112:115]
	v_mfma_f32_16x16x32_bf16 v[104:107], v[166:169], v[188:191], v[104:107]
	v_mfma_f32_16x16x32_bf16 v[96:99], v[158:161], v[196:199], v[96:99]
	v_mfma_f32_16x16x32_bf16 v[88:91], v[166:169], v[196:199], v[88:91]
	v_mfma_f32_16x16x32_bf16 v[80:83], v[158:161], v[204:207], v[80:83]
	v_mfma_f32_16x16x32_bf16 v[72:75], v[166:169], v[204:207], v[72:75]
	v_mfma_f32_16x16x32_bf16 v[116:119], v[208:211], v[170:173], v[116:119]
	v_mfma_f32_16x16x32_bf16 v[108:111], v[216:219], v[170:173], v[108:111]
	v_mfma_f32_16x16x32_bf16 v[100:103], v[208:211], v[184:187], v[100:103]
	v_mfma_f32_16x16x32_bf16 v[92:95], v[216:219], v[184:187], v[92:95]
	v_mfma_f32_16x16x32_bf16 v[84:87], v[208:211], v[192:195], v[84:87]
	v_mfma_f32_16x16x32_bf16 v[76:79], v[216:219], v[192:195], v[76:79]
	v_mfma_f32_16x16x32_bf16 v[68:71], v[208:211], v[200:203], v[68:71]
	v_mfma_f32_16x16x32_bf16 v[64:67], v[216:219], v[200:203], v[64:67]
	v_mfma_f32_16x16x32_bf16 v[116:119], v[212:215], v[174:177], v[116:119]
	v_mfma_f32_16x16x32_bf16 v[108:111], v[220:223], v[174:177], v[108:111]
	v_mfma_f32_16x16x32_bf16 v[100:103], v[212:215], v[188:191], v[100:103]
	v_mfma_f32_16x16x32_bf16 v[92:95], v[220:223], v[188:191], v[92:95]
	v_mfma_f32_16x16x32_bf16 v[84:87], v[212:215], v[196:199], v[84:87]
	v_mfma_f32_16x16x32_bf16 v[76:79], v[220:223], v[196:199], v[76:79]
	v_mfma_f32_16x16x32_bf16 v[68:71], v[212:215], v[204:207], v[68:71]
	v_mfma_f32_16x16x32_bf16 v[64:67], v[220:223], v[204:207], v[64:67]
	s_nop 0
	s_barrier
	s_add_i32 s61, s45, s36
	v_lshl_add_u64 v[146:147], s[24:25], 0, v[132:133]
	s_mov_b32 m0, s61
	s_nop 0
	global_load_lds_dwordx4 v[146:147], off
	v_lshl_add_u64 v[146:147], s[24:25], 0, v[136:137]
	s_add_i32 m0, s61, 0x2000
	s_nop 0
	global_load_lds_dwordx4 v[146:147], off
	s_mov_b32 m0, s21
	v_lshl_add_u64 v[146:147], s[28:29], 0, v[130:131]
	ds_read_b128 v[170:173], v152 offset:16384
	ds_read_b128 v[174:177], v152 offset:17408
	ds_read_b128 v[184:187], v152 offset:18432
	ds_read_b128 v[188:191], v152 offset:19456
	ds_read_b128 v[192:195], v152 offset:20480
	ds_read_b128 v[196:199], v152 offset:21504
	ds_read_b128 v[200:203], v152 offset:22528
	ds_read_b128 v[204:207], v152 offset:23552
	global_load_lds_dwordx4 v[146:147], off
	v_lshl_add_u64 v[146:147], s[28:29], 0, v[134:135]
	s_mov_b32 m0, s37
	s_nop 0
	global_load_lds_dwordx4 v[146:147], off
	s_add_u32 s62, s24, 0x4000
	s_addc_u32 s63, s25, 0
	s_add_i32 s61, s48, s36
	v_lshl_add_u64 v[146:147], s[62:63], 0, v[132:133]
	s_mov_b32 m0, s61
	s_nop 0
	global_load_lds_dwordx4 v[146:147], off
	v_lshl_add_u64 v[146:147], s[62:63], 0, v[136:137]
	s_add_i32 m0, s61, 0x2000
	s_nop 0
	global_load_lds_dwordx4 v[146:147], off
	s_waitcnt lgkmcnt(0)
	s_waitcnt vmcnt(8)
	s_barrier
; #define PG8_STAGE(bufoff, gbase, voff) do { _Pragma("unroll") for (int _i = 0; _i < 2; ++_i) \
;         __builtin_amdgcn_global_load_lds((const unsigned*)((const char*)(gbase) + (voff)[_i]), (LAS unsigned*)(lds + (bufoff) + ldsw + _i * 8192), 16, 0, 0); } while (0)
; #define PG8_LDA(dst, b, h) do { _Pragma("unroll") for (int m = 0; m < 4; ++m) _Pragma("unroll") for (int k = 0; k < 2; ++k) dst[m][k] = *(const LAS bf16x8*)(lds + PG8_SA(b, h) + aoff + m * 2048 + k * 1024); } while (0)
; #define PG8_LDB(dst, b, h) do { _Pragma("unroll") for (int n = 0; n < 2; ++n) _Pragma("unroll") for (int k = 0; k < 2; ++k) dst[n][k] = *(const LAS bf16x8*)(lds + PG8_SB(b, h) + boff + n * 2048 + k * 1024); } while (0)
; #define PG8_MMA(ai, bj, At, Bt) do { __builtin_amdgcn_s_setprio(1); _Pragma("unroll") for (int m = 0; m < 4; ++m) _Pragma("unroll") for (int n = 0; n < 2; ++n) _Pragma("unroll") for (int k = 0; k < 2; ++k) \
;         acc[ai][bj][m][n] = __builtin_amdgcn_mfma_f32_16x16x32_bf16(Bt[n][k], At[m][k], acc[ai][bj][m][n], 0, 0, 0); __builtin_amdgcn_s_setprio(0); } while (0)
; #define PG8_WAIT_V(n) asm volatile("s_waitcnt vmcnt(" #n ")" ::: "memory")
; #define PG8_WAIT_L(n) asm volatile("s_waitcnt lgkmcnt(" #n ")" ::: "memory")
; #define PG8_BAR __builtin_amdgcn_s_barrier()
; #define PG8_SCHED __builtin_amdgcn_sched_barrier(0)
; template <class Epi>
; __device__ __forceinline__ void gemm_phase(LAS unsigned char* lds, const Gemm g, const StaticOrder& S, const Epi& E) {
;     ...
;             PG8_BAR; PG8_WAIT_L(0); PG8_MMA(1, 0, At, B0); PG8_BAR; PG8_SCHED;
;             PG8_STAGE(PG8_SB(0, 1), b2 + hstep, voffB);
;             PG8_WAIT_V(6); PG8_BAR; PG8_MMA(1, 1, At, B1); PG8_BAR;
;             PG8_LDB(B0, 1, 0); PG8_SCHED; PG8_LDA(At, 1, 0); PG8_STAGE(PG8_SA(0, 1), a2 + hstep, voffA);
;             PG8_WAIT_L(8); PG8_BAR; PG8_WAIT_L(0); PG8_MMA(0, 0, At, B0); PG8_BAR; PG8_SCHED;
;             PG8_LDB(B1, 1, 1); PG8_STAGE(PG8_SB(1, 0), b3, voffB);
;             PG8_BAR; PG8_WAIT_L(0); PG8_MMA(0, 1, At, B1); PG8_BAR;
	s_nop 0
	v_mfma_f32_16x16x32_bf16 v[60:63], v[154:157], v[170:173], v[60:63]
	v_mfma_f32_16x16x32_bf16 v[56:59], v[162:165], v[170:173], v[56:59]
	v_mfma_f32_16x16x32_bf16 v[52:55], v[154:157], v[184:187], v[52:55]
	v_mfma_f32_16x16x32_bf16 v[44:47], v[162:165], v[184:187], v[44:47]
	v_mfma_f32_16x16x32_bf16 v[36:39], v[154:157], v[192:195], v[36:39]
	v_mfma_f32_16x16x32_bf16 v[28:31], v[162:165], v[192:195], v[28:31]
	v_mfma_f32_16x16x32_bf16 v[20:23], v[154:157], v[200:203], v[20:23]
	v_mfma_f32_16x16x32_bf16 v[12:15], v[162:165], v[200:203], v[12:15]
	v_mfma_f32_16x16x32_bf16 v[60:63], v[158:161], v[174:177], v[60:63]
	v_mfma_f32_16x16x32_bf16 v[56:59], v[166:169], v[174:177], v[56:59]
	v_mfma_f32_16x16x32_bf16 v[52:55], v[158:161], v[188:191], v[52:55]
	v_mfma_f32_16x16x32_bf16 v[44:47], v[166:169], v[188:191], v[44:47]
	v_mfma_f32_16x16x32_bf16 v[36:39], v[158:161], v[196:199], v[36:39]
	v_mfma_f32_16x16x32_bf16 v[28:31], v[166:169], v[196:199], v[28:31]
	v_mfma_f32_16x16x32_bf16 v[20:23], v[158:161], v[204:207], v[20:23]
	v_mfma_f32_16x16x32_bf16 v[12:15], v[166:169], v[204:207], v[12:15]
	v_mfma_f32_16x16x32_bf16 v[48:51], v[208:211], v[170:173], v[48:51]
	v_mfma_f32_16x16x32_bf16 v[40:43], v[216:219], v[170:173], v[40:43]
	v_mfma_f32_16x16x32_bf16 v[32:35], v[208:211], v[184:187], v[32:35]
	v_mfma_f32_16x16x32_bf16 v[24:27], v[216:219], v[184:187], v[24:27]
	v_mfma_f32_16x16x32_bf16 v[16:19], v[208:211], v[192:195], v[16:19]
	v_mfma_f32_16x16x32_bf16 v[8:11], v[216:219], v[192:195], v[8:11]
	v_mfma_f32_16x16x32_bf16 v[4:7], v[208:211], v[200:203], v[4:7]
	v_mfma_f32_16x16x32_bf16 v[0:3], v[216:219], v[200:203], v[0:3]
	v_mfma_f32_16x16x32_bf16 v[48:51], v[212:215], v[174:177], v[48:51]
	v_mfma_f32_16x16x32_bf16 v[40:43], v[220:223], v[174:177], v[40:43]
	v_mfma_f32_16x16x32_bf16 v[32:35], v[212:215], v[188:191], v[32:35]
	v_mfma_f32_16x16x32_bf16 v[24:27], v[220:223], v[188:191], v[24:27]
	v_mfma_f32_16x16x32_bf16 v[16:19], v[212:215], v[196:199], v[16:19]
	v_mfma_f32_16x16x32_bf16 v[8:11], v[220:223], v[196:199], v[8:11]
	v_mfma_f32_16x16x32_bf16 v[4:7], v[212:215], v[204:207], v[4:7]
	v_mfma_f32_16x16x32_bf16 v[0:3], v[220:223], v[204:207], v[0:3]
	s_nop 0
	s_add_i32 s61, 0, 0x18000
	v_add_u32_e32 v146, s61, v149
	s_barrier
	ds_read_b128 v[154:157], v146
	ds_read_b128 v[158:161], v146 offset:1024
	ds_read_b128 v[162:165], v146 offset:2048
	ds_read_b128 v[166:169], v146 offset:3072
	s_add_u32 s28, s28, 0x4000
	s_addc_u32 s29, s29, 0
	s_mov_b32 m0, s38
	v_lshl_add_u64 v[146:147], s[28:29], 0, v[130:131]
	ds_read_b128 v[170:173], v152 offset:32768
	ds_read_b128 v[174:177], v152 offset:33792
	ds_read_b128 v[184:187], v152 offset:34816
	ds_read_b128 v[188:191], v152 offset:35840
	ds_read_b128 v[192:195], v152 offset:36864
	ds_read_b128 v[196:199], v152 offset:37888
	ds_read_b128 v[200:203], v152 offset:38912
	ds_read_b128 v[204:207], v152 offset:39936
	global_load_lds_dwordx4 v[146:147], off
	v_lshl_add_u64 v[146:147], s[28:29], 0, v[134:135]
	s_mov_b32 m0, s39
	s_nop 0
	global_load_lds_dwordx4 v[146:147], off
	v_add_u32_e32 v253, 0x1c000, v149
	ds_read_b128 v[208:211], v253
	ds_read_b128 v[212:215], v253 offset:1024
	ds_read_b128 v[216:219], v253 offset:2048
	ds_read_b128 v[220:223], v253 offset:3072
	s_waitcnt lgkmcnt(0)
	s_waitcnt vmcnt(8)
	s_barrier
	s_nop 0
	v_mfma_f32_16x16x32_bf16 v[124:127], v[154:157], v[170:173], v[124:127]
	v_mfma_f32_16x16x32_bf16 v[120:123], v[162:165], v[170:173], v[120:123]
	v_mfma_f32_16x16x32_bf16 v[112:115], v[154:157], v[184:187], v[112:115]
	v_mfma_f32_16x16x32_bf16 v[104:107], v[162:165], v[184:187], v[104:107]
	v_mfma_f32_16x16x32_bf16 v[96:99], v[154:157], v[192:195], v[96:99]
	v_mfma_f32_16x16x32_bf16 v[88:91], v[162:165], v[192:195], v[88:91]
	v_mfma_f32_16x16x32_bf16 v[80:83], v[154:157], v[200:203], v[80:83]
	v_mfma_f32_16x16x32_bf16 v[72:75], v[162:165], v[200:203], v[72:75]
	v_mfma_f32_16x16x32_bf16 v[124:127], v[158:161], v[174:177], v[124:127]
	v_mfma_f32_16x16x32_bf16 v[120:123], v[166:169], v[174:177], v[120:123]
	v_mfma_f32_16x16x32_bf16 v[112:115], v[158:161], v[188:191], v[112:115]
	v_mfma_f32_16x16x32_bf16 v[104:107], v[166:169], v[188:191], v[104:107]
	v_mfma_f32_16x16x32_bf16 v[96:99], v[158:161], v[196:199], v[96:99]
	v_mfma_f32_16x16x32_bf16 v[88:91], v[166:169], v[196:199], v[88:91]
	v_mfma_f32_16x16x32_bf16 v[80:83], v[158:161], v[204:207], v[80:83]
	v_mfma_f32_16x16x32_bf16 v[72:75], v[166:169], v[204:207], v[72:75]
	v_mfma_f32_16x16x32_bf16 v[116:119], v[208:211], v[170:173], v[116:119]
	v_mfma_f32_16x16x32_bf16 v[108:111], v[216:219], v[170:173], v[108:111]
	v_mfma_f32_16x16x32_bf16 v[100:103], v[208:211], v[184:187], v[100:103]
	v_mfma_f32_16x16x32_bf16 v[92:95], v[216:219], v[184:187], v[92:95]
	v_mfma_f32_16x16x32_bf16 v[84:87], v[208:211], v[192:195], v[84:87]
	v_mfma_f32_16x16x32_bf16 v[76:79], v[216:219], v[192:195], v[76:79]
	v_mfma_f32_16x16x32_bf16 v[68:71], v[208:211], v[200:203], v[68:71]
	v_mfma_f32_16x16x32_bf16 v[64:67], v[216:219], v[200:203], v[64:67]
	v_mfma_f32_16x16x32_bf16 v[116:119], v[212:215], v[174:177], v[116:119]
	v_mfma_f32_16x16x32_bf16 v[108:111], v[220:223], v[174:177], v[108:111]
	v_mfma_f32_16x16x32_bf16 v[100:103], v[212:215], v[188:191], v[100:103]
	v_mfma_f32_16x16x32_bf16 v[92:95], v[220:223], v[188:191], v[92:95]
	v_mfma_f32_16x16x32_bf16 v[84:87], v[212:215], v[196:199], v[84:87]
	v_mfma_f32_16x16x32_bf16 v[76:79], v[220:223], v[196:199], v[76:79]
	v_mfma_f32_16x16x32_bf16 v[68:71], v[212:215], v[204:207], v[68:71]
	v_mfma_f32_16x16x32_bf16 v[64:67], v[220:223], v[204:207], v[64:67]
	s_nop 0
	s_barrier
; #define PG8_STAGE(bufoff, gbase, voff) do { _Pragma("unroll") for (int _i = 0; _i < 2; ++_i) \
;         __builtin_amdgcn_global_load_lds((const unsigned*)((const char*)(gbase) + (voff)[_i]), (LAS unsigned*)(lds + (bufoff) + ldsw + _i * 8192), 16, 0, 0); } while (0)
; #define PG8_LDA(dst, b, h) do { _Pragma("unroll") for (int m = 0; m < 4; ++m) _Pragma("unroll") for (int k = 0; k < 2; ++k) dst[m][k] = *(const LAS bf16x8*)(lds + PG8_SA(b, h) + aoff + m * 2048 + k * 1024); } while (0)
; #define PG8_MMA(ai, bj, At, Bt) do { __builtin_amdgcn_s_setprio(1); _Pragma("unroll") for (int m = 0; m < 4; ++m) _Pragma("unroll") for (int n = 0; n < 2; ++n) _Pragma("unroll") for (int k = 0; k < 2; ++k) \
;         acc[ai][bj][m][n] = __builtin_amdgcn_mfma_f32_16x16x32_bf16(Bt[n][k], At[m][k], acc[ai][bj][m][n], 0, 0, 0); __builtin_amdgcn_s_setprio(0); } while (0)
; #define PG8_WAIT_V(n) asm volatile("s_waitcnt vmcnt(" #n ")" ::: "memory")
; #define PG8_WAIT_L(n) asm volatile("s_waitcnt lgkmcnt(" #n ")" ::: "memory")
; #define PG8_BAR __builtin_amdgcn_s_barrier()
; #define PG8_SCHED __builtin_amdgcn_sched_barrier(0)
; template <class Epi>
; __device__ __forceinline__ void gemm_phase(LAS unsigned char* lds, const Gemm g, const StaticOrder& S, const Epi& E) {
;     ...
;             PG8_LDA(At, 1, 1); PG8_STAGE(PG8_SA(1, 0), a3, voffA);
;             PG8_BAR; PG8_WAIT_L(0); PG8_MMA(1, 0, At, B0); PG8_BAR; PG8_SCHED;
;             PG8_STAGE(PG8_SB(1, 1), b3 + hstep, voffB);
;             PG8_WAIT_V(6); PG8_BAR; PG8_MMA(1, 1, At, B1); PG8_BAR;
;         }
	s_add_i32 s62, 0, 0x1c000
	s_add_u32 s28, s24, 0x40000
	v_add_u32_e32 v146, s62, v149
	s_addc_u32 s29, s25, 0
	s_add_i32 s61, s61, s36
	s_nop 0
	v_lshl_add_u64 v[146:147], s[28:29], 0, v[132:133]
	s_mov_b32 m0, s61
	s_nop 0
	global_load_lds_dwordx4 v[146:147], off
	v_lshl_add_u64 v[146:147], s[28:29], 0, v[136:137]
	s_add_i32 m0, s61, 0x2000
	s_nop 0
	global_load_lds_dwordx4 v[146:147], off
	s_mov_b32 m0, s41
	v_lshl_add_u64 v[146:147], s[26:27], 0, v[130:131]
	ds_read_b128 v[170:173], v152 offset:49152
	ds_read_b128 v[174:177], v152 offset:50176
	ds_read_b128 v[184:187], v152 offset:51200
	ds_read_b128 v[188:191], v152 offset:52224
	ds_read_b128 v[192:195], v152 offset:53248
	ds_read_b128 v[196:199], v152 offset:54272
	ds_read_b128 v[200:203], v152 offset:55296
	ds_read_b128 v[204:207], v152 offset:56320
	global_load_lds_dwordx4 v[146:147], off
	v_lshl_add_u64 v[146:147], s[26:27], 0, v[134:135]
	s_mov_b32 m0, s42
	s_nop 0
	global_load_lds_dwordx4 v[146:147], off
	s_add_u32 s24, s24, 0x44000
	s_addc_u32 s25, s25, 0
	s_add_i32 s26, s62, s36
	v_lshl_add_u64 v[146:147], s[24:25], 0, v[132:133]
	s_mov_b32 m0, s26
	s_nop 0
	global_load_lds_dwordx4 v[146:147], off
	v_lshl_add_u64 v[146:147], s[24:25], 0, v[136:137]
	s_add_i32 m0, s26, 0x2000
	s_nop 0
	global_load_lds_dwordx4 v[146:147], off
	s_waitcnt lgkmcnt(0)
	s_waitcnt vmcnt(8)
	s_barrier
	s_nop 0
	v_mfma_f32_16x16x32_bf16 v[60:63], v[154:157], v[170:173], v[60:63]
	v_mfma_f32_16x16x32_bf16 v[56:59], v[162:165], v[170:173], v[56:59]
	v_mfma_f32_16x16x32_bf16 v[52:55], v[154:157], v[184:187], v[52:55]
	v_mfma_f32_16x16x32_bf16 v[44:47], v[162:165], v[184:187], v[44:47]
	v_mfma_f32_16x16x32_bf16 v[36:39], v[154:157], v[192:195], v[36:39]
	v_mfma_f32_16x16x32_bf16 v[28:31], v[162:165], v[192:195], v[28:31]
	v_mfma_f32_16x16x32_bf16 v[20:23], v[154:157], v[200:203], v[20:23]
	v_mfma_f32_16x16x32_bf16 v[12:15], v[162:165], v[200:203], v[12:15]
	v_mfma_f32_16x16x32_bf16 v[60:63], v[158:161], v[174:177], v[60:63]
	v_mfma_f32_16x16x32_bf16 v[56:59], v[166:169], v[174:177], v[56:59]
	v_mfma_f32_16x16x32_bf16 v[52:55], v[158:161], v[188:191], v[52:55]
	v_mfma_f32_16x16x32_bf16 v[44:47], v[166:169], v[188:191], v[44:47]
	v_mfma_f32_16x16x32_bf16 v[36:39], v[158:161], v[196:199], v[36:39]
	v_mfma_f32_16x16x32_bf16 v[28:31], v[166:169], v[196:199], v[28:31]
	v_mfma_f32_16x16x32_bf16 v[20:23], v[158:161], v[204:207], v[20:23]
	v_mfma_f32_16x16x32_bf16 v[12:15], v[166:169], v[204:207], v[12:15]
	v_mfma_f32_16x16x32_bf16 v[48:51], v[208:211], v[170:173], v[48:51]
	v_mfma_f32_16x16x32_bf16 v[40:43], v[216:219], v[170:173], v[40:43]
	v_mfma_f32_16x16x32_bf16 v[32:35], v[208:211], v[184:187], v[32:35]
	v_mfma_f32_16x16x32_bf16 v[24:27], v[216:219], v[184:187], v[24:27]
	v_mfma_f32_16x16x32_bf16 v[16:19], v[208:211], v[192:195], v[16:19]
	v_mfma_f32_16x16x32_bf16 v[8:11], v[216:219], v[192:195], v[8:11]
	v_mfma_f32_16x16x32_bf16 v[4:7], v[208:211], v[200:203], v[4:7]
	v_mfma_f32_16x16x32_bf16 v[0:3], v[216:219], v[200:203], v[0:3]
	v_mfma_f32_16x16x32_bf16 v[48:51], v[212:215], v[174:177], v[48:51]
	v_mfma_f32_16x16x32_bf16 v[40:43], v[220:223], v[174:177], v[40:43]
	v_mfma_f32_16x16x32_bf16 v[32:35], v[212:215], v[188:191], v[32:35]
	v_mfma_f32_16x16x32_bf16 v[24:27], v[220:223], v[188:191], v[24:27]
	v_mfma_f32_16x16x32_bf16 v[16:19], v[212:215], v[196:199], v[16:19]
	v_mfma_f32_16x16x32_bf16 v[8:11], v[220:223], v[196:199], v[8:11]
	v_mfma_f32_16x16x32_bf16 v[4:7], v[212:215], v[204:207], v[4:7]
	v_mfma_f32_16x16x32_bf16 v[0:3], v[220:223], v[204:207], v[0:3]
	s_nop 0
	s_add_i32 s60, s60, 2
	s_add_u32 s58, s58, 0x80000
	s_addc_u32 s59, s59, 0
	s_add_u32 s22, s22, 0x800000
	s_addc_u32 s23, s23, 0
	s_cmpk_gt_u32 s60, 0x55
	s_barrier
	s_cbranch_scc0 .LBB0_957
; __device__ __forceinline__ unsigned pk_bf16(float lo, float hi) { unsigned r; asm("v_cvt_pk_bf16_f32 %0, %1, %2" : "=v"(r) : "v"(lo), "v"(hi)); return r; }
; #define PG8_WAIT_V(n) asm volatile("s_waitcnt vmcnt(" #n ")" ::: "memory")
; #define PG8_BAR __builtin_amdgcn_s_barrier()
;     __device__ __forceinline__ void operator()(const f32x4 (&acc)[2][2][4][2], const Unit& u, int wr, int wc, int fr, int fq) const {
;         const int row0 = u.pm * BM + wr * 64 + fr; const int col0 = u.pn * BM + wc * 32 + 8 * fq;
; #pragma unroll
;         for (int ai = 0; ai < 2; ++ai)
; #pragma unroll
;             for (int m = 0; m < 4; ++m) { bf16_t* rowp = O + (size_t)(row0 + ai * HALF + m * 16) * ldc + col0;
; #pragma unroll
;                 for (int bj = 0; bj < 2; ++bj) { const f32x4 v0 = acc[ai][bj][m][0], v1 = acc[ai][bj][m][1];
;                     u32x4 w; w.x = pk_bf16(v0[0], v0[1]); w.y = pk_bf16(v0[2], v0[3]); w.z = pk_bf16(v1[0], v1[1]); w.w = pk_bf16(v1[2], v1[3]);
;                     *(u32x4*)(rowp + bj * HALF) = w; } }
; template <class Epi>
; __device__ __forceinline__ void gemm_phase(LAS unsigned char* lds, const Gemm g, const StaticOrder& S, const Epi& E) {
;     ...
;         if (!has_next) break;
; #pragma unroll
;         for (int a = 0; a < 2; ++a)
; #pragma unroll
;             for (int b = 0; b < 2; ++b)
; #pragma unroll
;                 for (int m = 0; m < 4; ++m)
; #pragma unroll
;                     for (int n = 0; n < 2; ++n) acc[a][b][m][n] = (f32x4){0.f, 0.f, 0.f, 0.f};
;         cur = nxt; cA = nA; cB = nB; ++ui;
;     }
;     PG8_WAIT_V(0);
;     if (wr == 0) PG8_BAR;
;     PG8_BAR;
	v_lshl_add_u32 v154, s20, 8, v148
	v_lshl_or_b32 v146, s55, 8, v150
	v_ashrrev_i32_e32 v155, 31, v154
	v_ashrrev_i32_e32 v147, 31, v146
	v_lshlrev_b64 v[156:157], 12, v[154:155]
	v_lshl_add_u64 v[156:157], s[52:53], 0, v[156:157]
	v_lshlrev_b64 v[158:159], 1, v[146:147]
	v_lshl_add_u64 v[146:147], v[156:157], 0, v[158:159]
	v_cvt_pk_bf16_f32 v60, v60, v61
	v_cvt_pk_bf16_f32 v61, v62, v63
	v_cvt_pk_bf16_f32 v62, v56, v57
	v_add_co_u32_e32 v56, vcc, s49, v146
	v_cvt_pk_bf16_f32 v116, v116, v117
	v_cvt_pk_bf16_f32 v117, v118, v119
	v_cvt_pk_bf16_f32 v118, v108, v109
	v_or_b32_e32 v108, 16, v154
	s_nop 0
	v_addc_co_u32_e32 v57, vcc, 0, v147, vcc
	v_cvt_pk_bf16_f32 v48, v48, v49
	v_cvt_pk_bf16_f32 v49, v50, v51
	v_cvt_pk_bf16_f32 v51, v42, v43
	v_cvt_pk_bf16_f32 v42, v44, v45
	v_add_co_u32_e32 v44, vcc, s50, v146
	v_ashrrev_i32_e32 v109, 31, v108
	v_cvt_pk_bf16_f32 v100, v100, v101
	v_cvt_pk_bf16_f32 v101, v102, v103
	v_cvt_pk_bf16_f32 v102, v92, v93
	v_or_b32_e32 v92, 32, v154
	v_addc_co_u32_e32 v45, vcc, 0, v147, vcc
	v_lshlrev_b64 v[108:109], 12, v[108:109]
	v_ashrrev_i32_e32 v93, 31, v92
	v_cvt_pk_bf16_f32 v84, v84, v85
	v_cvt_pk_bf16_f32 v85, v86, v87
	v_cvt_pk_bf16_f32 v86, v76, v77
	v_or_b32_e32 v76, 48, v154
	v_cvt_pk_bf16_f32 v32, v32, v33
	v_cvt_pk_bf16_f32 v33, v34, v35
	v_cvt_pk_bf16_f32 v35, v26, v27
	v_cvt_pk_bf16_f32 v26, v28, v29
	v_add_co_u32_e32 v28, vcc, s51, v146
	v_lshl_add_u64 v[108:109], s[52:53], 0, v[108:109]
	v_lshlrev_b64 v[92:93], 12, v[92:93]
	v_ashrrev_i32_e32 v77, 31, v76
	v_cvt_pk_bf16_f32 v68, v68, v69
	v_cvt_pk_bf16_f32 v69, v70, v71
	v_cvt_pk_bf16_f32 v70, v64, v65
	v_lshl_add_u64 v[64:65], v[146:147], 0, s[0:1]
	v_addc_co_u32_e32 v29, vcc, 0, v147, vcc
	v_cvt_pk_bf16_f32 v119, v110, v111
	global_store_dwordx4 v[146:147], v[116:119], off offset:256
	v_lshl_add_u64 v[92:93], s[52:53], 0, v[92:93]
	v_lshlrev_b64 v[76:77], 12, v[76:77]
	v_lshl_add_u64 v[116:117], v[108:109], 0, v[158:159]
	v_cvt_pk_bf16_f32 v50, v40, v41
	global_store_dwordx4 v[64:65], v[48:51], off offset:256
	v_cvt_pk_bf16_f32 v16, v16, v17
	v_cvt_pk_bf16_f32 v17, v18, v19
	v_cvt_pk_bf16_f32 v19, v10, v11
	v_cvt_pk_bf16_f32 v10, v12, v13
	v_add_co_u32_e32 v12, vcc, s54, v146
	s_nop 0
	v_lshl_add_u64 v[48:49], v[146:147], 0, s[6:7]
	v_cvt_pk_bf16_f32 v103, v94, v95
	global_store_dwordx4 v[116:117], v[100:103], off offset:256
	v_lshl_add_u64 v[76:77], s[52:53], 0, v[76:77]
	v_cvt_pk_bf16_f32 v34, v24, v25
	global_store_dwordx4 v[48:49], v[32:35], off offset:256
	v_lshl_add_u64 v[100:101], v[92:93], 0, v[158:159]
	v_addc_co_u32_e32 v13, vcc, 0, v147, vcc
	v_lshl_add_u64 v[32:33], v[146:147], 0, s[8:9]
	v_cvt_pk_bf16_f32 v87, v78, v79
	global_store_dwordx4 v[100:101], v[84:87], off offset:256
	v_cvt_pk_bf16_f32 v18, v8, v9
	global_store_dwordx4 v[32:33], v[16:19], off offset:256
	s_and_b64 vcc, exec, s[4:5]
	v_lshl_add_u64 v[84:85], v[76:77], 0, v[158:159]
	v_lshl_add_u64 v[16:17], v[146:147], 0, s[10:11]
	s_mov_b32 s55, s12
	s_mov_b32 s20, s14
	s_mov_b64 s[22:23], s[18:19]
	s_mov_b64 s[24:25], s[16:17]
	v_cvt_pk_bf16_f32 v124, v124, v125
	v_cvt_pk_bf16_f32 v125, v126, v127
	v_cvt_pk_bf16_f32 v126, v120, v121
	v_cvt_pk_bf16_f32 v127, v122, v123
	global_store_dwordx4 v[146:147], v[124:127], off
	v_cvt_pk_bf16_f32 v108, v112, v113
	v_cvt_pk_bf16_f32 v109, v114, v115
	v_cvt_pk_bf16_f32 v110, v104, v105
	v_cvt_pk_bf16_f32 v111, v106, v107
	global_store_dwordx4 v[116:117], v[108:111], off
	v_cvt_pk_bf16_f32 v92, v96, v97
	v_cvt_pk_bf16_f32 v93, v98, v99
	v_cvt_pk_bf16_f32 v94, v88, v89
	v_cvt_pk_bf16_f32 v95, v90, v91
	global_store_dwordx4 v[100:101], v[92:95], off
	v_cvt_pk_bf16_f32 v76, v80, v81
	v_cvt_pk_bf16_f32 v77, v82, v83
	v_cvt_pk_bf16_f32 v78, v72, v73
	v_cvt_pk_bf16_f32 v79, v74, v75
	global_store_dwordx4 v[84:85], v[76:79], off
	v_cvt_pk_bf16_f32 v71, v66, v67
	global_store_dwordx4 v[84:85], v[68:71], off offset:256
	v_cvt_pk_bf16_f32 v63, v58, v59
	global_store_dwordx4 v[56:57], v[60:63], off
	v_cvt_pk_bf16_f32 v40, v52, v53
	v_cvt_pk_bf16_f32 v41, v54, v55
	v_cvt_pk_bf16_f32 v43, v46, v47
	global_store_dwordx4 v[44:45], v[40:43], off
	v_cvt_pk_bf16_f32 v24, v36, v37
	v_cvt_pk_bf16_f32 v25, v38, v39
	v_cvt_pk_bf16_f32 v27, v30, v31
	global_store_dwordx4 v[28:29], v[24:27], off
	v_cvt_pk_bf16_f32 v8, v20, v21
	v_cvt_pk_bf16_f32 v9, v22, v23
	v_cvt_pk_bf16_f32 v11, v14, v15
	global_store_dwordx4 v[12:13], v[8:11], off
	v_cvt_pk_bf16_f32 v4, v4, v5
	v_cvt_pk_bf16_f32 v5, v6, v7
	v_cvt_pk_bf16_f32 v6, v0, v1
	v_cvt_pk_bf16_f32 v7, v2, v3
	global_store_dwordx4 v[16:17], v[4:7], off offset:256
	s_cbranch_vccz .LBB0_950
	s_waitcnt vmcnt(0)
	s_cmpk_gt_u32 s30, 0xff
	s_cbranch_scc1 .LBB0_961
	s_barrier
